# hid (UP output, DOWN's A operand) also stored k-blocked [K/32][M][32] by the UP epilogue; DOWN K-loop A pieces now contiguous 1 KiB reads
# speedup vs baseline: 1.1037x; 1.0164x over previous
.LBB0_13:
	s_lshr_b32 s13, s12, 4
	s_and_b32 s13, s13, 24
	s_and_b32 s14, s12, 7
	s_or_b32 s13, s13, s14
	s_lshl_b32 s13, s13, 10
	v_mov_b32 v8, v198
	s_or_b32 s14, s13, s65
	v_ashrrev_i32_e32 v12, 2, v8
	v_add_u32_e32 v0, s14, v12
	v_ashrrev_i32_e32 v1, 31, v0
	v_readlane_b32 s16, v253, 21
	s_lshl_b32 s15, s12, 5
	v_lshlrev_b64 v[0:1], 11, v[0:1]
	v_readlane_b32 s17, v253, 22
	v_lshlrev_b32_e32 v2, 4, v8
	s_and_b32 s13, s15, 0xf00
	v_lshl_add_u64 v[0:1], s[16:17], 0, v[0:1]
	v_and_b32_e32 v152, 48, v2
	v_lshl_add_u64 v[14:15], v[0:1], 0, v[152:153]
	v_add_u32_e32 v0, s13, v12
	v_ashrrev_i32_e32 v1, 31, v0
	v_lshlrev_b64 v[0:1], 6, v[0:1]
	v_lshl_add_u64 v[0:1], s[4:5], 0, v[0:1]
	v_add_co_u32_e32 v54, vcc, s62, v14
	v_lshl_add_u64 v[0:1], v[0:1], 0, v[152:153]
	s_nop 0
	v_addc_co_u32_e32 v55, vcc, 0, v15, vcc
	s_lshl_b32 s16, s11, 11
	s_lshl_b32 s17, s12, 6
	s_and_b32 s18, s10, 7
	v_add_co_u32_e32 v2, vcc, s62, v0
	s_and_b32 s16, s16, 0x780000
	s_and_b32 s19, s17, 0x6000
	s_lshl_b32 s18, s18, 10
	v_lshrrev_b32_e32 v6, 2, v8
	v_addc_co_u32_e32 v3, vcc, 0, v1, vcc
	v_and_b32_e32 v6, 12, v6
	v_ashrrev_i32_e32 v13, 31, v12
	s_movk_i32 s17, 0x1230
	s_add_u32 s16, s7, s16
	v_add_co_u32_e32 v4, vcc, s33, v0
	v_lshrrev_b32_e64 v10, v6, s17
	v_lshlrev_b64 v[6:7], 11, v[12:13]
	s_addc_u32 s17, s8, 0
	s_or_b32 s18, s18, s19
	v_addc_co_u32_e32 v5, vcc, 0, v1, vcc
	v_and_b32_e32 v22, 3, v8
	v_xor_b32_e32 v8, v10, v8
	v_lshl_add_u64 v[156:157], s[16:17], 0, v[6:7]
	s_or_b32 s16, s18, s65
	v_add_co_u32_e32 v20, vcc, s72, v0
	v_lshlrev_b32_e32 v9, 6, v12
	v_lshlrev_b32_e32 v8, 4, v8
	v_add_u32_e32 v12, s16, v12
	v_addc_co_u32_e32 v21, vcc, 0, v1, vcc
	s_nop 0
	v_readfirstlane_b32 s26, v14
	v_readfirstlane_b32 s27, v15
	v_readfirstlane_b32 s28, v0
	v_readfirstlane_b32 s29, v1
	v_lshrrev_b32_e32 v250, 6, v198
	s_nop 0
	v_readfirstlane_b32 s24, v250
	s_lshl_b32 s24, s24, 10
	v_lshrrev_b32_e32 v250, 2, v200
	v_lshrrev_b32_e32 v251, 4, v200
	v_lshlrev_b32_e32 v251, 2, v251
	v_mov_b32_e32 v248, 0x1230
	v_lshrrev_b32_e32 v251, v251, v248
	v_xor_b32_e32 v251, v251, v200
	v_and_b32_e32 v251, 3, v251
	v_lshlrev_b32_e32 v251, 4, v251
	v_lshl_add_u32 v244, v250, 11, v251
	v_add_u32_e32 v245, 0x20000, v244
	v_add_u32_e32 v246, 0x40000, v244
	v_add_u32_e32 v247, 0x60000, v244
	v_lshl_add_u32 v156, v250, 6, v251
	v_add_u32_e32 v157, 0x1000, v156
	v_add_u32_e32 v158, 0x2000, v156
	v_add_u32_e32 v159, 0x3000, v156
	s_mov_b32 s25, 0
	s_add_u32 m0, s25, s24
	s_nop 0
	global_load_lds_dwordx4 v244, s[26:27]
	s_add_u32 m0, m0, 0x1000
	s_nop 0
	global_load_lds_dwordx4 v245, s[26:27]
	s_add_u32 m0, m0, 0x1000
	s_nop 0
	global_load_lds_dwordx4 v156, s[28:29]
	s_add_u32 m0, m0, 0x1000
	s_nop 0
	global_load_lds_dwordx4 v157, s[28:29]
	s_add_u32 m0, m0, 0x1000
	s_nop 0
	global_load_lds_dwordx4 v158, s[28:29]
	s_add_u32 m0, m0, 0x1000
	s_nop 0
	global_load_lds_dwordx4 v159, s[28:29]
	s_add_u32 s26, s26, 0x40
	s_addc_u32 s27, s27, 0
	s_add_u32 s28, s28, 0x40000
	s_addc_u32 s29, s29, 0
	s_add_u32 s25, s25, 24576
	s_cmp_eq_u32 s25, 73728
	s_cselect_b32 s25, 0, s25
	s_add_u32 m0, s25, s24
	s_nop 0
	global_load_lds_dwordx4 v244, s[26:27]
	s_add_u32 m0, m0, 0x1000
	s_nop 0
	global_load_lds_dwordx4 v245, s[26:27]
	s_add_u32 m0, m0, 0x1000
	s_nop 0
	global_load_lds_dwordx4 v156, s[28:29]
	s_add_u32 m0, m0, 0x1000
	s_nop 0
	global_load_lds_dwordx4 v157, s[28:29]
	s_add_u32 m0, m0, 0x1000
	s_nop 0
	global_load_lds_dwordx4 v158, s[28:29]
	s_add_u32 m0, m0, 0x1000
	s_nop 0
	global_load_lds_dwordx4 v159, s[28:29]
	s_add_u32 s26, s26, 0x40
	s_addc_u32 s27, s27, 0
	s_add_u32 s28, s28, 0x40000
	s_addc_u32 s29, s29, 0
	s_add_u32 s25, s25, 24576
	s_cmp_eq_u32 s25, 73728
	s_cselect_b32 s25, 0, s25
	s_add_u32 m0, s25, s24
	s_nop 0
	global_load_lds_dwordx4 v244, s[26:27]
	s_add_u32 m0, m0, 0x1000
	s_nop 0
	global_load_lds_dwordx4 v245, s[26:27]
	s_add_u32 m0, m0, 0x1000
	s_nop 0
	global_load_lds_dwordx4 v156, s[28:29]
	s_add_u32 m0, m0, 0x1000
	s_nop 0
	global_load_lds_dwordx4 v157, s[28:29]
	s_add_u32 m0, m0, 0x1000
	s_nop 0
	global_load_lds_dwordx4 v158, s[28:29]
	s_add_u32 m0, m0, 0x1000
	s_nop 0
	global_load_lds_dwordx4 v159, s[28:29]
	s_add_u32 s26, s26, 0x40
	s_addc_u32 s27, s27, 0
	s_add_u32 s28, s28, 0x40000
	s_addc_u32 s29, s29, 0
	s_add_u32 s25, s25, 24576
	s_cmp_eq_u32 s25, 73728
	s_cselect_b32 s25, 0, s25
	v_mov_b32_e32 v24, 0
	v_mov_b32_e32 v25, v24
	v_mov_b32_e32 v26, v24
	v_mov_b32_e32 v27, v24
	v_mov_b32_e32 v28, v24
	v_mov_b32_e32 v29, v24
	v_mov_b32_e32 v84, v24
	v_mov_b32_e32 v85, v24
	v_mov_b32_e32 v86, v24
	v_mov_b32_e32 v87, v24
	v_mov_b32_e32 v88, v24
	v_mov_b32_e32 v89, v24
	v_mov_b32_e32 v90, v24
	v_mov_b32_e32 v91, v24
	v_mov_b32_e32 v92, v24
	v_mov_b32_e32 v93, v24
	v_mov_b32_e32 v94, v24
	v_mov_b32_e32 v95, v24
	v_mov_b32_e32 v96, v24
	v_mov_b32_e32 v97, v24
	v_mov_b32_e32 v98, v24
	v_mov_b32_e32 v99, v24
	v_mov_b32_e32 v54, v24
	v_mov_b32_e32 v55, v24
	v_mov_b32_e32 v100, v24
	v_mov_b32_e32 v101, v24
	v_mov_b32_e32 v30, v24
	v_mov_b32_e32 v31, v24
	v_mov_b32_e32 v32, v24
	v_mov_b32_e32 v33, v24
	v_mov_b32_e32 v34, v24
	v_mov_b32_e32 v35, v24
	v_mov_b32_e32 v36, v24
	v_mov_b32_e32 v37, v24
	v_mov_b32_e32 v38, v24
	v_mov_b32_e32 v39, v24
	v_mov_b32_e32 v40, v24
	v_mov_b32_e32 v41, v24
	v_mov_b32_e32 v42, v24
	v_mov_b32_e32 v43, v24
	v_mov_b32_e32 v44, v24
	v_mov_b32_e32 v45, v24
	v_mov_b32_e32 v46, v24
	v_mov_b32_e32 v47, v24
	v_mov_b32_e32 v48, v24
	v_mov_b32_e32 v49, v24
	v_mov_b32_e32 v50, v24
	v_mov_b32_e32 v51, v24
	v_mov_b32_e32 v52, v24
	v_mov_b32_e32 v53, v24
	v_mov_b32_e32 v102, v24
	v_mov_b32_e32 v103, v24
	v_mov_b32_e32 v104, v24
	v_mov_b32_e32 v105, v24
	v_mov_b32_e32 v106, v24
	v_mov_b32_e32 v107, v24
	v_mov_b32_e32 v116, v24
	v_mov_b32_e32 v117, v24
	v_mov_b32_e32 v118, v24
	v_mov_b32_e32 v119, v24
	v_mov_b32_e32 v128, v24
	v_mov_b32_e32 v129, v24
	v_mov_b32_e32 v130, v24
	v_mov_b32_e32 v131, v24
	v_mov_b32_e32 v108, v24
	v_mov_b32_e32 v109, v24
	v_mov_b32_e32 v110, v24
	v_mov_b32_e32 v111, v24
	v_mov_b32_e32 v112, v24
	v_mov_b32_e32 v113, v24
	v_mov_b32_e32 v114, v24
	v_mov_b32_e32 v115, v24
	v_mov_b32_e32 v120, v24
	v_mov_b32_e32 v121, v24
	v_mov_b32_e32 v122, v24
	v_mov_b32_e32 v123, v24
	v_mov_b32_e32 v124, v24
	v_mov_b32_e32 v125, v24
	v_mov_b32_e32 v126, v24
	v_mov_b32_e32 v127, v24
	v_mov_b32_e32 v64, v24
	v_mov_b32_e32 v65, v24
	v_mov_b32_e32 v66, v24
	v_mov_b32_e32 v67, v24
	v_mov_b32_e32 v68, v24
	v_mov_b32_e32 v69, v24
	v_mov_b32_e32 v70, v24
	v_mov_b32_e32 v71, v24
	v_mov_b32_e32 v80, v24
	v_mov_b32_e32 v81, v24
	v_mov_b32_e32 v82, v24
	v_mov_b32_e32 v83, v24
	v_mov_b32_e32 v56, v24
	v_mov_b32_e32 v57, v24
	v_mov_b32_e32 v58, v24
	v_mov_b32_e32 v59, v24
	v_mov_b32_e32 v132, v24
	v_mov_b32_e32 v133, v24
	v_mov_b32_e32 v134, v24
	v_mov_b32_e32 v135, v24
	v_mov_b32_e32 v136, v24
	v_mov_b32_e32 v137, v24
	v_mov_b32_e32 v138, v24
	v_mov_b32_e32 v139, v24
	v_mov_b32_e32 v140, v24
	v_mov_b32_e32 v141, v24
	v_mov_b32_e32 v142, v24
	v_mov_b32_e32 v143, v24
	v_mov_b32_e32 v144, v24
	v_mov_b32_e32 v145, v24
	v_mov_b32_e32 v146, v24
	v_mov_b32_e32 v147, v24
	v_mov_b32_e32 v76, v24
	v_mov_b32_e32 v77, v24
	v_mov_b32_e32 v78, v24
	v_mov_b32_e32 v79, v24
	v_mov_b32_e32 v72, v24
	v_mov_b32_e32 v73, v24
	v_mov_b32_e32 v74, v24
	v_mov_b32_e32 v75, v24
	v_mov_b32_e32 v60, v24
	v_mov_b32_e32 v61, v24
	v_mov_b32_e32 v62, v24
	v_mov_b32_e32 v63, v24
	v_mov_b32_e32 v148, v24
	v_mov_b32_e32 v149, v24
	v_mov_b32_e32 v150, v24
	v_mov_b32_e32 v151, v24
	s_waitcnt vmcnt(12)
	s_barrier
	s_mov_b32 s30, 0
	v_add_u32_e32 v248, s30, v155
	v_add_u32_e32 v249, s30, v160
	ds_read_b128 v[186:189], v248
	ds_read_b128 v[212:215], v249 offset:8192
	ds_read_b128 v[190:193], v248 offset:1024
	ds_read_b128 v[216:219], v249 offset:9216
	ds_read_b128 v[194:197], v248 offset:2048
	ds_read_b128 v[220:223], v249 offset:10240
	ds_read_b128 v[208:211], v248 offset:3072
	ds_read_b128 v[224:227], v249 offset:11264
	ds_read_b128 v[228:231], v249 offset:12288
	ds_read_b128 v[232:235], v249 offset:13312
	ds_read_b128 v[236:239], v249 offset:14336
	ds_read_b128 v[240:243], v249 offset:15360
	s_add_u32 s30, s30, 24576
	s_cmp_eq_u32 s30, 73728
	s_cselect_b32 s30, 0, s30
	s_waitcnt vmcnt(6)
	s_waitcnt lgkmcnt(0)
	s_barrier
	s_mov_b32 s31, 14
.Lgm0_loop:
	v_add_u32_e32 v248, s30, v155
	v_add_u32_e32 v249, s30, v160
	v_mfma_f32_16x16x32_bf16 v[128:131], v[212:215], v[186:189], v[128:131]
	ds_read_b128 v[0:3], v248
	v_mfma_f32_16x16x32_bf16 v[96:99], v[212:215], v[190:193], v[96:99]
	ds_read_b128 v[16:19], v249 offset:8192
	v_mfma_f32_16x16x32_bf16 v[108:111], v[212:215], v[194:197], v[108:111]
	ds_read_b128 v[4:7], v248 offset:1024
	v_mfma_f32_16x16x32_bf16 v[132:135], v[212:215], v[208:211], v[132:135]
	ds_read_b128 v[20:23], v249 offset:9216
	v_mfma_f32_16x16x32_bf16 v[116:119], v[216:219], v[186:189], v[116:119]
	ds_read_b128 v[8:11], v248 offset:2048
	v_mfma_f32_16x16x32_bf16 v[92:95], v[216:219], v[190:193], v[92:95]
	ds_read_b128 v[162:165], v249 offset:10240
	v_mfma_f32_16x16x32_bf16 v[112:115], v[216:219], v[194:197], v[112:115]
	ds_read_b128 v[12:15], v248 offset:3072
	v_mfma_f32_16x16x32_bf16 v[136:139], v[216:219], v[208:211], v[136:139]
	ds_read_b128 v[166:169], v249 offset:11264
	v_mfma_f32_16x16x32_bf16 v[104:107], v[220:223], v[186:189], v[104:107]
	ds_read_b128 v[170:173], v249 offset:12288
	v_mfma_f32_16x16x32_bf16 v[88:91], v[220:223], v[190:193], v[88:91]
	ds_read_b128 v[174:177], v249 offset:13312
	v_mfma_f32_16x16x32_bf16 v[120:123], v[220:223], v[194:197], v[120:123]
	ds_read_b128 v[178:181], v249 offset:14336
	v_mfma_f32_16x16x32_bf16 v[140:143], v[220:223], v[208:211], v[140:143]
	ds_read_b128 v[182:185], v249 offset:15360
	s_add_u32 m0, s25, s24
	v_mfma_f32_16x16x32_bf16 v[100:103], v[224:227], v[186:189], v[100:103]
	global_load_lds_dwordx4 v244, s[26:27]
	v_mfma_f32_16x16x32_bf16 v[84:87], v[224:227], v[190:193], v[84:87]
	v_mfma_f32_16x16x32_bf16 v[124:127], v[224:227], v[194:197], v[124:127]
	s_add_u32 m0, m0, 0x1000
	v_mfma_f32_16x16x32_bf16 v[144:147], v[224:227], v[208:211], v[144:147]
	global_load_lds_dwordx4 v245, s[26:27]
	v_mfma_f32_16x16x32_bf16 v[52:55], v[228:231], v[186:189], v[52:55]
	v_mfma_f32_16x16x32_bf16 v[36:39], v[228:231], v[190:193], v[36:39]
	s_add_u32 m0, m0, 0x1000
	v_mfma_f32_16x16x32_bf16 v[64:67], v[228:231], v[194:197], v[64:67]
	global_load_lds_dwordx4 v156, s[28:29]
	v_mfma_f32_16x16x32_bf16 v[76:79], v[228:231], v[208:211], v[76:79]
	v_mfma_f32_16x16x32_bf16 v[48:51], v[232:235], v[186:189], v[48:51]
	s_add_u32 m0, m0, 0x1000
	v_mfma_f32_16x16x32_bf16 v[32:35], v[232:235], v[190:193], v[32:35]
	global_load_lds_dwordx4 v157, s[28:29]
	v_mfma_f32_16x16x32_bf16 v[68:71], v[232:235], v[194:197], v[68:71]
	v_mfma_f32_16x16x32_bf16 v[72:75], v[232:235], v[208:211], v[72:75]
	s_add_u32 m0, m0, 0x1000
	v_mfma_f32_16x16x32_bf16 v[44:47], v[236:239], v[186:189], v[44:47]
	global_load_lds_dwordx4 v158, s[28:29]
	v_mfma_f32_16x16x32_bf16 v[28:31], v[236:239], v[190:193], v[28:31]
	v_mfma_f32_16x16x32_bf16 v[80:83], v[236:239], v[194:197], v[80:83]
	s_add_u32 m0, m0, 0x1000
	v_mfma_f32_16x16x32_bf16 v[60:63], v[236:239], v[208:211], v[60:63]
	global_load_lds_dwordx4 v159, s[28:29]
	v_mfma_f32_16x16x32_bf16 v[40:43], v[240:243], v[186:189], v[40:43]
	v_mfma_f32_16x16x32_bf16 v[24:27], v[240:243], v[190:193], v[24:27]
	v_mfma_f32_16x16x32_bf16 v[56:59], v[240:243], v[194:197], v[56:59]
	v_mfma_f32_16x16x32_bf16 v[148:151], v[240:243], v[208:211], v[148:151]
	s_add_u32 s26, s26, 0x40
	s_addc_u32 s27, s27, 0
	s_add_u32 s28, s28, 0x40000
	s_addc_u32 s29, s29, 0
	s_add_u32 s25, s25, 24576
	s_cmp_eq_u32 s25, 73728
	s_cselect_b32 s25, 0, s25
	s_add_u32 s30, s30, 24576
	s_cmp_eq_u32 s30, 73728
	s_cselect_b32 s30, 0, s30
	s_waitcnt vmcnt(6)
	s_waitcnt lgkmcnt(0)
	s_barrier
	v_add_u32_e32 v248, s30, v155
	v_add_u32_e32 v249, s30, v160
	v_mfma_f32_16x16x32_bf16 v[128:131], v[16:19], v[0:3], v[128:131]
	ds_read_b128 v[186:189], v248
	v_mfma_f32_16x16x32_bf16 v[96:99], v[16:19], v[4:7], v[96:99]
	ds_read_b128 v[212:215], v249 offset:8192
	v_mfma_f32_16x16x32_bf16 v[108:111], v[16:19], v[8:11], v[108:111]
	ds_read_b128 v[190:193], v248 offset:1024
	v_mfma_f32_16x16x32_bf16 v[132:135], v[16:19], v[12:15], v[132:135]
	ds_read_b128 v[216:219], v249 offset:9216
	v_mfma_f32_16x16x32_bf16 v[116:119], v[20:23], v[0:3], v[116:119]
	ds_read_b128 v[194:197], v248 offset:2048
	v_mfma_f32_16x16x32_bf16 v[92:95], v[20:23], v[4:7], v[92:95]
	ds_read_b128 v[220:223], v249 offset:10240
	v_mfma_f32_16x16x32_bf16 v[112:115], v[20:23], v[8:11], v[112:115]
	ds_read_b128 v[208:211], v248 offset:3072
	v_mfma_f32_16x16x32_bf16 v[136:139], v[20:23], v[12:15], v[136:139]
	ds_read_b128 v[224:227], v249 offset:11264
	v_mfma_f32_16x16x32_bf16 v[104:107], v[162:165], v[0:3], v[104:107]
	ds_read_b128 v[228:231], v249 offset:12288
	v_mfma_f32_16x16x32_bf16 v[88:91], v[162:165], v[4:7], v[88:91]
	ds_read_b128 v[232:235], v249 offset:13312
	v_mfma_f32_16x16x32_bf16 v[120:123], v[162:165], v[8:11], v[120:123]
	ds_read_b128 v[236:239], v249 offset:14336
	v_mfma_f32_16x16x32_bf16 v[140:143], v[162:165], v[12:15], v[140:143]
	ds_read_b128 v[240:243], v249 offset:15360
	s_add_u32 m0, s25, s24
	v_mfma_f32_16x16x32_bf16 v[100:103], v[166:169], v[0:3], v[100:103]
	global_load_lds_dwordx4 v244, s[26:27]
	v_mfma_f32_16x16x32_bf16 v[84:87], v[166:169], v[4:7], v[84:87]
	v_mfma_f32_16x16x32_bf16 v[124:127], v[166:169], v[8:11], v[124:127]
	s_add_u32 m0, m0, 0x1000
	v_mfma_f32_16x16x32_bf16 v[144:147], v[166:169], v[12:15], v[144:147]
	global_load_lds_dwordx4 v245, s[26:27]
	v_mfma_f32_16x16x32_bf16 v[52:55], v[170:173], v[0:3], v[52:55]
	v_mfma_f32_16x16x32_bf16 v[36:39], v[170:173], v[4:7], v[36:39]
	s_add_u32 m0, m0, 0x1000
	v_mfma_f32_16x16x32_bf16 v[64:67], v[170:173], v[8:11], v[64:67]
	global_load_lds_dwordx4 v156, s[28:29]
	v_mfma_f32_16x16x32_bf16 v[76:79], v[170:173], v[12:15], v[76:79]
	v_mfma_f32_16x16x32_bf16 v[48:51], v[174:177], v[0:3], v[48:51]
	s_add_u32 m0, m0, 0x1000
	v_mfma_f32_16x16x32_bf16 v[32:35], v[174:177], v[4:7], v[32:35]
	global_load_lds_dwordx4 v157, s[28:29]
	v_mfma_f32_16x16x32_bf16 v[68:71], v[174:177], v[8:11], v[68:71]
	v_mfma_f32_16x16x32_bf16 v[72:75], v[174:177], v[12:15], v[72:75]
	s_add_u32 m0, m0, 0x1000
	v_mfma_f32_16x16x32_bf16 v[44:47], v[178:181], v[0:3], v[44:47]
	global_load_lds_dwordx4 v158, s[28:29]
	v_mfma_f32_16x16x32_bf16 v[28:31], v[178:181], v[4:7], v[28:31]
	v_mfma_f32_16x16x32_bf16 v[80:83], v[178:181], v[8:11], v[80:83]
	s_add_u32 m0, m0, 0x1000
	v_mfma_f32_16x16x32_bf16 v[60:63], v[178:181], v[12:15], v[60:63]
	global_load_lds_dwordx4 v159, s[28:29]
	v_mfma_f32_16x16x32_bf16 v[40:43], v[182:185], v[0:3], v[40:43]
	v_mfma_f32_16x16x32_bf16 v[24:27], v[182:185], v[4:7], v[24:27]
	v_mfma_f32_16x16x32_bf16 v[56:59], v[182:185], v[8:11], v[56:59]
	v_mfma_f32_16x16x32_bf16 v[148:151], v[182:185], v[12:15], v[148:151]
	s_add_u32 s26, s26, 0x40
	s_addc_u32 s27, s27, 0
	s_add_u32 s28, s28, 0x40000
	s_addc_u32 s29, s29, 0
	s_add_u32 s25, s25, 24576
	s_cmp_eq_u32 s25, 73728
	s_cselect_b32 s25, 0, s25
	s_add_u32 s30, s30, 24576
	s_cmp_eq_u32 s30, 73728
	s_cselect_b32 s30, 0, s30
	s_waitcnt vmcnt(6)
	s_waitcnt lgkmcnt(0)
	s_barrier
	s_sub_u32 s31, s31, 1
	s_cmp_lg_u32 s31, 0
	s_cbranch_scc1 .Lgm0_loop
	v_add_u32_e32 v248, s30, v155
	v_add_u32_e32 v249, s30, v160
	v_mfma_f32_16x16x32_bf16 v[128:131], v[212:215], v[186:189], v[128:131]
	ds_read_b128 v[0:3], v248
	v_mfma_f32_16x16x32_bf16 v[96:99], v[212:215], v[190:193], v[96:99]
	ds_read_b128 v[16:19], v249 offset:8192
	v_mfma_f32_16x16x32_bf16 v[108:111], v[212:215], v[194:197], v[108:111]
	ds_read_b128 v[4:7], v248 offset:1024
	v_mfma_f32_16x16x32_bf16 v[132:135], v[212:215], v[208:211], v[132:135]
	ds_read_b128 v[20:23], v249 offset:9216
	v_mfma_f32_16x16x32_bf16 v[116:119], v[216:219], v[186:189], v[116:119]
	ds_read_b128 v[8:11], v248 offset:2048
	v_mfma_f32_16x16x32_bf16 v[92:95], v[216:219], v[190:193], v[92:95]
	ds_read_b128 v[162:165], v249 offset:10240
	v_mfma_f32_16x16x32_bf16 v[112:115], v[216:219], v[194:197], v[112:115]
	ds_read_b128 v[12:15], v248 offset:3072
	v_mfma_f32_16x16x32_bf16 v[136:139], v[216:219], v[208:211], v[136:139]
	ds_read_b128 v[166:169], v249 offset:11264
	v_mfma_f32_16x16x32_bf16 v[104:107], v[220:223], v[186:189], v[104:107]
	ds_read_b128 v[170:173], v249 offset:12288
	v_mfma_f32_16x16x32_bf16 v[88:91], v[220:223], v[190:193], v[88:91]
	ds_read_b128 v[174:177], v249 offset:13312
	v_mfma_f32_16x16x32_bf16 v[120:123], v[220:223], v[194:197], v[120:123]
	ds_read_b128 v[178:181], v249 offset:14336
	v_mfma_f32_16x16x32_bf16 v[140:143], v[220:223], v[208:211], v[140:143]
	ds_read_b128 v[182:185], v249 offset:15360
	s_add_u32 m0, s25, s24
	v_mfma_f32_16x16x32_bf16 v[100:103], v[224:227], v[186:189], v[100:103]
	global_load_lds_dwordx4 v244, s[26:27]
	v_mfma_f32_16x16x32_bf16 v[84:87], v[224:227], v[190:193], v[84:87]
	v_mfma_f32_16x16x32_bf16 v[124:127], v[224:227], v[194:197], v[124:127]
	s_add_u32 m0, m0, 0x1000
	v_mfma_f32_16x16x32_bf16 v[144:147], v[224:227], v[208:211], v[144:147]
	global_load_lds_dwordx4 v245, s[26:27]
	v_mfma_f32_16x16x32_bf16 v[52:55], v[228:231], v[186:189], v[52:55]
	v_mfma_f32_16x16x32_bf16 v[36:39], v[228:231], v[190:193], v[36:39]
	s_add_u32 m0, m0, 0x1000
	v_mfma_f32_16x16x32_bf16 v[64:67], v[228:231], v[194:197], v[64:67]
	global_load_lds_dwordx4 v156, s[28:29]
	v_mfma_f32_16x16x32_bf16 v[76:79], v[228:231], v[208:211], v[76:79]
	v_mfma_f32_16x16x32_bf16 v[48:51], v[232:235], v[186:189], v[48:51]
	s_add_u32 m0, m0, 0x1000
	v_mfma_f32_16x16x32_bf16 v[32:35], v[232:235], v[190:193], v[32:35]
	global_load_lds_dwordx4 v157, s[28:29]
	v_mfma_f32_16x16x32_bf16 v[68:71], v[232:235], v[194:197], v[68:71]
	v_mfma_f32_16x16x32_bf16 v[72:75], v[232:235], v[208:211], v[72:75]
	s_add_u32 m0, m0, 0x1000
	v_mfma_f32_16x16x32_bf16 v[44:47], v[236:239], v[186:189], v[44:47]
	global_load_lds_dwordx4 v158, s[28:29]
	v_mfma_f32_16x16x32_bf16 v[28:31], v[236:239], v[190:193], v[28:31]
	v_mfma_f32_16x16x32_bf16 v[80:83], v[236:239], v[194:197], v[80:83]
	s_add_u32 m0, m0, 0x1000
	v_mfma_f32_16x16x32_bf16 v[60:63], v[236:239], v[208:211], v[60:63]
	global_load_lds_dwordx4 v159, s[28:29]
	v_mfma_f32_16x16x32_bf16 v[40:43], v[240:243], v[186:189], v[40:43]
	v_mfma_f32_16x16x32_bf16 v[24:27], v[240:243], v[190:193], v[24:27]
	v_mfma_f32_16x16x32_bf16 v[56:59], v[240:243], v[194:197], v[56:59]
	v_mfma_f32_16x16x32_bf16 v[148:151], v[240:243], v[208:211], v[148:151]
	s_add_u32 s26, s26, 0x40
	s_addc_u32 s27, s27, 0
	s_add_u32 s28, s28, 0x40000
	s_addc_u32 s29, s29, 0
	s_add_u32 s25, s25, 24576
	s_cmp_eq_u32 s25, 73728
	s_cselect_b32 s25, 0, s25
	s_add_u32 s30, s30, 24576
	s_cmp_eq_u32 s30, 73728
	s_cselect_b32 s30, 0, s30
	s_waitcnt vmcnt(6)
	s_waitcnt lgkmcnt(0)
	s_barrier
	v_add_u32_e32 v248, s30, v155
	v_add_u32_e32 v249, s30, v160
	v_mfma_f32_16x16x32_bf16 v[128:131], v[16:19], v[0:3], v[128:131]
	ds_read_b128 v[186:189], v248
	v_mfma_f32_16x16x32_bf16 v[96:99], v[16:19], v[4:7], v[96:99]
	ds_read_b128 v[212:215], v249 offset:8192
	v_mfma_f32_16x16x32_bf16 v[108:111], v[16:19], v[8:11], v[108:111]
	ds_read_b128 v[190:193], v248 offset:1024
	v_mfma_f32_16x16x32_bf16 v[132:135], v[16:19], v[12:15], v[132:135]
	ds_read_b128 v[216:219], v249 offset:9216
	v_mfma_f32_16x16x32_bf16 v[116:119], v[20:23], v[0:3], v[116:119]
	ds_read_b128 v[194:197], v248 offset:2048
	v_mfma_f32_16x16x32_bf16 v[92:95], v[20:23], v[4:7], v[92:95]
	ds_read_b128 v[220:223], v249 offset:10240
	v_mfma_f32_16x16x32_bf16 v[112:115], v[20:23], v[8:11], v[112:115]
	ds_read_b128 v[208:211], v248 offset:3072
	v_mfma_f32_16x16x32_bf16 v[136:139], v[20:23], v[12:15], v[136:139]
	ds_read_b128 v[224:227], v249 offset:11264
	v_mfma_f32_16x16x32_bf16 v[104:107], v[162:165], v[0:3], v[104:107]
	ds_read_b128 v[228:231], v249 offset:12288
	v_mfma_f32_16x16x32_bf16 v[88:91], v[162:165], v[4:7], v[88:91]
	ds_read_b128 v[232:235], v249 offset:13312
	v_mfma_f32_16x16x32_bf16 v[120:123], v[162:165], v[8:11], v[120:123]
	ds_read_b128 v[236:239], v249 offset:14336
	v_mfma_f32_16x16x32_bf16 v[140:143], v[162:165], v[12:15], v[140:143]
	ds_read_b128 v[240:243], v249 offset:15360
	v_mfma_f32_16x16x32_bf16 v[100:103], v[166:169], v[0:3], v[100:103]
	v_mfma_f32_16x16x32_bf16 v[84:87], v[166:169], v[4:7], v[84:87]
	v_mfma_f32_16x16x32_bf16 v[124:127], v[166:169], v[8:11], v[124:127]
	v_mfma_f32_16x16x32_bf16 v[144:147], v[166:169], v[12:15], v[144:147]
	v_mfma_f32_16x16x32_bf16 v[52:55], v[170:173], v[0:3], v[52:55]
	v_mfma_f32_16x16x32_bf16 v[36:39], v[170:173], v[4:7], v[36:39]
	v_mfma_f32_16x16x32_bf16 v[64:67], v[170:173], v[8:11], v[64:67]
	v_mfma_f32_16x16x32_bf16 v[76:79], v[170:173], v[12:15], v[76:79]
	v_mfma_f32_16x16x32_bf16 v[48:51], v[174:177], v[0:3], v[48:51]
	v_mfma_f32_16x16x32_bf16 v[32:35], v[174:177], v[4:7], v[32:35]
	v_mfma_f32_16x16x32_bf16 v[68:71], v[174:177], v[8:11], v[68:71]
	v_mfma_f32_16x16x32_bf16 v[72:75], v[174:177], v[12:15], v[72:75]
	v_mfma_f32_16x16x32_bf16 v[44:47], v[178:181], v[0:3], v[44:47]
	v_mfma_f32_16x16x32_bf16 v[28:31], v[178:181], v[4:7], v[28:31]
	v_mfma_f32_16x16x32_bf16 v[80:83], v[178:181], v[8:11], v[80:83]
	v_mfma_f32_16x16x32_bf16 v[60:63], v[178:181], v[12:15], v[60:63]
	v_mfma_f32_16x16x32_bf16 v[40:43], v[182:185], v[0:3], v[40:43]
	v_mfma_f32_16x16x32_bf16 v[24:27], v[182:185], v[4:7], v[24:27]
	v_mfma_f32_16x16x32_bf16 v[56:59], v[182:185], v[8:11], v[56:59]
	v_mfma_f32_16x16x32_bf16 v[148:151], v[182:185], v[12:15], v[148:151]
	s_add_u32 s30, s30, 24576
	s_cmp_eq_u32 s30, 73728
	s_cselect_b32 s30, 0, s30
	s_waitcnt vmcnt(0)
	s_waitcnt lgkmcnt(0)
	s_barrier
	v_add_u32_e32 v248, s30, v155
	v_add_u32_e32 v249, s30, v160
	v_mfma_f32_16x16x32_bf16 v[128:131], v[212:215], v[186:189], v[128:131]
	ds_read_b128 v[0:3], v248
	v_mfma_f32_16x16x32_bf16 v[96:99], v[212:215], v[190:193], v[96:99]
	ds_read_b128 v[16:19], v249 offset:8192
	v_mfma_f32_16x16x32_bf16 v[108:111], v[212:215], v[194:197], v[108:111]
	ds_read_b128 v[4:7], v248 offset:1024
	v_mfma_f32_16x16x32_bf16 v[132:135], v[212:215], v[208:211], v[132:135]
	ds_read_b128 v[20:23], v249 offset:9216
	v_mfma_f32_16x16x32_bf16 v[116:119], v[216:219], v[186:189], v[116:119]
	ds_read_b128 v[8:11], v248 offset:2048
	v_mfma_f32_16x16x32_bf16 v[92:95], v[216:219], v[190:193], v[92:95]
	ds_read_b128 v[162:165], v249 offset:10240
	v_mfma_f32_16x16x32_bf16 v[112:115], v[216:219], v[194:197], v[112:115]
	ds_read_b128 v[12:15], v248 offset:3072
	v_mfma_f32_16x16x32_bf16 v[136:139], v[216:219], v[208:211], v[136:139]
	ds_read_b128 v[166:169], v249 offset:11264
	v_mfma_f32_16x16x32_bf16 v[104:107], v[220:223], v[186:189], v[104:107]
	ds_read_b128 v[170:173], v249 offset:12288
	v_mfma_f32_16x16x32_bf16 v[88:91], v[220:223], v[190:193], v[88:91]
	ds_read_b128 v[174:177], v249 offset:13312
	v_mfma_f32_16x16x32_bf16 v[120:123], v[220:223], v[194:197], v[120:123]
	ds_read_b128 v[178:181], v249 offset:14336
	v_mfma_f32_16x16x32_bf16 v[140:143], v[220:223], v[208:211], v[140:143]
	ds_read_b128 v[182:185], v249 offset:15360
	v_mfma_f32_16x16x32_bf16 v[100:103], v[224:227], v[186:189], v[100:103]
	v_mfma_f32_16x16x32_bf16 v[84:87], v[224:227], v[190:193], v[84:87]
	v_mfma_f32_16x16x32_bf16 v[124:127], v[224:227], v[194:197], v[124:127]
	v_mfma_f32_16x16x32_bf16 v[144:147], v[224:227], v[208:211], v[144:147]
	v_mfma_f32_16x16x32_bf16 v[52:55], v[228:231], v[186:189], v[52:55]
	v_mfma_f32_16x16x32_bf16 v[36:39], v[228:231], v[190:193], v[36:39]
	v_mfma_f32_16x16x32_bf16 v[64:67], v[228:231], v[194:197], v[64:67]
	v_mfma_f32_16x16x32_bf16 v[76:79], v[228:231], v[208:211], v[76:79]
	v_mfma_f32_16x16x32_bf16 v[48:51], v[232:235], v[186:189], v[48:51]
	v_mfma_f32_16x16x32_bf16 v[32:35], v[232:235], v[190:193], v[32:35]
	v_mfma_f32_16x16x32_bf16 v[68:71], v[232:235], v[194:197], v[68:71]
	v_mfma_f32_16x16x32_bf16 v[72:75], v[232:235], v[208:211], v[72:75]
	v_mfma_f32_16x16x32_bf16 v[44:47], v[236:239], v[186:189], v[44:47]
	v_mfma_f32_16x16x32_bf16 v[28:31], v[236:239], v[190:193], v[28:31]
	v_mfma_f32_16x16x32_bf16 v[80:83], v[236:239], v[194:197], v[80:83]
	v_mfma_f32_16x16x32_bf16 v[60:63], v[236:239], v[208:211], v[60:63]
	v_mfma_f32_16x16x32_bf16 v[40:43], v[240:243], v[186:189], v[40:43]
	v_mfma_f32_16x16x32_bf16 v[24:27], v[240:243], v[190:193], v[24:27]
	v_mfma_f32_16x16x32_bf16 v[56:59], v[240:243], v[194:197], v[56:59]
	v_mfma_f32_16x16x32_bf16 v[148:151], v[240:243], v[208:211], v[148:151]
	s_add_u32 s30, s30, 24576
	s_cmp_eq_u32 s30, 73728
	s_cselect_b32 s30, 0, s30
	s_waitcnt lgkmcnt(0)
	s_barrier
	v_mfma_f32_16x16x32_bf16 v[128:131], v[16:19], v[0:3], v[128:131]
	v_mfma_f32_16x16x32_bf16 v[96:99], v[16:19], v[4:7], v[96:99]
	v_mfma_f32_16x16x32_bf16 v[108:111], v[16:19], v[8:11], v[108:111]
	v_mfma_f32_16x16x32_bf16 v[132:135], v[16:19], v[12:15], v[132:135]
	v_mfma_f32_16x16x32_bf16 v[116:119], v[20:23], v[0:3], v[116:119]
	v_mfma_f32_16x16x32_bf16 v[92:95], v[20:23], v[4:7], v[92:95]
	v_mfma_f32_16x16x32_bf16 v[112:115], v[20:23], v[8:11], v[112:115]
	v_mfma_f32_16x16x32_bf16 v[136:139], v[20:23], v[12:15], v[136:139]
	v_mfma_f32_16x16x32_bf16 v[104:107], v[162:165], v[0:3], v[104:107]
	v_mfma_f32_16x16x32_bf16 v[88:91], v[162:165], v[4:7], v[88:91]
	v_mfma_f32_16x16x32_bf16 v[120:123], v[162:165], v[8:11], v[120:123]
	v_mfma_f32_16x16x32_bf16 v[140:143], v[162:165], v[12:15], v[140:143]
	v_mfma_f32_16x16x32_bf16 v[100:103], v[166:169], v[0:3], v[100:103]
	v_mfma_f32_16x16x32_bf16 v[84:87], v[166:169], v[4:7], v[84:87]
	v_mfma_f32_16x16x32_bf16 v[124:127], v[166:169], v[8:11], v[124:127]
	v_mfma_f32_16x16x32_bf16 v[144:147], v[166:169], v[12:15], v[144:147]
	v_mfma_f32_16x16x32_bf16 v[52:55], v[170:173], v[0:3], v[52:55]
	v_mfma_f32_16x16x32_bf16 v[36:39], v[170:173], v[4:7], v[36:39]
	v_mfma_f32_16x16x32_bf16 v[64:67], v[170:173], v[8:11], v[64:67]
	v_mfma_f32_16x16x32_bf16 v[76:79], v[170:173], v[12:15], v[76:79]
	v_mfma_f32_16x16x32_bf16 v[48:51], v[174:177], v[0:3], v[48:51]
	v_mfma_f32_16x16x32_bf16 v[32:35], v[174:177], v[4:7], v[32:35]
	v_mfma_f32_16x16x32_bf16 v[68:71], v[174:177], v[8:11], v[68:71]
	v_mfma_f32_16x16x32_bf16 v[72:75], v[174:177], v[12:15], v[72:75]
	v_mfma_f32_16x16x32_bf16 v[44:47], v[178:181], v[0:3], v[44:47]
	v_mfma_f32_16x16x32_bf16 v[28:31], v[178:181], v[4:7], v[28:31]
	v_mfma_f32_16x16x32_bf16 v[80:83], v[178:181], v[8:11], v[80:83]
	v_mfma_f32_16x16x32_bf16 v[60:63], v[178:181], v[12:15], v[60:63]
	v_mfma_f32_16x16x32_bf16 v[40:43], v[182:185], v[0:3], v[40:43]
	v_mfma_f32_16x16x32_bf16 v[24:27], v[182:185], v[4:7], v[24:27]
	v_mfma_f32_16x16x32_bf16 v[56:59], v[182:185], v[8:11], v[56:59]
	v_mfma_f32_16x16x32_bf16 v[148:151], v[182:185], v[12:15], v[148:151]
	s_add_i32 s12, s12, s6
	s_add_i32 s11, s11, s9
	s_add_i32 s10, s10, s6
	s_cmpk_gt_u32 s12, 0x1ff
	s_cselect_b32 s23, 1, 0
	v_mov_b32 v250, v198
	s_nop 0
	v_and_b32_e32 v251, 15, v250
	v_bfe_u32 v156, v250, 4, 2
	v_bfe_u32 v157, v250, 6, 1
	v_bfe_u32 v158, v250, 7, 1
	v_lshl_add_u32 v158, v158, 6, s14
	v_add_u32_e32 v158, v158, v251
	v_lshl_add_u32 v157, v157, 7, s13
	v_lshl_add_u32 v159, v156, 2, v157
	v_lshlrev_b32_e32 v230, 6, v158
	v_lshrrev_b32_e32 v228, 5, v157
	v_lshlrev_b32_e32 v228, 21, v228
	v_lshl_add_u32 v228, v158, 6, v228
	v_lshl_add_u32 v228, v156, 3, v228
	v_and_b32_e32 v161, 1, v156
	v_mul_u32_u24_e32 v161, 24, v161
	v_add_u32_e32 v229, v228, v161
	s_mov_b32 s30, s92
	s_mov_b32 s31, s93
	global_load_dwordx4 v[0:3], v230, s[94:95]
	global_load_dwordx4 v[4:7], v230, s[94:95] offset:16
	global_load_dwordx4 v[8:11], v230, s[94:95] offset:32
	global_load_dwordx4 v[12:15], v230, s[94:95] offset:48
	global_load_dwordx4 v[16:19], v230, s[94:95] offset:1024
	global_load_dwordx4 v[20:23], v230, s[94:95] offset:1040
	global_load_dwordx4 v[162:165], v230, s[94:95] offset:1056
	global_load_dwordx4 v[166:169], v230, s[94:95] offset:1072
	global_load_dwordx4 v[170:173], v230, s[94:95] offset:2048
	global_load_dwordx4 v[174:177], v230, s[94:95] offset:2064
	global_load_dwordx4 v[178:181], v230, s[94:95] offset:2080
	global_load_dwordx4 v[182:185], v230, s[94:95] offset:2096
	global_load_dwordx4 v[186:189], v230, s[94:95] offset:3072
	global_load_dwordx4 v[190:193], v230, s[94:95] offset:3088
	global_load_dwordx4 v[194:197], v230, s[94:95] offset:3104
	global_load_dwordx4 v[208:211], v230, s[94:95] offset:3120
	s_waitcnt vmcnt(12)
	v_add_f32_e32 v231, v0, v1
	v_add_f32_e32 v248, v2, v3
	v_add_f32_e32 v231, v231, v248
	v_add_f32_e32 v249, v4, v5
	v_add_f32_e32 v248, v6, v7
	v_add_f32_e32 v249, v249, v248
	v_add_f32_e32 v231, v231, v249
	v_add_f32_e32 v249, v8, v9
	v_add_f32_e32 v248, v10, v11
	v_add_f32_e32 v249, v249, v248
	v_add_f32_e32 v231, v231, v249
	v_add_f32_e32 v249, v12, v13
	v_add_f32_e32 v248, v14, v15
	v_add_f32_e32 v249, v249, v248
	v_add_f32_e32 v231, v231, v249
	v_fmamk_f32 v231, v231, 0x3a800000, v199
	v_cmp_gt_f32_e32 vcc, s73, v231
	v_mul_f32_e32 v248, 0x4b800000, v231
	s_nop 0
	v_cndmask_b32_e32 v231, v231, v248, vcc
	v_rsq_f32_e32 v231, v231
	s_nop 0
	v_mul_f32_e32 v248, 0x45800000, v231
	v_cndmask_b32_e32 v231, v231, v248, vcc
	v_mul_f32_e32 v212, v128, v231
	v_mul_f32_e32 v249, v129, v231
	v_mul_f32_e32 v213, v130, v231
	v_mul_f32_e32 v248, v131, v231
	v_max_f32_e32 v212, 0, v212
	v_max_f32_e32 v249, 0, v249
	v_max_f32_e32 v213, 0, v213
	v_max_f32_e32 v248, 0, v248
	v_mul_f32_e32 v212, v212, v212
	v_mul_f32_e32 v249, v249, v249
	v_mul_f32_e32 v213, v213, v213
	v_mul_f32_e32 v248, v248, v248
	v_cvt_pk_bf16_f32 v212, v212, v249
	v_cvt_pk_bf16_f32 v213, v213, v248
	v_mul_f32_e32 v214, v116, v231
	v_mul_f32_e32 v249, v117, v231
	v_mul_f32_e32 v215, v118, v231
	v_mul_f32_e32 v248, v119, v231
	v_max_f32_e32 v214, 0, v214
	v_max_f32_e32 v249, 0, v249
	v_max_f32_e32 v215, 0, v215
	v_max_f32_e32 v248, 0, v248
	v_mul_f32_e32 v214, v214, v214
	v_mul_f32_e32 v249, v249, v249
	v_mul_f32_e32 v215, v215, v215
	v_mul_f32_e32 v248, v248, v248
	v_cvt_pk_bf16_f32 v214, v214, v249
	v_cvt_pk_bf16_f32 v215, v215, v248
	s_add_u32 s30, s92, 0x0
	s_addc_u32 s31, s93, 0
	s_nop 0
	v_permlane16_swap_b32_e32 v212, v214
	v_permlane16_swap_b32_e32 v213, v215
	global_store_dwordx4 v229, v[212:215], s[30:31]
	v_mul_f32_e32 v216, v104, v231
	v_mul_f32_e32 v249, v105, v231
	v_mul_f32_e32 v217, v106, v231
	v_mul_f32_e32 v248, v107, v231
	v_max_f32_e32 v216, 0, v216
	v_max_f32_e32 v249, 0, v249
	v_max_f32_e32 v217, 0, v217
	v_max_f32_e32 v248, 0, v248
	v_mul_f32_e32 v216, v216, v216
	v_mul_f32_e32 v249, v249, v249
	v_mul_f32_e32 v217, v217, v217
	v_mul_f32_e32 v248, v248, v248
	v_cvt_pk_bf16_f32 v216, v216, v249
	v_cvt_pk_bf16_f32 v217, v217, v248
	v_mul_f32_e32 v218, v100, v231
	v_mul_f32_e32 v249, v101, v231
	v_mul_f32_e32 v219, v102, v231
	v_mul_f32_e32 v248, v103, v231
	v_max_f32_e32 v218, 0, v218
	v_max_f32_e32 v249, 0, v249
	v_max_f32_e32 v219, 0, v219
	v_max_f32_e32 v248, 0, v248
	v_mul_f32_e32 v218, v218, v218
	v_mul_f32_e32 v249, v249, v249
	v_mul_f32_e32 v219, v219, v219
	v_mul_f32_e32 v248, v248, v248
	v_cvt_pk_bf16_f32 v218, v218, v249
	v_cvt_pk_bf16_f32 v219, v219, v248
	s_add_u32 s30, s92, 0x200000
	s_addc_u32 s31, s93, 0
	s_nop 0
	v_permlane16_swap_b32_e32 v216, v218
	v_permlane16_swap_b32_e32 v217, v219
	global_store_dwordx4 v229, v[216:219], s[30:31]
	v_mul_f32_e32 v220, v52, v231
	v_mul_f32_e32 v249, v53, v231
	v_mul_f32_e32 v221, v54, v231
	v_mul_f32_e32 v248, v55, v231
	v_max_f32_e32 v220, 0, v220
	v_max_f32_e32 v249, 0, v249
	v_max_f32_e32 v221, 0, v221
	v_max_f32_e32 v248, 0, v248
	v_mul_f32_e32 v220, v220, v220
	v_mul_f32_e32 v249, v249, v249
	v_mul_f32_e32 v221, v221, v221
	v_mul_f32_e32 v248, v248, v248
	v_cvt_pk_bf16_f32 v220, v220, v249
	v_cvt_pk_bf16_f32 v221, v221, v248
	v_mul_f32_e32 v222, v48, v231
	v_mul_f32_e32 v249, v49, v231
	v_mul_f32_e32 v223, v50, v231
	v_mul_f32_e32 v248, v51, v231
	v_max_f32_e32 v222, 0, v222
	v_max_f32_e32 v249, 0, v249
	v_max_f32_e32 v223, 0, v223
	v_max_f32_e32 v248, 0, v248
	v_mul_f32_e32 v222, v222, v222
	v_mul_f32_e32 v249, v249, v249
	v_mul_f32_e32 v223, v223, v223
	v_mul_f32_e32 v248, v248, v248
	v_cvt_pk_bf16_f32 v222, v222, v249
	v_cvt_pk_bf16_f32 v223, v223, v248
	s_add_u32 s30, s92, 0x400000
	s_addc_u32 s31, s93, 0
	s_nop 0
	v_permlane16_swap_b32_e32 v220, v222
	v_permlane16_swap_b32_e32 v221, v223
	global_store_dwordx4 v229, v[220:223], s[30:31]
	v_mul_f32_e32 v224, v44, v231
	v_mul_f32_e32 v249, v45, v231
	v_mul_f32_e32 v225, v46, v231
	v_mul_f32_e32 v248, v47, v231
	v_max_f32_e32 v224, 0, v224
	v_max_f32_e32 v249, 0, v249
	v_max_f32_e32 v225, 0, v225
	v_max_f32_e32 v248, 0, v248
	v_mul_f32_e32 v224, v224, v224
	v_mul_f32_e32 v249, v249, v249
	v_mul_f32_e32 v225, v225, v225
	v_mul_f32_e32 v248, v248, v248
	v_cvt_pk_bf16_f32 v224, v224, v249
	v_cvt_pk_bf16_f32 v225, v225, v248
	v_mul_f32_e32 v226, v40, v231
	v_mul_f32_e32 v249, v41, v231
	v_mul_f32_e32 v227, v42, v231
	v_mul_f32_e32 v248, v43, v231
	v_max_f32_e32 v226, 0, v226
	v_max_f32_e32 v249, 0, v249
	v_max_f32_e32 v227, 0, v227
	v_max_f32_e32 v248, 0, v248
	v_mul_f32_e32 v226, v226, v226
	v_mul_f32_e32 v249, v249, v249
	v_mul_f32_e32 v227, v227, v227
	v_mul_f32_e32 v248, v248, v248
	v_cvt_pk_bf16_f32 v226, v226, v249
	v_cvt_pk_bf16_f32 v227, v227, v248
	s_add_u32 s30, s92, 0x600000
	s_addc_u32 s31, s93, 0
	s_nop 0
	v_permlane16_swap_b32_e32 v224, v226
	v_permlane16_swap_b32_e32 v225, v227
	global_store_dwordx4 v229, v[224:227], s[30:31]
	s_waitcnt vmcnt(12)
	v_add_f32_e32 v231, v16, v17
	v_add_f32_e32 v248, v18, v19
	v_add_f32_e32 v231, v231, v248
	v_add_f32_e32 v249, v20, v21
	v_add_f32_e32 v248, v22, v23
	v_add_f32_e32 v249, v249, v248
	v_add_f32_e32 v231, v231, v249
	v_add_f32_e32 v249, v162, v163
	v_add_f32_e32 v248, v164, v165
	v_add_f32_e32 v249, v249, v248
	v_add_f32_e32 v231, v231, v249
	v_add_f32_e32 v249, v166, v167
	v_add_f32_e32 v248, v168, v169
	v_add_f32_e32 v249, v249, v248
	v_add_f32_e32 v231, v231, v249
	v_fmamk_f32 v231, v231, 0x3a800000, v199
	v_cmp_gt_f32_e32 vcc, s73, v231
	v_mul_f32_e32 v248, 0x4b800000, v231
	s_nop 0
	v_cndmask_b32_e32 v231, v231, v248, vcc
	v_rsq_f32_e32 v231, v231
	s_nop 0
	v_mul_f32_e32 v248, 0x45800000, v231
	v_cndmask_b32_e32 v231, v231, v248, vcc
	v_mul_f32_e32 v212, v96, v231
	v_mul_f32_e32 v249, v97, v231
	v_mul_f32_e32 v213, v98, v231
	v_mul_f32_e32 v248, v99, v231
	v_max_f32_e32 v212, 0, v212
	v_max_f32_e32 v249, 0, v249
	v_max_f32_e32 v213, 0, v213
	v_max_f32_e32 v248, 0, v248
	v_mul_f32_e32 v212, v212, v212
	v_mul_f32_e32 v249, v249, v249
	v_mul_f32_e32 v213, v213, v213
	v_mul_f32_e32 v248, v248, v248
	v_cvt_pk_bf16_f32 v212, v212, v249
	v_cvt_pk_bf16_f32 v213, v213, v248
	v_mul_f32_e32 v214, v92, v231
	v_mul_f32_e32 v249, v93, v231
	v_mul_f32_e32 v215, v94, v231
	v_mul_f32_e32 v248, v95, v231
	v_max_f32_e32 v214, 0, v214
	v_max_f32_e32 v249, 0, v249
	v_max_f32_e32 v215, 0, v215
	v_max_f32_e32 v248, 0, v248
	v_mul_f32_e32 v214, v214, v214
	v_mul_f32_e32 v249, v249, v249
	v_mul_f32_e32 v215, v215, v215
	v_mul_f32_e32 v248, v248, v248
	v_cvt_pk_bf16_f32 v214, v214, v249
	v_cvt_pk_bf16_f32 v215, v215, v248
	s_add_u32 s30, s92, 0x400
	s_addc_u32 s31, s93, 0
	s_nop 0
	v_permlane16_swap_b32_e32 v212, v214
	v_permlane16_swap_b32_e32 v213, v215
	global_store_dwordx4 v229, v[212:215], s[30:31]
	v_mul_f32_e32 v216, v88, v231
	v_mul_f32_e32 v249, v89, v231
	v_mul_f32_e32 v217, v90, v231
	v_mul_f32_e32 v248, v91, v231
	v_max_f32_e32 v216, 0, v216
	v_max_f32_e32 v249, 0, v249
	v_max_f32_e32 v217, 0, v217
	v_max_f32_e32 v248, 0, v248
	v_mul_f32_e32 v216, v216, v216
	v_mul_f32_e32 v249, v249, v249
	v_mul_f32_e32 v217, v217, v217
	v_mul_f32_e32 v248, v248, v248
	v_cvt_pk_bf16_f32 v216, v216, v249
	v_cvt_pk_bf16_f32 v217, v217, v248
	v_mul_f32_e32 v218, v84, v231
	v_mul_f32_e32 v249, v85, v231
	v_mul_f32_e32 v219, v86, v231
	v_mul_f32_e32 v248, v87, v231
	v_max_f32_e32 v218, 0, v218
	v_max_f32_e32 v249, 0, v249
	v_max_f32_e32 v219, 0, v219
	v_max_f32_e32 v248, 0, v248
	v_mul_f32_e32 v218, v218, v218
	v_mul_f32_e32 v249, v249, v249
	v_mul_f32_e32 v219, v219, v219
	v_mul_f32_e32 v248, v248, v248
	v_cvt_pk_bf16_f32 v218, v218, v249
	v_cvt_pk_bf16_f32 v219, v219, v248
	s_add_u32 s30, s92, 0x200400
	s_addc_u32 s31, s93, 0
	s_nop 0
	v_permlane16_swap_b32_e32 v216, v218
	v_permlane16_swap_b32_e32 v217, v219
	global_store_dwordx4 v229, v[216:219], s[30:31]
	v_mul_f32_e32 v220, v36, v231
	v_mul_f32_e32 v249, v37, v231
	v_mul_f32_e32 v221, v38, v231
	v_mul_f32_e32 v248, v39, v231
	v_max_f32_e32 v220, 0, v220
	v_max_f32_e32 v249, 0, v249
	v_max_f32_e32 v221, 0, v221
	v_max_f32_e32 v248, 0, v248
	v_mul_f32_e32 v220, v220, v220
	v_mul_f32_e32 v249, v249, v249
	v_mul_f32_e32 v221, v221, v221
	v_mul_f32_e32 v248, v248, v248
	v_cvt_pk_bf16_f32 v220, v220, v249
	v_cvt_pk_bf16_f32 v221, v221, v248
	v_mul_f32_e32 v222, v32, v231
	v_mul_f32_e32 v249, v33, v231
	v_mul_f32_e32 v223, v34, v231
	v_mul_f32_e32 v248, v35, v231
	v_max_f32_e32 v222, 0, v222
	v_max_f32_e32 v249, 0, v249
	v_max_f32_e32 v223, 0, v223
	v_max_f32_e32 v248, 0, v248
	v_mul_f32_e32 v222, v222, v222
	v_mul_f32_e32 v249, v249, v249
	v_mul_f32_e32 v223, v223, v223
	v_mul_f32_e32 v248, v248, v248
	v_cvt_pk_bf16_f32 v222, v222, v249
	v_cvt_pk_bf16_f32 v223, v223, v248
	s_add_u32 s30, s92, 0x400400
	s_addc_u32 s31, s93, 0
	s_nop 0
	v_permlane16_swap_b32_e32 v220, v222
	v_permlane16_swap_b32_e32 v221, v223
	global_store_dwordx4 v229, v[220:223], s[30:31]
	v_mul_f32_e32 v224, v28, v231
	v_mul_f32_e32 v249, v29, v231
	v_mul_f32_e32 v225, v30, v231
	v_mul_f32_e32 v248, v31, v231
	v_max_f32_e32 v224, 0, v224
	v_max_f32_e32 v249, 0, v249
	v_max_f32_e32 v225, 0, v225
	v_max_f32_e32 v248, 0, v248
	v_mul_f32_e32 v224, v224, v224
	v_mul_f32_e32 v249, v249, v249
	v_mul_f32_e32 v225, v225, v225
	v_mul_f32_e32 v248, v248, v248
	v_cvt_pk_bf16_f32 v224, v224, v249
	v_cvt_pk_bf16_f32 v225, v225, v248
	v_mul_f32_e32 v226, v24, v231
	v_mul_f32_e32 v249, v25, v231
	v_mul_f32_e32 v227, v26, v231
	v_mul_f32_e32 v248, v27, v231
	v_max_f32_e32 v226, 0, v226
	v_max_f32_e32 v249, 0, v249
	v_max_f32_e32 v227, 0, v227
	v_max_f32_e32 v248, 0, v248
	v_mul_f32_e32 v226, v226, v226
	v_mul_f32_e32 v249, v249, v249
	v_mul_f32_e32 v227, v227, v227
	v_mul_f32_e32 v248, v248, v248
	v_cvt_pk_bf16_f32 v226, v226, v249
	v_cvt_pk_bf16_f32 v227, v227, v248
	s_add_u32 s30, s92, 0x600400
	s_addc_u32 s31, s93, 0
	s_nop 0
	v_permlane16_swap_b32_e32 v224, v226
	v_permlane16_swap_b32_e32 v225, v227
	global_store_dwordx4 v229, v[224:227], s[30:31]
	s_waitcnt vmcnt(12)
	v_add_f32_e32 v231, v170, v171
	v_add_f32_e32 v248, v172, v173
	v_add_f32_e32 v231, v231, v248
	v_add_f32_e32 v249, v174, v175
	v_add_f32_e32 v248, v176, v177
	v_add_f32_e32 v249, v249, v248
	v_add_f32_e32 v231, v231, v249
	v_add_f32_e32 v249, v178, v179
	v_add_f32_e32 v248, v180, v181
	v_add_f32_e32 v249, v249, v248
	v_add_f32_e32 v231, v231, v249
	v_add_f32_e32 v249, v182, v183
	v_add_f32_e32 v248, v184, v185
	v_add_f32_e32 v249, v249, v248
	v_add_f32_e32 v231, v231, v249
	v_fmamk_f32 v231, v231, 0x3a800000, v199
	v_cmp_gt_f32_e32 vcc, s73, v231
	v_mul_f32_e32 v248, 0x4b800000, v231
	s_nop 0
	v_cndmask_b32_e32 v231, v231, v248, vcc
	v_rsq_f32_e32 v231, v231
	s_nop 0
	v_mul_f32_e32 v248, 0x45800000, v231
	v_cndmask_b32_e32 v231, v231, v248, vcc
	v_mul_f32_e32 v212, v108, v231
	v_mul_f32_e32 v249, v109, v231
	v_mul_f32_e32 v213, v110, v231
	v_mul_f32_e32 v248, v111, v231
	v_max_f32_e32 v212, 0, v212
	v_max_f32_e32 v249, 0, v249
	v_max_f32_e32 v213, 0, v213
	v_max_f32_e32 v248, 0, v248
	v_mul_f32_e32 v212, v212, v212
	v_mul_f32_e32 v249, v249, v249
	v_mul_f32_e32 v213, v213, v213
	v_mul_f32_e32 v248, v248, v248
	v_cvt_pk_bf16_f32 v212, v212, v249
	v_cvt_pk_bf16_f32 v213, v213, v248
	v_mul_f32_e32 v214, v112, v231
	v_mul_f32_e32 v249, v113, v231
	v_mul_f32_e32 v215, v114, v231
	v_mul_f32_e32 v248, v115, v231
	v_max_f32_e32 v214, 0, v214
	v_max_f32_e32 v249, 0, v249
	v_max_f32_e32 v215, 0, v215
	v_max_f32_e32 v248, 0, v248
	v_mul_f32_e32 v214, v214, v214
	v_mul_f32_e32 v249, v249, v249
	v_mul_f32_e32 v215, v215, v215
	v_mul_f32_e32 v248, v248, v248
	v_cvt_pk_bf16_f32 v214, v214, v249
	v_cvt_pk_bf16_f32 v215, v215, v248
	s_add_u32 s30, s92, 0x800
	s_addc_u32 s31, s93, 0
	s_nop 0
	v_permlane16_swap_b32_e32 v212, v214
	v_permlane16_swap_b32_e32 v213, v215
	global_store_dwordx4 v229, v[212:215], s[30:31]
	v_mul_f32_e32 v216, v120, v231
	v_mul_f32_e32 v249, v121, v231
	v_mul_f32_e32 v217, v122, v231
	v_mul_f32_e32 v248, v123, v231
	v_max_f32_e32 v216, 0, v216
	v_max_f32_e32 v249, 0, v249
	v_max_f32_e32 v217, 0, v217
	v_max_f32_e32 v248, 0, v248
	v_mul_f32_e32 v216, v216, v216
	v_mul_f32_e32 v249, v249, v249
	v_mul_f32_e32 v217, v217, v217
	v_mul_f32_e32 v248, v248, v248
	v_cvt_pk_bf16_f32 v216, v216, v249
	v_cvt_pk_bf16_f32 v217, v217, v248
	v_mul_f32_e32 v218, v124, v231
	v_mul_f32_e32 v249, v125, v231
	v_mul_f32_e32 v219, v126, v231
	v_mul_f32_e32 v248, v127, v231
	v_max_f32_e32 v218, 0, v218
	v_max_f32_e32 v249, 0, v249
	v_max_f32_e32 v219, 0, v219
	v_max_f32_e32 v248, 0, v248
	v_mul_f32_e32 v218, v218, v218
	v_mul_f32_e32 v249, v249, v249
	v_mul_f32_e32 v219, v219, v219
	v_mul_f32_e32 v248, v248, v248
	v_cvt_pk_bf16_f32 v218, v218, v249
	v_cvt_pk_bf16_f32 v219, v219, v248
	s_add_u32 s30, s92, 0x200800
	s_addc_u32 s31, s93, 0
	s_nop 0
	v_permlane16_swap_b32_e32 v216, v218
	v_permlane16_swap_b32_e32 v217, v219
	global_store_dwordx4 v229, v[216:219], s[30:31]
	v_mul_f32_e32 v220, v64, v231
	v_mul_f32_e32 v249, v65, v231
	v_mul_f32_e32 v221, v66, v231
	v_mul_f32_e32 v248, v67, v231
	v_max_f32_e32 v220, 0, v220
	v_max_f32_e32 v249, 0, v249
	v_max_f32_e32 v221, 0, v221
	v_max_f32_e32 v248, 0, v248
	v_mul_f32_e32 v220, v220, v220
	v_mul_f32_e32 v249, v249, v249
	v_mul_f32_e32 v221, v221, v221
	v_mul_f32_e32 v248, v248, v248
	v_cvt_pk_bf16_f32 v220, v220, v249
	v_cvt_pk_bf16_f32 v221, v221, v248
	v_mul_f32_e32 v222, v68, v231
	v_mul_f32_e32 v249, v69, v231
	v_mul_f32_e32 v223, v70, v231
	v_mul_f32_e32 v248, v71, v231
	v_max_f32_e32 v222, 0, v222
	v_max_f32_e32 v249, 0, v249
	v_max_f32_e32 v223, 0, v223
	v_max_f32_e32 v248, 0, v248
	v_mul_f32_e32 v222, v222, v222
	v_mul_f32_e32 v249, v249, v249
	v_mul_f32_e32 v223, v223, v223
	v_mul_f32_e32 v248, v248, v248
	v_cvt_pk_bf16_f32 v222, v222, v249
	v_cvt_pk_bf16_f32 v223, v223, v248
	s_add_u32 s30, s92, 0x400800
	s_addc_u32 s31, s93, 0
	s_nop 0
	v_permlane16_swap_b32_e32 v220, v222
	v_permlane16_swap_b32_e32 v221, v223
	global_store_dwordx4 v229, v[220:223], s[30:31]
	v_mul_f32_e32 v224, v80, v231
	v_mul_f32_e32 v249, v81, v231
	v_mul_f32_e32 v225, v82, v231
	v_mul_f32_e32 v248, v83, v231
	v_max_f32_e32 v224, 0, v224
	v_max_f32_e32 v249, 0, v249
	v_max_f32_e32 v225, 0, v225
	v_max_f32_e32 v248, 0, v248
	v_mul_f32_e32 v224, v224, v224
	v_mul_f32_e32 v249, v249, v249
	v_mul_f32_e32 v225, v225, v225
	v_mul_f32_e32 v248, v248, v248
	v_cvt_pk_bf16_f32 v224, v224, v249
	v_cvt_pk_bf16_f32 v225, v225, v248
	v_mul_f32_e32 v226, v56, v231
	v_mul_f32_e32 v249, v57, v231
	v_mul_f32_e32 v227, v58, v231
	v_mul_f32_e32 v248, v59, v231
	v_max_f32_e32 v226, 0, v226
	v_max_f32_e32 v249, 0, v249
	v_max_f32_e32 v227, 0, v227
	v_max_f32_e32 v248, 0, v248
	v_mul_f32_e32 v226, v226, v226
	v_mul_f32_e32 v249, v249, v249
	v_mul_f32_e32 v227, v227, v227
	v_mul_f32_e32 v248, v248, v248
	v_cvt_pk_bf16_f32 v226, v226, v249
	v_cvt_pk_bf16_f32 v227, v227, v248
	s_add_u32 s30, s92, 0x600800
	s_addc_u32 s31, s93, 0
	s_nop 0
	v_permlane16_swap_b32_e32 v224, v226
	v_permlane16_swap_b32_e32 v225, v227
	global_store_dwordx4 v229, v[224:227], s[30:31]
	s_waitcnt vmcnt(12)
	v_add_f32_e32 v231, v186, v187
	v_add_f32_e32 v248, v188, v189
	v_add_f32_e32 v231, v231, v248
	v_add_f32_e32 v249, v190, v191
	v_add_f32_e32 v248, v192, v193
	v_add_f32_e32 v249, v249, v248
	v_add_f32_e32 v231, v231, v249
	v_add_f32_e32 v249, v194, v195
	v_add_f32_e32 v248, v196, v197
	v_add_f32_e32 v249, v249, v248
	v_add_f32_e32 v231, v231, v249
	v_add_f32_e32 v249, v208, v209
	v_add_f32_e32 v248, v210, v211
	v_add_f32_e32 v249, v249, v248
	v_add_f32_e32 v231, v231, v249
	v_fmamk_f32 v231, v231, 0x3a800000, v199
	v_cmp_gt_f32_e32 vcc, s73, v231
	v_mul_f32_e32 v248, 0x4b800000, v231
	s_nop 0
	v_cndmask_b32_e32 v231, v231, v248, vcc
	v_rsq_f32_e32 v231, v231
	s_nop 0
	v_mul_f32_e32 v248, 0x45800000, v231
	v_cndmask_b32_e32 v231, v231, v248, vcc
	v_mul_f32_e32 v212, v132, v231
	v_mul_f32_e32 v249, v133, v231
	v_mul_f32_e32 v213, v134, v231
	v_mul_f32_e32 v248, v135, v231
	v_max_f32_e32 v212, 0, v212
	v_max_f32_e32 v249, 0, v249
	v_max_f32_e32 v213, 0, v213
	v_max_f32_e32 v248, 0, v248
	v_mul_f32_e32 v212, v212, v212
	v_mul_f32_e32 v249, v249, v249
	v_mul_f32_e32 v213, v213, v213
	v_mul_f32_e32 v248, v248, v248
	v_cvt_pk_bf16_f32 v212, v212, v249
	v_cvt_pk_bf16_f32 v213, v213, v248
	v_mul_f32_e32 v214, v136, v231
	v_mul_f32_e32 v249, v137, v231
	v_mul_f32_e32 v215, v138, v231
	v_mul_f32_e32 v248, v139, v231
	v_max_f32_e32 v214, 0, v214
	v_max_f32_e32 v249, 0, v249
	v_max_f32_e32 v215, 0, v215
	v_max_f32_e32 v248, 0, v248
	v_mul_f32_e32 v214, v214, v214
	v_mul_f32_e32 v249, v249, v249
	v_mul_f32_e32 v215, v215, v215
	v_mul_f32_e32 v248, v248, v248
	v_cvt_pk_bf16_f32 v214, v214, v249
	v_cvt_pk_bf16_f32 v215, v215, v248
	s_add_u32 s30, s92, 0xc00
	s_addc_u32 s31, s93, 0
	s_nop 0
	v_permlane16_swap_b32_e32 v212, v214
	v_permlane16_swap_b32_e32 v213, v215
	global_store_dwordx4 v229, v[212:215], s[30:31]
	v_mul_f32_e32 v216, v140, v231
	v_mul_f32_e32 v249, v141, v231
	v_mul_f32_e32 v217, v142, v231
	v_mul_f32_e32 v248, v143, v231
	v_max_f32_e32 v216, 0, v216
	v_max_f32_e32 v249, 0, v249
	v_max_f32_e32 v217, 0, v217
	v_max_f32_e32 v248, 0, v248
	v_mul_f32_e32 v216, v216, v216
	v_mul_f32_e32 v249, v249, v249
	v_mul_f32_e32 v217, v217, v217
	v_mul_f32_e32 v248, v248, v248
	v_cvt_pk_bf16_f32 v216, v216, v249
	v_cvt_pk_bf16_f32 v217, v217, v248
	v_mul_f32_e32 v218, v144, v231
	v_mul_f32_e32 v249, v145, v231
	v_mul_f32_e32 v219, v146, v231
	v_mul_f32_e32 v248, v147, v231
	v_max_f32_e32 v218, 0, v218
	v_max_f32_e32 v249, 0, v249
	v_max_f32_e32 v219, 0, v219
	v_max_f32_e32 v248, 0, v248
	v_mul_f32_e32 v218, v218, v218
	v_mul_f32_e32 v249, v249, v249
	v_mul_f32_e32 v219, v219, v219
	v_mul_f32_e32 v248, v248, v248
	v_cvt_pk_bf16_f32 v218, v218, v249
	v_cvt_pk_bf16_f32 v219, v219, v248
	s_add_u32 s30, s92, 0x200c00
	s_addc_u32 s31, s93, 0
	s_nop 0
	v_permlane16_swap_b32_e32 v216, v218
	v_permlane16_swap_b32_e32 v217, v219
	global_store_dwordx4 v229, v[216:219], s[30:31]
	v_mul_f32_e32 v220, v76, v231
	v_mul_f32_e32 v249, v77, v231
	v_mul_f32_e32 v221, v78, v231
	v_mul_f32_e32 v248, v79, v231
	v_max_f32_e32 v220, 0, v220
	v_max_f32_e32 v249, 0, v249
	v_max_f32_e32 v221, 0, v221
	v_max_f32_e32 v248, 0, v248
	v_mul_f32_e32 v220, v220, v220
	v_mul_f32_e32 v249, v249, v249
	v_mul_f32_e32 v221, v221, v221
	v_mul_f32_e32 v248, v248, v248
	v_cvt_pk_bf16_f32 v220, v220, v249
	v_cvt_pk_bf16_f32 v221, v221, v248
	v_mul_f32_e32 v222, v72, v231
	v_mul_f32_e32 v249, v73, v231
	v_mul_f32_e32 v223, v74, v231
	v_mul_f32_e32 v248, v75, v231
	v_max_f32_e32 v222, 0, v222
	v_max_f32_e32 v249, 0, v249
	v_max_f32_e32 v223, 0, v223
	v_max_f32_e32 v248, 0, v248
	v_mul_f32_e32 v222, v222, v222
	v_mul_f32_e32 v249, v249, v249
	v_mul_f32_e32 v223, v223, v223
	v_mul_f32_e32 v248, v248, v248
	v_cvt_pk_bf16_f32 v222, v222, v249
	v_cvt_pk_bf16_f32 v223, v223, v248
	s_add_u32 s30, s92, 0x400c00
	s_addc_u32 s31, s93, 0
	s_nop 0
	v_permlane16_swap_b32_e32 v220, v222
	v_permlane16_swap_b32_e32 v221, v223
	global_store_dwordx4 v229, v[220:223], s[30:31]
	v_mul_f32_e32 v224, v60, v231
	v_mul_f32_e32 v249, v61, v231
	v_mul_f32_e32 v225, v62, v231
	v_mul_f32_e32 v248, v63, v231
	v_max_f32_e32 v224, 0, v224
	v_max_f32_e32 v249, 0, v249
	v_max_f32_e32 v225, 0, v225
	v_max_f32_e32 v248, 0, v248
	v_mul_f32_e32 v224, v224, v224
	v_mul_f32_e32 v249, v249, v249
	v_mul_f32_e32 v225, v225, v225
	v_mul_f32_e32 v248, v248, v248
	v_cvt_pk_bf16_f32 v224, v224, v249
	v_cvt_pk_bf16_f32 v225, v225, v248
	v_mul_f32_e32 v226, v148, v231
	v_mul_f32_e32 v249, v149, v231
	v_mul_f32_e32 v227, v150, v231
	v_mul_f32_e32 v248, v151, v231
	v_max_f32_e32 v226, 0, v226
	v_max_f32_e32 v249, 0, v249
	v_max_f32_e32 v227, 0, v227
	v_max_f32_e32 v248, 0, v248
	v_mul_f32_e32 v226, v226, v226
	v_mul_f32_e32 v249, v249, v249
	v_mul_f32_e32 v227, v227, v227
	v_mul_f32_e32 v248, v248, v248
	v_cvt_pk_bf16_f32 v226, v226, v249
	v_cvt_pk_bf16_f32 v227, v227, v248
	s_add_u32 s30, s92, 0x600c00
	s_addc_u32 s31, s93, 0
	s_nop 0
	v_permlane16_swap_b32_e32 v224, v226
	v_permlane16_swap_b32_e32 v225, v227
	global_store_dwordx4 v229, v[224:227], s[30:31]
	s_cmp_lg_u32 s23, 0
	s_cbranch_scc0 .LBB0_13

.LBB0_24:
	s_lshr_b32 s10, s18, 2
	s_and_b32 s10, s10, 24
	s_and_b32 s11, s18, 7
	s_or_b32 s10, s10, s11
	s_lshl_b32 s10, s10, 10
	v_mov_b32 v8, v198
	s_or_b32 s10, s10, s65
	v_ashrrev_i32_e32 v12, 2, v8
	v_add_u32_e32 v0, s10, v12
	s_waitcnt lgkmcnt(0)
	v_ashrrev_i32_e32 v1, 31, v0
	s_lshl_b32 s11, s18, 5
	v_lshlrev_b64 v[0:1], 11, v[0:1]
	v_lshlrev_b32_e32 v2, 4, v8
	s_and_b32 s11, s11, 0x300
	v_lshl_add_u64 v[0:1], s[96:97], 0, v[0:1]
	v_and_b32_e32 v152, 48, v2
	v_lshl_add_u64 v[14:15], v[0:1], 0, v[152:153]
	v_add_u32_e32 v0, s11, v12
	v_ashrrev_i32_e32 v1, 31, v0
	v_lshlrev_b64 v[0:1], 6, v[0:1]
	v_lshl_add_u64 v[0:1], s[4:5], 0, v[0:1]
	v_add_co_u32_e32 v54, vcc, s62, v14
	v_lshl_add_u64 v[0:1], v[0:1], 0, v[152:153]
	s_nop 0
	v_addc_co_u32_e32 v55, vcc, 0, v15, vcc
	s_lshl_b32 s20, s17, 11
	s_lshl_b32 s21, s18, 8
	s_and_b32 s22, s16, 7
	v_add_co_u32_e32 v2, vcc, s62, v0
	s_and_b32 s20, s20, 0x180000
	s_and_b32 s23, s21, 0x6000
	s_lshl_b32 s22, s22, 10
	v_lshrrev_b32_e32 v6, 2, v8
	v_addc_co_u32_e32 v3, vcc, 0, v1, vcc
	v_and_b32_e32 v6, 12, v6
	v_ashrrev_i32_e32 v13, 31, v12
	s_movk_i32 s21, 0x1230
	s_add_u32 s20, s13, s20
	v_add_co_u32_e32 v4, vcc, s33, v0
	v_lshrrev_b32_e64 v10, v6, s21
	v_lshlrev_b64 v[6:7], 11, v[12:13]
	s_addc_u32 s21, s14, 0
	s_or_b32 s22, s22, s23
	v_addc_co_u32_e32 v5, vcc, 0, v1, vcc
	v_and_b32_e32 v22, 3, v8
	v_xor_b32_e32 v8, v10, v8
	v_lshl_add_u64 v[156:157], s[20:21], 0, v[6:7]
	s_or_b32 s20, s22, s65
	v_add_co_u32_e32 v20, vcc, s72, v0
	v_lshlrev_b32_e32 v9, 6, v12
	v_lshlrev_b32_e32 v8, 4, v8
	v_add_u32_e32 v12, s20, v12
	v_addc_co_u32_e32 v21, vcc, 0, v1, vcc
	s_nop 0
	v_readfirstlane_b32 s26, v14
	v_readfirstlane_b32 s27, v15
	v_readfirstlane_b32 s28, v0
	v_readfirstlane_b32 s29, v1
	v_lshrrev_b32_e32 v250, 6, v198
	s_nop 0
	v_readfirstlane_b32 s24, v250
	s_lshl_b32 s24, s24, 10
	v_lshrrev_b32_e32 v250, 2, v200
	v_lshrrev_b32_e32 v251, 4, v200
	v_lshlrev_b32_e32 v251, 2, v251
	v_mov_b32_e32 v248, 0x1230
	v_lshrrev_b32_e32 v251, v251, v248
	v_xor_b32_e32 v251, v251, v200
	v_and_b32_e32 v251, 3, v251
	v_lshlrev_b32_e32 v251, 4, v251
	v_lshl_add_u32 v244, v250, 11, v251
	v_add_u32_e32 v245, 0x20000, v244
	v_add_u32_e32 v246, 0x40000, v244
	v_add_u32_e32 v247, 0x60000, v244
	v_lshl_add_u32 v156, v250, 6, v251
	v_add_u32_e32 v157, 0x1000, v156
	v_add_u32_e32 v158, 0x2000, v156
	v_add_u32_e32 v159, 0x3000, v156
	s_mov_b32 s25, 0
	s_add_u32 m0, s25, s24
	s_nop 0
	global_load_lds_dwordx4 v244, s[26:27]
	s_add_u32 m0, m0, 0x1000
	s_nop 0
	global_load_lds_dwordx4 v245, s[26:27]
	s_add_u32 m0, m0, 0x1000
	s_nop 0
	global_load_lds_dwordx4 v156, s[28:29]
	s_add_u32 m0, m0, 0x1000
	s_nop 0
	global_load_lds_dwordx4 v157, s[28:29]
	s_add_u32 m0, m0, 0x1000
	s_nop 0
	global_load_lds_dwordx4 v158, s[28:29]
	s_add_u32 m0, m0, 0x1000
	s_nop 0
	global_load_lds_dwordx4 v159, s[28:29]
	s_add_u32 s26, s26, 0x40
	s_addc_u32 s27, s27, 0
	s_add_u32 s28, s28, 0x10000
	s_addc_u32 s29, s29, 0
	s_add_u32 s25, s25, 24576
	s_cmp_eq_u32 s25, 73728
	s_cselect_b32 s25, 0, s25
	s_add_u32 m0, s25, s24
	s_nop 0
	global_load_lds_dwordx4 v244, s[26:27]
	s_add_u32 m0, m0, 0x1000
	s_nop 0
	global_load_lds_dwordx4 v245, s[26:27]
	s_add_u32 m0, m0, 0x1000
	s_nop 0
	global_load_lds_dwordx4 v156, s[28:29]
	s_add_u32 m0, m0, 0x1000
	s_nop 0
	global_load_lds_dwordx4 v157, s[28:29]
	s_add_u32 m0, m0, 0x1000
	s_nop 0
	global_load_lds_dwordx4 v158, s[28:29]
	s_add_u32 m0, m0, 0x1000
	s_nop 0
	global_load_lds_dwordx4 v159, s[28:29]
	s_add_u32 s26, s26, 0x40
	s_addc_u32 s27, s27, 0
	s_add_u32 s28, s28, 0x10000
	s_addc_u32 s29, s29, 0
	s_add_u32 s25, s25, 24576
	s_cmp_eq_u32 s25, 73728
	s_cselect_b32 s25, 0, s25
	s_add_u32 m0, s25, s24
	s_nop 0
	global_load_lds_dwordx4 v244, s[26:27]
	s_add_u32 m0, m0, 0x1000
	s_nop 0
	global_load_lds_dwordx4 v245, s[26:27]
	s_add_u32 m0, m0, 0x1000
	s_nop 0
	global_load_lds_dwordx4 v156, s[28:29]
	s_add_u32 m0, m0, 0x1000
	s_nop 0
	global_load_lds_dwordx4 v157, s[28:29]
	s_add_u32 m0, m0, 0x1000
	s_nop 0
	global_load_lds_dwordx4 v158, s[28:29]
	s_add_u32 m0, m0, 0x1000
	s_nop 0
	global_load_lds_dwordx4 v159, s[28:29]
	s_add_u32 s26, s26, 0x40
	s_addc_u32 s27, s27, 0
	s_add_u32 s28, s28, 0x10000
	s_addc_u32 s29, s29, 0
	s_add_u32 s25, s25, 24576
	s_cmp_eq_u32 s25, 73728
	s_cselect_b32 s25, 0, s25
	v_mov_b32_e32 v24, 0
	v_mov_b32_e32 v25, v24
	v_mov_b32_e32 v26, v24
	v_mov_b32_e32 v27, v24
	v_mov_b32_e32 v28, v24
	v_mov_b32_e32 v29, v24
	v_mov_b32_e32 v60, v24
	v_mov_b32_e32 v61, v24
	v_mov_b32_e32 v62, v24
	v_mov_b32_e32 v63, v24
	v_mov_b32_e32 v64, v24
	v_mov_b32_e32 v65, v24
	v_mov_b32_e32 v66, v24
	v_mov_b32_e32 v67, v24
	v_mov_b32_e32 v72, v24
	v_mov_b32_e32 v73, v24
	v_mov_b32_e32 v74, v24
	v_mov_b32_e32 v75, v24
	v_mov_b32_e32 v80, v24
	v_mov_b32_e32 v81, v24
	v_mov_b32_e32 v82, v24
	v_mov_b32_e32 v83, v24
	v_mov_b32_e32 v56, v24
	v_mov_b32_e32 v57, v24
	v_mov_b32_e32 v58, v24
	v_mov_b32_e32 v59, v24
	v_mov_b32_e32 v68, v24
	v_mov_b32_e32 v69, v24
	v_mov_b32_e32 v30, v24
	v_mov_b32_e32 v31, v24
	v_mov_b32_e32 v32, v24
	v_mov_b32_e32 v33, v24
	v_mov_b32_e32 v34, v24
	v_mov_b32_e32 v35, v24
	v_mov_b32_e32 v36, v24
	v_mov_b32_e32 v37, v24
	v_mov_b32_e32 v38, v24
	v_mov_b32_e32 v39, v24
	v_mov_b32_e32 v40, v24
	v_mov_b32_e32 v41, v24
	v_mov_b32_e32 v42, v24
	v_mov_b32_e32 v43, v24
	v_mov_b32_e32 v48, v24
	v_mov_b32_e32 v49, v24
	v_mov_b32_e32 v50, v24
	v_mov_b32_e32 v51, v24
	v_mov_b32_e32 v70, v24
	v_mov_b32_e32 v71, v24
	v_mov_b32_e32 v100, v24
	v_mov_b32_e32 v101, v24
	v_mov_b32_e32 v102, v24
	v_mov_b32_e32 v103, v24
	v_mov_b32_e32 v104, v24
	v_mov_b32_e32 v105, v24
	v_mov_b32_e32 v106, v24
	v_mov_b32_e32 v107, v24
	v_mov_b32_e32 v120, v24
	v_mov_b32_e32 v121, v24
	v_mov_b32_e32 v122, v24
	v_mov_b32_e32 v123, v24
	v_mov_b32_e32 v128, v24
	v_mov_b32_e32 v129, v24
	v_mov_b32_e32 v130, v24
	v_mov_b32_e32 v131, v24
	v_mov_b32_e32 v108, v24
	v_mov_b32_e32 v109, v24
	v_mov_b32_e32 v110, v24
	v_mov_b32_e32 v111, v24
	v_mov_b32_e32 v112, v24
	v_mov_b32_e32 v113, v24
	v_mov_b32_e32 v114, v24
	v_mov_b32_e32 v115, v24
	v_mov_b32_e32 v116, v24
	v_mov_b32_e32 v117, v24
	v_mov_b32_e32 v118, v24
	v_mov_b32_e32 v119, v24
	v_mov_b32_e32 v124, v24
	v_mov_b32_e32 v125, v24
	v_mov_b32_e32 v126, v24
	v_mov_b32_e32 v127, v24
	v_mov_b32_e32 v88, v24
	v_mov_b32_e32 v89, v24
	v_mov_b32_e32 v90, v24
	v_mov_b32_e32 v91, v24
	v_mov_b32_e32 v92, v24
	v_mov_b32_e32 v93, v24
	v_mov_b32_e32 v94, v24
	v_mov_b32_e32 v95, v24
	v_mov_b32_e32 v96, v24
	v_mov_b32_e32 v97, v24
	v_mov_b32_e32 v98, v24
	v_mov_b32_e32 v99, v24
	v_mov_b32_e32 v84, v24
	v_mov_b32_e32 v85, v24
	v_mov_b32_e32 v86, v24
	v_mov_b32_e32 v87, v24
	v_mov_b32_e32 v132, v24
	v_mov_b32_e32 v133, v24
	v_mov_b32_e32 v134, v24
	v_mov_b32_e32 v135, v24
	v_mov_b32_e32 v136, v24
	v_mov_b32_e32 v137, v24
	v_mov_b32_e32 v138, v24
	v_mov_b32_e32 v139, v24
	v_mov_b32_e32 v140, v24
	v_mov_b32_e32 v141, v24
	v_mov_b32_e32 v142, v24
	v_mov_b32_e32 v143, v24
	v_mov_b32_e32 v144, v24
	v_mov_b32_e32 v145, v24
	v_mov_b32_e32 v146, v24
	v_mov_b32_e32 v147, v24
	v_mov_b32_e32 v76, v24
	v_mov_b32_e32 v77, v24
	v_mov_b32_e32 v78, v24
	v_mov_b32_e32 v79, v24
	v_mov_b32_e32 v52, v24
	v_mov_b32_e32 v53, v24
	v_mov_b32_e32 v54, v24
	v_mov_b32_e32 v55, v24
	v_mov_b32_e32 v44, v24
	v_mov_b32_e32 v45, v24
	v_mov_b32_e32 v46, v24
	v_mov_b32_e32 v47, v24
	v_mov_b32_e32 v148, v24
	v_mov_b32_e32 v149, v24
	v_mov_b32_e32 v150, v24
	v_mov_b32_e32 v151, v24
	s_waitcnt vmcnt(12)
	s_barrier
	s_mov_b32 s30, 0
	v_add_u32_e32 v248, s30, v155
	v_add_u32_e32 v249, s30, v160
	ds_read_b128 v[186:189], v248
	ds_read_b128 v[212:215], v249 offset:8192
	ds_read_b128 v[190:193], v248 offset:1024
	ds_read_b128 v[216:219], v249 offset:9216
	ds_read_b128 v[194:197], v248 offset:2048
	ds_read_b128 v[220:223], v249 offset:10240
	ds_read_b128 v[208:211], v248 offset:3072
	ds_read_b128 v[224:227], v249 offset:11264
	ds_read_b128 v[228:231], v249 offset:12288
	ds_read_b128 v[232:235], v249 offset:13312
	ds_read_b128 v[236:239], v249 offset:14336
	ds_read_b128 v[240:243], v249 offset:15360
	s_add_u32 s30, s30, 24576
	s_cmp_eq_u32 s30, 73728
	s_cselect_b32 s30, 0, s30
	s_waitcnt vmcnt(6)
	s_waitcnt lgkmcnt(0)
	s_barrier
	s_mov_b32 s31, 14
.Lgm1_loop:
	v_add_u32_e32 v248, s30, v155
	v_add_u32_e32 v249, s30, v160
	v_mfma_f32_16x16x32_bf16 v[128:131], v[212:215], v[186:189], v[128:131]
	ds_read_b128 v[0:3], v248
	v_mfma_f32_16x16x32_bf16 v[80:83], v[212:215], v[190:193], v[80:83]
	ds_read_b128 v[16:19], v249 offset:8192
	v_mfma_f32_16x16x32_bf16 v[108:111], v[212:215], v[194:197], v[108:111]
	ds_read_b128 v[4:7], v248 offset:1024
	v_mfma_f32_16x16x32_bf16 v[132:135], v[212:215], v[208:211], v[132:135]
	ds_read_b128 v[20:23], v249 offset:9216
	v_mfma_f32_16x16x32_bf16 v[120:123], v[216:219], v[186:189], v[120:123]
	ds_read_b128 v[8:11], v248 offset:2048
	v_mfma_f32_16x16x32_bf16 v[72:75], v[216:219], v[190:193], v[72:75]
	ds_read_b128 v[162:165], v249 offset:10240
	v_mfma_f32_16x16x32_bf16 v[112:115], v[216:219], v[194:197], v[112:115]
	ds_read_b128 v[12:15], v248 offset:3072
	v_mfma_f32_16x16x32_bf16 v[136:139], v[216:219], v[208:211], v[136:139]
	ds_read_b128 v[166:169], v249 offset:11264
	v_mfma_f32_16x16x32_bf16 v[104:107], v[220:223], v[186:189], v[104:107]
	ds_read_b128 v[170:173], v249 offset:12288
	v_mfma_f32_16x16x32_bf16 v[64:67], v[220:223], v[190:193], v[64:67]
	ds_read_b128 v[174:177], v249 offset:13312
	v_mfma_f32_16x16x32_bf16 v[116:119], v[220:223], v[194:197], v[116:119]
	ds_read_b128 v[178:181], v249 offset:14336
	v_mfma_f32_16x16x32_bf16 v[140:143], v[220:223], v[208:211], v[140:143]
	ds_read_b128 v[182:185], v249 offset:15360
	s_add_u32 m0, s25, s24
	v_mfma_f32_16x16x32_bf16 v[100:103], v[224:227], v[186:189], v[100:103]
	global_load_lds_dwordx4 v244, s[26:27]
	v_mfma_f32_16x16x32_bf16 v[60:63], v[224:227], v[190:193], v[60:63]
	v_mfma_f32_16x16x32_bf16 v[124:127], v[224:227], v[194:197], v[124:127]
	s_add_u32 m0, m0, 0x1000
	v_mfma_f32_16x16x32_bf16 v[144:147], v[224:227], v[208:211], v[144:147]
	global_load_lds_dwordx4 v245, s[26:27]
	v_mfma_f32_16x16x32_bf16 v[68:71], v[228:231], v[186:189], v[68:71]
	v_mfma_f32_16x16x32_bf16 v[36:39], v[228:231], v[190:193], v[36:39]
	s_add_u32 m0, m0, 0x1000
	v_mfma_f32_16x16x32_bf16 v[88:91], v[228:231], v[194:197], v[88:91]
	global_load_lds_dwordx4 v156, s[28:29]
	v_mfma_f32_16x16x32_bf16 v[76:79], v[228:231], v[208:211], v[76:79]
	v_mfma_f32_16x16x32_bf16 v[56:59], v[232:235], v[186:189], v[56:59]
	s_add_u32 m0, m0, 0x1000
	v_mfma_f32_16x16x32_bf16 v[32:35], v[232:235], v[190:193], v[32:35]
	global_load_lds_dwordx4 v157, s[28:29]
	v_mfma_f32_16x16x32_bf16 v[92:95], v[232:235], v[194:197], v[92:95]
	v_mfma_f32_16x16x32_bf16 v[52:55], v[232:235], v[208:211], v[52:55]
	s_add_u32 m0, m0, 0x1000
	v_mfma_f32_16x16x32_bf16 v[48:51], v[236:239], v[186:189], v[48:51]
	global_load_lds_dwordx4 v158, s[28:29]
	v_mfma_f32_16x16x32_bf16 v[28:31], v[236:239], v[190:193], v[28:31]
	v_mfma_f32_16x16x32_bf16 v[96:99], v[236:239], v[194:197], v[96:99]
	s_add_u32 m0, m0, 0x1000
	v_mfma_f32_16x16x32_bf16 v[44:47], v[236:239], v[208:211], v[44:47]
	global_load_lds_dwordx4 v159, s[28:29]
	v_mfma_f32_16x16x32_bf16 v[40:43], v[240:243], v[186:189], v[40:43]
	v_mfma_f32_16x16x32_bf16 v[24:27], v[240:243], v[190:193], v[24:27]
	v_mfma_f32_16x16x32_bf16 v[84:87], v[240:243], v[194:197], v[84:87]
	v_mfma_f32_16x16x32_bf16 v[148:151], v[240:243], v[208:211], v[148:151]
	s_add_u32 s26, s26, 0x40
	s_addc_u32 s27, s27, 0
	s_add_u32 s28, s28, 0x10000
	s_addc_u32 s29, s29, 0
	s_add_u32 s25, s25, 24576
	s_cmp_eq_u32 s25, 73728
	s_cselect_b32 s25, 0, s25
	s_add_u32 s30, s30, 24576
	s_cmp_eq_u32 s30, 73728
	s_cselect_b32 s30, 0, s30
	s_waitcnt vmcnt(6)
	s_waitcnt lgkmcnt(0)
	s_barrier
	v_add_u32_e32 v248, s30, v155
	v_add_u32_e32 v249, s30, v160
	v_mfma_f32_16x16x32_bf16 v[128:131], v[16:19], v[0:3], v[128:131]
	ds_read_b128 v[186:189], v248
	v_mfma_f32_16x16x32_bf16 v[80:83], v[16:19], v[4:7], v[80:83]
	ds_read_b128 v[212:215], v249 offset:8192
	v_mfma_f32_16x16x32_bf16 v[108:111], v[16:19], v[8:11], v[108:111]
	ds_read_b128 v[190:193], v248 offset:1024
	v_mfma_f32_16x16x32_bf16 v[132:135], v[16:19], v[12:15], v[132:135]
	ds_read_b128 v[216:219], v249 offset:9216
	v_mfma_f32_16x16x32_bf16 v[120:123], v[20:23], v[0:3], v[120:123]
	ds_read_b128 v[194:197], v248 offset:2048
	v_mfma_f32_16x16x32_bf16 v[72:75], v[20:23], v[4:7], v[72:75]
	ds_read_b128 v[220:223], v249 offset:10240
	v_mfma_f32_16x16x32_bf16 v[112:115], v[20:23], v[8:11], v[112:115]
	ds_read_b128 v[208:211], v248 offset:3072
	v_mfma_f32_16x16x32_bf16 v[136:139], v[20:23], v[12:15], v[136:139]
	ds_read_b128 v[224:227], v249 offset:11264
	v_mfma_f32_16x16x32_bf16 v[104:107], v[162:165], v[0:3], v[104:107]
	ds_read_b128 v[228:231], v249 offset:12288
	v_mfma_f32_16x16x32_bf16 v[64:67], v[162:165], v[4:7], v[64:67]
	ds_read_b128 v[232:235], v249 offset:13312
	v_mfma_f32_16x16x32_bf16 v[116:119], v[162:165], v[8:11], v[116:119]
	ds_read_b128 v[236:239], v249 offset:14336
	v_mfma_f32_16x16x32_bf16 v[140:143], v[162:165], v[12:15], v[140:143]
	ds_read_b128 v[240:243], v249 offset:15360
	s_add_u32 m0, s25, s24
	v_mfma_f32_16x16x32_bf16 v[100:103], v[166:169], v[0:3], v[100:103]
	global_load_lds_dwordx4 v244, s[26:27]
	v_mfma_f32_16x16x32_bf16 v[60:63], v[166:169], v[4:7], v[60:63]
	v_mfma_f32_16x16x32_bf16 v[124:127], v[166:169], v[8:11], v[124:127]
	s_add_u32 m0, m0, 0x1000
	v_mfma_f32_16x16x32_bf16 v[144:147], v[166:169], v[12:15], v[144:147]
	global_load_lds_dwordx4 v245, s[26:27]
	v_mfma_f32_16x16x32_bf16 v[68:71], v[170:173], v[0:3], v[68:71]
	v_mfma_f32_16x16x32_bf16 v[36:39], v[170:173], v[4:7], v[36:39]
	s_add_u32 m0, m0, 0x1000
	v_mfma_f32_16x16x32_bf16 v[88:91], v[170:173], v[8:11], v[88:91]
	global_load_lds_dwordx4 v156, s[28:29]
	v_mfma_f32_16x16x32_bf16 v[76:79], v[170:173], v[12:15], v[76:79]
	v_mfma_f32_16x16x32_bf16 v[56:59], v[174:177], v[0:3], v[56:59]
	s_add_u32 m0, m0, 0x1000
	v_mfma_f32_16x16x32_bf16 v[32:35], v[174:177], v[4:7], v[32:35]
	global_load_lds_dwordx4 v157, s[28:29]
	v_mfma_f32_16x16x32_bf16 v[92:95], v[174:177], v[8:11], v[92:95]
	v_mfma_f32_16x16x32_bf16 v[52:55], v[174:177], v[12:15], v[52:55]
	s_add_u32 m0, m0, 0x1000
	v_mfma_f32_16x16x32_bf16 v[48:51], v[178:181], v[0:3], v[48:51]
	global_load_lds_dwordx4 v158, s[28:29]
	v_mfma_f32_16x16x32_bf16 v[28:31], v[178:181], v[4:7], v[28:31]
	v_mfma_f32_16x16x32_bf16 v[96:99], v[178:181], v[8:11], v[96:99]
	s_add_u32 m0, m0, 0x1000
	v_mfma_f32_16x16x32_bf16 v[44:47], v[178:181], v[12:15], v[44:47]
	global_load_lds_dwordx4 v159, s[28:29]
	v_mfma_f32_16x16x32_bf16 v[40:43], v[182:185], v[0:3], v[40:43]
	v_mfma_f32_16x16x32_bf16 v[24:27], v[182:185], v[4:7], v[24:27]
	v_mfma_f32_16x16x32_bf16 v[84:87], v[182:185], v[8:11], v[84:87]
	v_mfma_f32_16x16x32_bf16 v[148:151], v[182:185], v[12:15], v[148:151]
	s_add_u32 s26, s26, 0x40
	s_addc_u32 s27, s27, 0
	s_add_u32 s28, s28, 0x10000
	s_addc_u32 s29, s29, 0
	s_add_u32 s25, s25, 24576
	s_cmp_eq_u32 s25, 73728
	s_cselect_b32 s25, 0, s25
	s_add_u32 s30, s30, 24576
	s_cmp_eq_u32 s30, 73728
	s_cselect_b32 s30, 0, s30
	s_waitcnt vmcnt(6)
	s_waitcnt lgkmcnt(0)
	s_barrier
	s_sub_u32 s31, s31, 1
	s_cmp_lg_u32 s31, 0
	s_cbranch_scc1 .Lgm1_loop
	v_add_u32_e32 v248, s30, v155
	v_add_u32_e32 v249, s30, v160
	v_mfma_f32_16x16x32_bf16 v[128:131], v[212:215], v[186:189], v[128:131]
	ds_read_b128 v[0:3], v248
	v_mfma_f32_16x16x32_bf16 v[80:83], v[212:215], v[190:193], v[80:83]
	ds_read_b128 v[16:19], v249 offset:8192
	v_mfma_f32_16x16x32_bf16 v[108:111], v[212:215], v[194:197], v[108:111]
	ds_read_b128 v[4:7], v248 offset:1024
	v_mfma_f32_16x16x32_bf16 v[132:135], v[212:215], v[208:211], v[132:135]
	ds_read_b128 v[20:23], v249 offset:9216
	v_mfma_f32_16x16x32_bf16 v[120:123], v[216:219], v[186:189], v[120:123]
	ds_read_b128 v[8:11], v248 offset:2048
	v_mfma_f32_16x16x32_bf16 v[72:75], v[216:219], v[190:193], v[72:75]
	ds_read_b128 v[162:165], v249 offset:10240
	v_mfma_f32_16x16x32_bf16 v[112:115], v[216:219], v[194:197], v[112:115]
	ds_read_b128 v[12:15], v248 offset:3072
	v_mfma_f32_16x16x32_bf16 v[136:139], v[216:219], v[208:211], v[136:139]
	ds_read_b128 v[166:169], v249 offset:11264
	v_mfma_f32_16x16x32_bf16 v[104:107], v[220:223], v[186:189], v[104:107]
	ds_read_b128 v[170:173], v249 offset:12288
	v_mfma_f32_16x16x32_bf16 v[64:67], v[220:223], v[190:193], v[64:67]
	ds_read_b128 v[174:177], v249 offset:13312
	v_mfma_f32_16x16x32_bf16 v[116:119], v[220:223], v[194:197], v[116:119]
	ds_read_b128 v[178:181], v249 offset:14336
	v_mfma_f32_16x16x32_bf16 v[140:143], v[220:223], v[208:211], v[140:143]
	ds_read_b128 v[182:185], v249 offset:15360
	s_add_u32 m0, s25, s24
	v_mfma_f32_16x16x32_bf16 v[100:103], v[224:227], v[186:189], v[100:103]
	global_load_lds_dwordx4 v244, s[26:27]
	v_mfma_f32_16x16x32_bf16 v[60:63], v[224:227], v[190:193], v[60:63]
	v_mfma_f32_16x16x32_bf16 v[124:127], v[224:227], v[194:197], v[124:127]
	s_add_u32 m0, m0, 0x1000
	v_mfma_f32_16x16x32_bf16 v[144:147], v[224:227], v[208:211], v[144:147]
	global_load_lds_dwordx4 v245, s[26:27]
	v_mfma_f32_16x16x32_bf16 v[68:71], v[228:231], v[186:189], v[68:71]
	v_mfma_f32_16x16x32_bf16 v[36:39], v[228:231], v[190:193], v[36:39]
	s_add_u32 m0, m0, 0x1000
	v_mfma_f32_16x16x32_bf16 v[88:91], v[228:231], v[194:197], v[88:91]
	global_load_lds_dwordx4 v156, s[28:29]
	v_mfma_f32_16x16x32_bf16 v[76:79], v[228:231], v[208:211], v[76:79]
	v_mfma_f32_16x16x32_bf16 v[56:59], v[232:235], v[186:189], v[56:59]
	s_add_u32 m0, m0, 0x1000
	v_mfma_f32_16x16x32_bf16 v[32:35], v[232:235], v[190:193], v[32:35]
	global_load_lds_dwordx4 v157, s[28:29]
	v_mfma_f32_16x16x32_bf16 v[92:95], v[232:235], v[194:197], v[92:95]
	v_mfma_f32_16x16x32_bf16 v[52:55], v[232:235], v[208:211], v[52:55]
	s_add_u32 m0, m0, 0x1000
	v_mfma_f32_16x16x32_bf16 v[48:51], v[236:239], v[186:189], v[48:51]
	global_load_lds_dwordx4 v158, s[28:29]
	v_mfma_f32_16x16x32_bf16 v[28:31], v[236:239], v[190:193], v[28:31]
	v_mfma_f32_16x16x32_bf16 v[96:99], v[236:239], v[194:197], v[96:99]
	s_add_u32 m0, m0, 0x1000
	v_mfma_f32_16x16x32_bf16 v[44:47], v[236:239], v[208:211], v[44:47]
	global_load_lds_dwordx4 v159, s[28:29]
	v_mfma_f32_16x16x32_bf16 v[40:43], v[240:243], v[186:189], v[40:43]
	v_mfma_f32_16x16x32_bf16 v[24:27], v[240:243], v[190:193], v[24:27]
	v_mfma_f32_16x16x32_bf16 v[84:87], v[240:243], v[194:197], v[84:87]
	v_mfma_f32_16x16x32_bf16 v[148:151], v[240:243], v[208:211], v[148:151]
	s_add_u32 s26, s26, 0x40
	s_addc_u32 s27, s27, 0
	s_add_u32 s28, s28, 0x10000
	s_addc_u32 s29, s29, 0
	s_add_u32 s25, s25, 24576
	s_cmp_eq_u32 s25, 73728
	s_cselect_b32 s25, 0, s25
	s_add_u32 s30, s30, 24576
	s_cmp_eq_u32 s30, 73728
	s_cselect_b32 s30, 0, s30
	s_waitcnt vmcnt(6)
	s_waitcnt lgkmcnt(0)
	s_barrier
	v_add_u32_e32 v248, s30, v155
	v_add_u32_e32 v249, s30, v160
	v_mfma_f32_16x16x32_bf16 v[128:131], v[16:19], v[0:3], v[128:131]
	ds_read_b128 v[186:189], v248
	v_mfma_f32_16x16x32_bf16 v[80:83], v[16:19], v[4:7], v[80:83]
	ds_read_b128 v[212:215], v249 offset:8192
	v_mfma_f32_16x16x32_bf16 v[108:111], v[16:19], v[8:11], v[108:111]
	ds_read_b128 v[190:193], v248 offset:1024
	v_mfma_f32_16x16x32_bf16 v[132:135], v[16:19], v[12:15], v[132:135]
	ds_read_b128 v[216:219], v249 offset:9216
	v_mfma_f32_16x16x32_bf16 v[120:123], v[20:23], v[0:3], v[120:123]
	ds_read_b128 v[194:197], v248 offset:2048
	v_mfma_f32_16x16x32_bf16 v[72:75], v[20:23], v[4:7], v[72:75]
	ds_read_b128 v[220:223], v249 offset:10240
	v_mfma_f32_16x16x32_bf16 v[112:115], v[20:23], v[8:11], v[112:115]
	ds_read_b128 v[208:211], v248 offset:3072
	v_mfma_f32_16x16x32_bf16 v[136:139], v[20:23], v[12:15], v[136:139]
	ds_read_b128 v[224:227], v249 offset:11264
	v_mfma_f32_16x16x32_bf16 v[104:107], v[162:165], v[0:3], v[104:107]
	ds_read_b128 v[228:231], v249 offset:12288
	v_mfma_f32_16x16x32_bf16 v[64:67], v[162:165], v[4:7], v[64:67]
	ds_read_b128 v[232:235], v249 offset:13312
	v_mfma_f32_16x16x32_bf16 v[116:119], v[162:165], v[8:11], v[116:119]
	ds_read_b128 v[236:239], v249 offset:14336
	v_mfma_f32_16x16x32_bf16 v[140:143], v[162:165], v[12:15], v[140:143]
	ds_read_b128 v[240:243], v249 offset:15360
	v_mfma_f32_16x16x32_bf16 v[100:103], v[166:169], v[0:3], v[100:103]
	v_mfma_f32_16x16x32_bf16 v[60:63], v[166:169], v[4:7], v[60:63]
	v_mfma_f32_16x16x32_bf16 v[124:127], v[166:169], v[8:11], v[124:127]
	v_mfma_f32_16x16x32_bf16 v[144:147], v[166:169], v[12:15], v[144:147]
	v_mfma_f32_16x16x32_bf16 v[68:71], v[170:173], v[0:3], v[68:71]
	v_mfma_f32_16x16x32_bf16 v[36:39], v[170:173], v[4:7], v[36:39]
	v_mfma_f32_16x16x32_bf16 v[88:91], v[170:173], v[8:11], v[88:91]
	v_mfma_f32_16x16x32_bf16 v[76:79], v[170:173], v[12:15], v[76:79]
	v_mfma_f32_16x16x32_bf16 v[56:59], v[174:177], v[0:3], v[56:59]
	v_mfma_f32_16x16x32_bf16 v[32:35], v[174:177], v[4:7], v[32:35]
	v_mfma_f32_16x16x32_bf16 v[92:95], v[174:177], v[8:11], v[92:95]
	v_mfma_f32_16x16x32_bf16 v[52:55], v[174:177], v[12:15], v[52:55]
	v_mfma_f32_16x16x32_bf16 v[48:51], v[178:181], v[0:3], v[48:51]
	v_mfma_f32_16x16x32_bf16 v[28:31], v[178:181], v[4:7], v[28:31]
	v_mfma_f32_16x16x32_bf16 v[96:99], v[178:181], v[8:11], v[96:99]
	v_mfma_f32_16x16x32_bf16 v[44:47], v[178:181], v[12:15], v[44:47]
	v_mfma_f32_16x16x32_bf16 v[40:43], v[182:185], v[0:3], v[40:43]
	v_mfma_f32_16x16x32_bf16 v[24:27], v[182:185], v[4:7], v[24:27]
	v_mfma_f32_16x16x32_bf16 v[84:87], v[182:185], v[8:11], v[84:87]
	v_mfma_f32_16x16x32_bf16 v[148:151], v[182:185], v[12:15], v[148:151]
	s_add_u32 s30, s30, 24576
	s_cmp_eq_u32 s30, 73728
	s_cselect_b32 s30, 0, s30
	s_waitcnt vmcnt(0)
	s_waitcnt lgkmcnt(0)
	s_barrier
	v_add_u32_e32 v248, s30, v155
	v_add_u32_e32 v249, s30, v160
	v_mfma_f32_16x16x32_bf16 v[128:131], v[212:215], v[186:189], v[128:131]
	ds_read_b128 v[0:3], v248
	v_mfma_f32_16x16x32_bf16 v[80:83], v[212:215], v[190:193], v[80:83]
	ds_read_b128 v[16:19], v249 offset:8192
	v_mfma_f32_16x16x32_bf16 v[108:111], v[212:215], v[194:197], v[108:111]
	ds_read_b128 v[4:7], v248 offset:1024
	v_mfma_f32_16x16x32_bf16 v[132:135], v[212:215], v[208:211], v[132:135]
	ds_read_b128 v[20:23], v249 offset:9216
	v_mfma_f32_16x16x32_bf16 v[120:123], v[216:219], v[186:189], v[120:123]
	ds_read_b128 v[8:11], v248 offset:2048
	v_mfma_f32_16x16x32_bf16 v[72:75], v[216:219], v[190:193], v[72:75]
	ds_read_b128 v[162:165], v249 offset:10240
	v_mfma_f32_16x16x32_bf16 v[112:115], v[216:219], v[194:197], v[112:115]
	ds_read_b128 v[12:15], v248 offset:3072
	v_mfma_f32_16x16x32_bf16 v[136:139], v[216:219], v[208:211], v[136:139]
	ds_read_b128 v[166:169], v249 offset:11264
	v_mfma_f32_16x16x32_bf16 v[104:107], v[220:223], v[186:189], v[104:107]
	ds_read_b128 v[170:173], v249 offset:12288
	v_mfma_f32_16x16x32_bf16 v[64:67], v[220:223], v[190:193], v[64:67]
	ds_read_b128 v[174:177], v249 offset:13312
	v_mfma_f32_16x16x32_bf16 v[116:119], v[220:223], v[194:197], v[116:119]
	ds_read_b128 v[178:181], v249 offset:14336
	v_mfma_f32_16x16x32_bf16 v[140:143], v[220:223], v[208:211], v[140:143]
	ds_read_b128 v[182:185], v249 offset:15360
	v_mfma_f32_16x16x32_bf16 v[100:103], v[224:227], v[186:189], v[100:103]
	v_mfma_f32_16x16x32_bf16 v[60:63], v[224:227], v[190:193], v[60:63]
	v_mfma_f32_16x16x32_bf16 v[124:127], v[224:227], v[194:197], v[124:127]
	v_mfma_f32_16x16x32_bf16 v[144:147], v[224:227], v[208:211], v[144:147]
	v_mfma_f32_16x16x32_bf16 v[68:71], v[228:231], v[186:189], v[68:71]
	v_mfma_f32_16x16x32_bf16 v[36:39], v[228:231], v[190:193], v[36:39]
	v_mfma_f32_16x16x32_bf16 v[88:91], v[228:231], v[194:197], v[88:91]
	v_mfma_f32_16x16x32_bf16 v[76:79], v[228:231], v[208:211], v[76:79]
	v_mfma_f32_16x16x32_bf16 v[56:59], v[232:235], v[186:189], v[56:59]
	v_mfma_f32_16x16x32_bf16 v[32:35], v[232:235], v[190:193], v[32:35]
	v_mfma_f32_16x16x32_bf16 v[92:95], v[232:235], v[194:197], v[92:95]
	v_mfma_f32_16x16x32_bf16 v[52:55], v[232:235], v[208:211], v[52:55]
	v_mfma_f32_16x16x32_bf16 v[48:51], v[236:239], v[186:189], v[48:51]
	v_mfma_f32_16x16x32_bf16 v[28:31], v[236:239], v[190:193], v[28:31]
	v_mfma_f32_16x16x32_bf16 v[96:99], v[236:239], v[194:197], v[96:99]
	v_mfma_f32_16x16x32_bf16 v[44:47], v[236:239], v[208:211], v[44:47]
	v_mfma_f32_16x16x32_bf16 v[40:43], v[240:243], v[186:189], v[40:43]
	v_mfma_f32_16x16x32_bf16 v[24:27], v[240:243], v[190:193], v[24:27]
	v_mfma_f32_16x16x32_bf16 v[84:87], v[240:243], v[194:197], v[84:87]
	v_mfma_f32_16x16x32_bf16 v[148:151], v[240:243], v[208:211], v[148:151]
	s_add_u32 s30, s30, 24576
	s_cmp_eq_u32 s30, 73728
	s_cselect_b32 s30, 0, s30
	s_waitcnt lgkmcnt(0)
	s_barrier
	v_mfma_f32_16x16x32_bf16 v[128:131], v[16:19], v[0:3], v[128:131]
	v_mfma_f32_16x16x32_bf16 v[80:83], v[16:19], v[4:7], v[80:83]
	v_mfma_f32_16x16x32_bf16 v[108:111], v[16:19], v[8:11], v[108:111]
	v_mfma_f32_16x16x32_bf16 v[132:135], v[16:19], v[12:15], v[132:135]
	v_mfma_f32_16x16x32_bf16 v[120:123], v[20:23], v[0:3], v[120:123]
	v_mfma_f32_16x16x32_bf16 v[72:75], v[20:23], v[4:7], v[72:75]
	v_mfma_f32_16x16x32_bf16 v[112:115], v[20:23], v[8:11], v[112:115]
	v_mfma_f32_16x16x32_bf16 v[136:139], v[20:23], v[12:15], v[136:139]
	v_mfma_f32_16x16x32_bf16 v[104:107], v[162:165], v[0:3], v[104:107]
	v_mfma_f32_16x16x32_bf16 v[64:67], v[162:165], v[4:7], v[64:67]
	v_mfma_f32_16x16x32_bf16 v[116:119], v[162:165], v[8:11], v[116:119]
	v_mfma_f32_16x16x32_bf16 v[140:143], v[162:165], v[12:15], v[140:143]
	v_mfma_f32_16x16x32_bf16 v[100:103], v[166:169], v[0:3], v[100:103]
	v_mfma_f32_16x16x32_bf16 v[60:63], v[166:169], v[4:7], v[60:63]
	v_mfma_f32_16x16x32_bf16 v[124:127], v[166:169], v[8:11], v[124:127]
	v_mfma_f32_16x16x32_bf16 v[144:147], v[166:169], v[12:15], v[144:147]
	v_mfma_f32_16x16x32_bf16 v[68:71], v[170:173], v[0:3], v[68:71]
	v_mfma_f32_16x16x32_bf16 v[36:39], v[170:173], v[4:7], v[36:39]
	v_mfma_f32_16x16x32_bf16 v[88:91], v[170:173], v[8:11], v[88:91]
	v_mfma_f32_16x16x32_bf16 v[76:79], v[170:173], v[12:15], v[76:79]
	v_mfma_f32_16x16x32_bf16 v[56:59], v[174:177], v[0:3], v[56:59]
	v_mfma_f32_16x16x32_bf16 v[32:35], v[174:177], v[4:7], v[32:35]
	v_mfma_f32_16x16x32_bf16 v[92:95], v[174:177], v[8:11], v[92:95]
	v_mfma_f32_16x16x32_bf16 v[52:55], v[174:177], v[12:15], v[52:55]
	v_mfma_f32_16x16x32_bf16 v[48:51], v[178:181], v[0:3], v[48:51]
	v_mfma_f32_16x16x32_bf16 v[28:31], v[178:181], v[4:7], v[28:31]
	v_mfma_f32_16x16x32_bf16 v[96:99], v[178:181], v[8:11], v[96:99]
	v_mfma_f32_16x16x32_bf16 v[44:47], v[178:181], v[12:15], v[44:47]
	v_mfma_f32_16x16x32_bf16 v[40:43], v[182:185], v[0:3], v[40:43]
	v_mfma_f32_16x16x32_bf16 v[24:27], v[182:185], v[4:7], v[24:27]
	v_mfma_f32_16x16x32_bf16 v[84:87], v[182:185], v[8:11], v[84:87]
	v_mfma_f32_16x16x32_bf16 v[148:151], v[182:185], v[12:15], v[148:151]
	v_mov_b32 v250, v198
	s_nop 0
	v_and_b32_e32 v251, 15, v250
	v_bfe_u32 v156, v250, 4, 2
	v_bfe_u32 v157, v250, 6, 1
	v_bfe_u32 v158, v250, 7, 1
	v_lshl_add_u32 v158, v158, 6, s10
	v_add_u32_e32 v158, v158, v251
	v_lshl_add_u32 v157, v157, 7, s11
	v_lshl_add_u32 v159, v156, 2, v157
	v_lshlrev_b32_e32 v246, 2, v159
	v_lshl_add_u32 v244, v158, 12, v246
	v_lshlrev_b32_e32 v161, 1, v159
	v_lshl_add_u32 v245, v158, 11, v161
	v_and_b32_e32 v254, 1, v156
	v_mul_u32_u24_e32 v254, 24, v254
	v_add_u32_e32 v254, v254, v245
	v_lshrrev_b32_e32 v161, 6, v157
	v_lshlrev_b32_e32 v161, 2, v161
	v_lshl_add_u32 v247, v158, 6, v161
	v_xor_b32_e32 v248, 16, v200
	v_lshlrev_b32_e32 v248, 2, v248
	v_xor_b32_e32 v249, 32, v200
	v_lshlrev_b32_e32 v249, 2, v249
	s_mov_b32 s24, s6
	s_mov_b32 s25, s7
	s_mov_b32 s26, s78
	s_mov_b32 s27, s79
	v_readlane_b32 s28, v253, 21
	v_readlane_b32 s29, v253, 22
	s_mov_b32 s30, s94
	s_mov_b32 s31, s95
	global_load_dwordx4 v[208:211], v246, s[8:9]
	global_load_dwordx4 v[212:215], v246, s[8:9] offset:64
	global_load_dwordx4 v[216:219], v246, s[8:9] offset:128
	global_load_dwordx4 v[220:223], v246, s[8:9] offset:192
	global_load_dwordx4 v[224:227], v246, s[8:9] offset:256
	global_load_dwordx4 v[228:231], v246, s[8:9] offset:320
	global_load_dwordx4 v[232:235], v246, s[8:9] offset:384
	global_load_dwordx4 v[236:239], v246, s[8:9] offset:448
	global_load_dwordx4 v[0:3], v244, s[24:25]
	global_load_dwordx4 v[4:7], v244, s[24:25] offset:64
	global_load_dwordx4 v[8:11], v244, s[24:25] offset:128
	global_load_dwordx4 v[12:15], v244, s[24:25] offset:192
	global_load_dwordx4 v[16:19], v244, s[24:25] offset:256
	global_load_dwordx4 v[20:23], v244, s[24:25] offset:320
	global_load_dwordx4 v[162:165], v244, s[24:25] offset:384
	global_load_dwordx4 v[166:169], v244, s[24:25] offset:448
	s_add_u32 s24, s24, 0x10000
	s_addc_u32 s25, s25, 0
	global_load_dwordx4 v[170:173], v244, s[24:25]
	global_load_dwordx4 v[174:177], v244, s[24:25] offset:64
	global_load_dwordx4 v[178:181], v244, s[24:25] offset:128
	global_load_dwordx4 v[182:185], v244, s[24:25] offset:192
	global_load_dwordx4 v[186:189], v244, s[24:25] offset:256
	global_load_dwordx4 v[190:193], v244, s[24:25] offset:320
	global_load_dwordx4 v[194:197], v244, s[24:25] offset:384
	global_load_dwordx4 v[240:243], v244, s[24:25] offset:448
	s_add_u32 s24, s24, 0x10000
	s_addc_u32 s25, s25, 0
	s_waitcnt vmcnt(12)
	v_add_f32_e32 v0, v128, v0
	v_add_f32_e32 v1, v129, v1
	v_add_f32_e32 v2, v130, v2
	v_add_f32_e32 v3, v131, v3
	global_store_dwordx4 v244, v[0:3], s[26:27]
	v_mul_f32_e32 v158, v0, v0
	v_mul_f32_e32 v159, v1, v1
	v_mul_f32_e32 v250, v2, v2
	v_mul_f32_e32 v251, v3, v3
	v_add_f32_e32 v158, v158, v159
	v_add_f32_e32 v250, v250, v251
	v_add_f32_e32 v161, v158, v250
	v_mul_f32_e32 v156, v0, v208
	v_mul_f32_e32 v157, v1, v209
	v_mul_f32_e32 v158, v2, v210
	v_mul_f32_e32 v159, v3, v211
	v_cvt_pk_bf16_f32 v156, v156, v157
	v_cvt_pk_bf16_f32 v157, v158, v159
	v_add_f32_e32 v4, v120, v4
	v_add_f32_e32 v5, v121, v5
	v_add_f32_e32 v6, v122, v6
	v_add_f32_e32 v7, v123, v7
	global_store_dwordx4 v244, v[4:7], s[26:27] offset:64
	v_mul_f32_e32 v158, v4, v4
	v_mul_f32_e32 v159, v5, v5
	v_mul_f32_e32 v250, v6, v6
	v_mul_f32_e32 v251, v7, v7
	v_add_f32_e32 v158, v158, v159
	v_add_f32_e32 v250, v250, v251
	v_add_f32_e32 v158, v158, v250
	v_add_f32_e32 v161, v161, v158
	v_mul_f32_e32 v158, v4, v212
	v_mul_f32_e32 v159, v5, v213
	v_mul_f32_e32 v250, v6, v214
	v_mul_f32_e32 v251, v7, v215
	v_cvt_pk_bf16_f32 v158, v158, v159
	v_cvt_pk_bf16_f32 v159, v250, v251
	s_nop 1
	v_permlane16_swap_b32_e32 v156, v158
	v_permlane16_swap_b32_e32 v157, v159
	global_store_dwordx4 v254, v[156:159], s[28:29]
	v_add_f32_e32 v8, v104, v8
	v_add_f32_e32 v9, v105, v9
	v_add_f32_e32 v10, v106, v10
	v_add_f32_e32 v11, v107, v11
	global_store_dwordx4 v244, v[8:11], s[26:27] offset:128
	v_mul_f32_e32 v158, v8, v8
	v_mul_f32_e32 v159, v9, v9
	v_mul_f32_e32 v250, v10, v10
	v_mul_f32_e32 v251, v11, v11
	v_add_f32_e32 v158, v158, v159
	v_add_f32_e32 v250, v250, v251
	v_add_f32_e32 v158, v158, v250
	v_add_f32_e32 v161, v161, v158
	v_mul_f32_e32 v156, v8, v216
	v_mul_f32_e32 v157, v9, v217
	v_mul_f32_e32 v158, v10, v218
	v_mul_f32_e32 v159, v11, v219
	v_cvt_pk_bf16_f32 v156, v156, v157
	v_cvt_pk_bf16_f32 v157, v158, v159
	v_add_f32_e32 v12, v100, v12
	v_add_f32_e32 v13, v101, v13
	v_add_f32_e32 v14, v102, v14
	v_add_f32_e32 v15, v103, v15
	global_store_dwordx4 v244, v[12:15], s[26:27] offset:192
	v_mul_f32_e32 v158, v12, v12
	v_mul_f32_e32 v159, v13, v13
	v_mul_f32_e32 v250, v14, v14
	v_mul_f32_e32 v251, v15, v15
	v_add_f32_e32 v158, v158, v159
	v_add_f32_e32 v250, v250, v251
	v_add_f32_e32 v158, v158, v250
	v_add_f32_e32 v161, v161, v158
	v_mul_f32_e32 v158, v12, v220
	v_mul_f32_e32 v159, v13, v221
	v_mul_f32_e32 v250, v14, v222
	v_mul_f32_e32 v251, v15, v223
	v_cvt_pk_bf16_f32 v158, v158, v159
	v_cvt_pk_bf16_f32 v159, v250, v251
	s_nop 1
	v_permlane16_swap_b32_e32 v156, v158
	v_permlane16_swap_b32_e32 v157, v159
	global_store_dwordx4 v254, v[156:159], s[28:29] offset:64
	ds_bpermute_b32 v158, v248, v161
	s_waitcnt lgkmcnt(0)
	v_add_f32_e32 v161, v161, v158
	ds_bpermute_b32 v158, v249, v161
	s_waitcnt lgkmcnt(0)
	v_add_f32_e32 v161, v161, v158
	global_store_dword v247, v161, s[30:31]
	global_load_dwordx4 v[0:3], v244, s[24:25]
	global_load_dwordx4 v[4:7], v244, s[24:25] offset:64
	global_load_dwordx4 v[8:11], v244, s[24:25] offset:128
	global_load_dwordx4 v[12:15], v244, s[24:25] offset:192
	s_waitcnt vmcnt(19)
	v_add_f32_e32 v16, v68, v16
	v_add_f32_e32 v17, v69, v17
	v_add_f32_e32 v18, v70, v18
	v_add_f32_e32 v19, v71, v19
	global_store_dwordx4 v244, v[16:19], s[26:27] offset:256
	v_mul_f32_e32 v158, v16, v16
	v_mul_f32_e32 v159, v17, v17
	v_mul_f32_e32 v250, v18, v18
	v_mul_f32_e32 v251, v19, v19
	v_add_f32_e32 v158, v158, v159
	v_add_f32_e32 v250, v250, v251
	v_add_f32_e32 v161, v158, v250
	v_mul_f32_e32 v156, v16, v224
	v_mul_f32_e32 v157, v17, v225
	v_mul_f32_e32 v158, v18, v226
	v_mul_f32_e32 v159, v19, v227
	v_cvt_pk_bf16_f32 v156, v156, v157
	v_cvt_pk_bf16_f32 v157, v158, v159
	v_add_f32_e32 v20, v56, v20
	v_add_f32_e32 v21, v57, v21
	v_add_f32_e32 v22, v58, v22
	v_add_f32_e32 v23, v59, v23
	global_store_dwordx4 v244, v[20:23], s[26:27] offset:320
	v_mul_f32_e32 v158, v20, v20
	v_mul_f32_e32 v159, v21, v21
	v_mul_f32_e32 v250, v22, v22
	v_mul_f32_e32 v251, v23, v23
	v_add_f32_e32 v158, v158, v159
	v_add_f32_e32 v250, v250, v251
	v_add_f32_e32 v158, v158, v250
	v_add_f32_e32 v161, v161, v158
	v_mul_f32_e32 v158, v20, v228
	v_mul_f32_e32 v159, v21, v229
	v_mul_f32_e32 v250, v22, v230
	v_mul_f32_e32 v251, v23, v231
	v_cvt_pk_bf16_f32 v158, v158, v159
	v_cvt_pk_bf16_f32 v159, v250, v251
	s_nop 1
	v_permlane16_swap_b32_e32 v156, v158
	v_permlane16_swap_b32_e32 v157, v159
	global_store_dwordx4 v254, v[156:159], s[28:29] offset:128
	v_add_f32_e32 v162, v48, v162
	v_add_f32_e32 v163, v49, v163
	v_add_f32_e32 v164, v50, v164
	v_add_f32_e32 v165, v51, v165
	global_store_dwordx4 v244, v[162:165], s[26:27] offset:384
	v_mul_f32_e32 v158, v162, v162
	v_mul_f32_e32 v159, v163, v163
	v_mul_f32_e32 v250, v164, v164
	v_mul_f32_e32 v251, v165, v165
	v_add_f32_e32 v158, v158, v159
	v_add_f32_e32 v250, v250, v251
	v_add_f32_e32 v158, v158, v250
	v_add_f32_e32 v161, v161, v158
	v_mul_f32_e32 v156, v162, v232
	v_mul_f32_e32 v157, v163, v233
	v_mul_f32_e32 v158, v164, v234
	v_mul_f32_e32 v159, v165, v235
	v_cvt_pk_bf16_f32 v156, v156, v157
	v_cvt_pk_bf16_f32 v157, v158, v159
	v_add_f32_e32 v166, v40, v166
	v_add_f32_e32 v167, v41, v167
	v_add_f32_e32 v168, v42, v168
	v_add_f32_e32 v169, v43, v169
	global_store_dwordx4 v244, v[166:169], s[26:27] offset:448
	v_mul_f32_e32 v158, v166, v166
	v_mul_f32_e32 v159, v167, v167
	v_mul_f32_e32 v250, v168, v168
	v_mul_f32_e32 v251, v169, v169
	v_add_f32_e32 v158, v158, v159
	v_add_f32_e32 v250, v250, v251
	v_add_f32_e32 v158, v158, v250
	v_add_f32_e32 v161, v161, v158
	v_mul_f32_e32 v158, v166, v236
	v_mul_f32_e32 v159, v167, v237
	v_mul_f32_e32 v250, v168, v238
	v_mul_f32_e32 v251, v169, v239
	v_cvt_pk_bf16_f32 v158, v158, v159
	v_cvt_pk_bf16_f32 v159, v250, v251
	s_nop 1
	v_permlane16_swap_b32_e32 v156, v158
	v_permlane16_swap_b32_e32 v157, v159
	global_store_dwordx4 v254, v[156:159], s[28:29] offset:192
	ds_bpermute_b32 v158, v248, v161
	s_waitcnt lgkmcnt(0)
	v_add_f32_e32 v161, v161, v158
	ds_bpermute_b32 v158, v249, v161
	s_waitcnt lgkmcnt(0)
	v_add_f32_e32 v161, v161, v158
	global_store_dword v247, v161, s[30:31] offset:4
	s_add_u32 s26, s26, 0x10000
	s_addc_u32 s27, s27, 0
	s_add_u32 s28, s28, 0x8000
	s_addc_u32 s29, s29, 0
	s_add_u32 s30, s30, 0x400
	s_addc_u32 s31, s31, 0
	global_load_dwordx4 v[16:19], v244, s[24:25] offset:256
	global_load_dwordx4 v[20:23], v244, s[24:25] offset:320
	global_load_dwordx4 v[162:165], v244, s[24:25] offset:384
	global_load_dwordx4 v[166:169], v244, s[24:25] offset:448
	s_add_u32 s24, s24, 0x10000
	s_addc_u32 s25, s25, 0
	s_waitcnt vmcnt(26)
	v_add_f32_e32 v170, v80, v170
	v_add_f32_e32 v171, v81, v171
	v_add_f32_e32 v172, v82, v172
	v_add_f32_e32 v173, v83, v173
	global_store_dwordx4 v244, v[170:173], s[26:27]
	v_mul_f32_e32 v158, v170, v170
	v_mul_f32_e32 v159, v171, v171
	v_mul_f32_e32 v250, v172, v172
	v_mul_f32_e32 v251, v173, v173
	v_add_f32_e32 v158, v158, v159
	v_add_f32_e32 v250, v250, v251
	v_add_f32_e32 v161, v158, v250
	v_mul_f32_e32 v156, v170, v208
	v_mul_f32_e32 v157, v171, v209
	v_mul_f32_e32 v158, v172, v210
	v_mul_f32_e32 v159, v173, v211
	v_cvt_pk_bf16_f32 v156, v156, v157
	v_cvt_pk_bf16_f32 v157, v158, v159
	v_add_f32_e32 v174, v72, v174
	v_add_f32_e32 v175, v73, v175
	v_add_f32_e32 v176, v74, v176
	v_add_f32_e32 v177, v75, v177
	global_store_dwordx4 v244, v[174:177], s[26:27] offset:64
	v_mul_f32_e32 v158, v174, v174
	v_mul_f32_e32 v159, v175, v175
	v_mul_f32_e32 v250, v176, v176
	v_mul_f32_e32 v251, v177, v177
	v_add_f32_e32 v158, v158, v159
	v_add_f32_e32 v250, v250, v251
	v_add_f32_e32 v158, v158, v250
	v_add_f32_e32 v161, v161, v158
	v_mul_f32_e32 v158, v174, v212
	v_mul_f32_e32 v159, v175, v213
	v_mul_f32_e32 v250, v176, v214
	v_mul_f32_e32 v251, v177, v215
	v_cvt_pk_bf16_f32 v158, v158, v159
	v_cvt_pk_bf16_f32 v159, v250, v251
	s_nop 1
	v_permlane16_swap_b32_e32 v156, v158
	v_permlane16_swap_b32_e32 v157, v159
	global_store_dwordx4 v254, v[156:159], s[28:29]
	v_add_f32_e32 v178, v64, v178
	v_add_f32_e32 v179, v65, v179
	v_add_f32_e32 v180, v66, v180
	v_add_f32_e32 v181, v67, v181
	global_store_dwordx4 v244, v[178:181], s[26:27] offset:128
	v_mul_f32_e32 v158, v178, v178
	v_mul_f32_e32 v159, v179, v179
	v_mul_f32_e32 v250, v180, v180
	v_mul_f32_e32 v251, v181, v181
	v_add_f32_e32 v158, v158, v159
	v_add_f32_e32 v250, v250, v251
	v_add_f32_e32 v158, v158, v250
	v_add_f32_e32 v161, v161, v158
	v_mul_f32_e32 v156, v178, v216
	v_mul_f32_e32 v157, v179, v217
	v_mul_f32_e32 v158, v180, v218
	v_mul_f32_e32 v159, v181, v219
	v_cvt_pk_bf16_f32 v156, v156, v157
	v_cvt_pk_bf16_f32 v157, v158, v159
	v_add_f32_e32 v182, v60, v182
	v_add_f32_e32 v183, v61, v183
	v_add_f32_e32 v184, v62, v184
	v_add_f32_e32 v185, v63, v185
	global_store_dwordx4 v244, v[182:185], s[26:27] offset:192
	v_mul_f32_e32 v158, v182, v182
	v_mul_f32_e32 v159, v183, v183
	v_mul_f32_e32 v250, v184, v184
	v_mul_f32_e32 v251, v185, v185
	v_add_f32_e32 v158, v158, v159
	v_add_f32_e32 v250, v250, v251
	v_add_f32_e32 v158, v158, v250
	v_add_f32_e32 v161, v161, v158
	v_mul_f32_e32 v158, v182, v220
	v_mul_f32_e32 v159, v183, v221
	v_mul_f32_e32 v250, v184, v222
	v_mul_f32_e32 v251, v185, v223
	v_cvt_pk_bf16_f32 v158, v158, v159
	v_cvt_pk_bf16_f32 v159, v250, v251
	s_nop 1
	v_permlane16_swap_b32_e32 v156, v158
	v_permlane16_swap_b32_e32 v157, v159
	global_store_dwordx4 v254, v[156:159], s[28:29] offset:64
	ds_bpermute_b32 v158, v248, v161
	s_waitcnt lgkmcnt(0)
	v_add_f32_e32 v161, v161, v158
	ds_bpermute_b32 v158, v249, v161
	s_waitcnt lgkmcnt(0)
	v_add_f32_e32 v161, v161, v158
	global_store_dword v247, v161, s[30:31]
	global_load_dwordx4 v[170:173], v244, s[24:25]
	global_load_dwordx4 v[174:177], v244, s[24:25] offset:64
	global_load_dwordx4 v[178:181], v244, s[24:25] offset:128
	global_load_dwordx4 v[182:185], v244, s[24:25] offset:192
	s_waitcnt vmcnt(33)
	v_add_f32_e32 v186, v36, v186
	v_add_f32_e32 v187, v37, v187
	v_add_f32_e32 v188, v38, v188
	v_add_f32_e32 v189, v39, v189
	global_store_dwordx4 v244, v[186:189], s[26:27] offset:256
	v_mul_f32_e32 v158, v186, v186
	v_mul_f32_e32 v159, v187, v187
	v_mul_f32_e32 v250, v188, v188
	v_mul_f32_e32 v251, v189, v189
	v_add_f32_e32 v158, v158, v159
	v_add_f32_e32 v250, v250, v251
	v_add_f32_e32 v161, v158, v250
	v_mul_f32_e32 v156, v186, v224
	v_mul_f32_e32 v157, v187, v225
	v_mul_f32_e32 v158, v188, v226
	v_mul_f32_e32 v159, v189, v227
	v_cvt_pk_bf16_f32 v156, v156, v157
	v_cvt_pk_bf16_f32 v157, v158, v159
	v_add_f32_e32 v190, v32, v190
	v_add_f32_e32 v191, v33, v191
	v_add_f32_e32 v192, v34, v192
	v_add_f32_e32 v193, v35, v193
	global_store_dwordx4 v244, v[190:193], s[26:27] offset:320
	v_mul_f32_e32 v158, v190, v190
	v_mul_f32_e32 v159, v191, v191
	v_mul_f32_e32 v250, v192, v192
	v_mul_f32_e32 v251, v193, v193
	v_add_f32_e32 v158, v158, v159
	v_add_f32_e32 v250, v250, v251
	v_add_f32_e32 v158, v158, v250
	v_add_f32_e32 v161, v161, v158
	v_mul_f32_e32 v158, v190, v228
	v_mul_f32_e32 v159, v191, v229
	v_mul_f32_e32 v250, v192, v230
	v_mul_f32_e32 v251, v193, v231
	v_cvt_pk_bf16_f32 v158, v158, v159
	v_cvt_pk_bf16_f32 v159, v250, v251
	s_nop 1
	v_permlane16_swap_b32_e32 v156, v158
	v_permlane16_swap_b32_e32 v157, v159
	global_store_dwordx4 v254, v[156:159], s[28:29] offset:128
	v_add_f32_e32 v194, v28, v194
	v_add_f32_e32 v195, v29, v195
	v_add_f32_e32 v196, v30, v196
	v_add_f32_e32 v197, v31, v197
	global_store_dwordx4 v244, v[194:197], s[26:27] offset:384
	v_mul_f32_e32 v158, v194, v194
	v_mul_f32_e32 v159, v195, v195
	v_mul_f32_e32 v250, v196, v196
	v_mul_f32_e32 v251, v197, v197
	v_add_f32_e32 v158, v158, v159
	v_add_f32_e32 v250, v250, v251
	v_add_f32_e32 v158, v158, v250
	v_add_f32_e32 v161, v161, v158
	v_mul_f32_e32 v156, v194, v232
	v_mul_f32_e32 v157, v195, v233
	v_mul_f32_e32 v158, v196, v234
	v_mul_f32_e32 v159, v197, v235
	v_cvt_pk_bf16_f32 v156, v156, v157
	v_cvt_pk_bf16_f32 v157, v158, v159
	v_add_f32_e32 v240, v24, v240
	v_add_f32_e32 v241, v25, v241
	v_add_f32_e32 v242, v26, v242
	v_add_f32_e32 v243, v27, v243
	global_store_dwordx4 v244, v[240:243], s[26:27] offset:448
	v_mul_f32_e32 v158, v240, v240
	v_mul_f32_e32 v159, v241, v241
	v_mul_f32_e32 v250, v242, v242
	v_mul_f32_e32 v251, v243, v243
	v_add_f32_e32 v158, v158, v159
	v_add_f32_e32 v250, v250, v251
	v_add_f32_e32 v158, v158, v250
	v_add_f32_e32 v161, v161, v158
	v_mul_f32_e32 v158, v240, v236
	v_mul_f32_e32 v159, v241, v237
	v_mul_f32_e32 v250, v242, v238
	v_mul_f32_e32 v251, v243, v239
	v_cvt_pk_bf16_f32 v158, v158, v159
	v_cvt_pk_bf16_f32 v159, v250, v251
	s_nop 1
	v_permlane16_swap_b32_e32 v156, v158
	v_permlane16_swap_b32_e32 v157, v159
	global_store_dwordx4 v254, v[156:159], s[28:29] offset:192
	ds_bpermute_b32 v158, v248, v161
	s_waitcnt lgkmcnt(0)
	v_add_f32_e32 v161, v161, v158
	ds_bpermute_b32 v158, v249, v161
	s_waitcnt lgkmcnt(0)
	v_add_f32_e32 v161, v161, v158
	global_store_dword v247, v161, s[30:31] offset:4
	s_add_u32 s26, s26, 0x10000
	s_addc_u32 s27, s27, 0
	s_add_u32 s28, s28, 0x8000
	s_addc_u32 s29, s29, 0
	s_add_u32 s30, s30, 0x400
	s_addc_u32 s31, s31, 0
	global_load_dwordx4 v[186:189], v244, s[24:25] offset:256
	global_load_dwordx4 v[190:193], v244, s[24:25] offset:320
	global_load_dwordx4 v[194:197], v244, s[24:25] offset:384
	global_load_dwordx4 v[240:243], v244, s[24:25] offset:448
	s_add_u32 s24, s24, 0x10000
	s_addc_u32 s25, s25, 0
	s_waitcnt vmcnt(33)
	v_add_f32_e32 v0, v108, v0
	v_add_f32_e32 v1, v109, v1
	v_add_f32_e32 v2, v110, v2
	v_add_f32_e32 v3, v111, v3
	global_store_dwordx4 v244, v[0:3], s[26:27]
	v_mul_f32_e32 v158, v0, v0
	v_mul_f32_e32 v159, v1, v1
	v_mul_f32_e32 v250, v2, v2
	v_mul_f32_e32 v251, v3, v3
	v_add_f32_e32 v158, v158, v159
	v_add_f32_e32 v250, v250, v251
	v_add_f32_e32 v161, v158, v250
	v_mul_f32_e32 v156, v0, v208
	v_mul_f32_e32 v157, v1, v209
	v_mul_f32_e32 v158, v2, v210
	v_mul_f32_e32 v159, v3, v211
	v_cvt_pk_bf16_f32 v156, v156, v157
	v_cvt_pk_bf16_f32 v157, v158, v159
	v_add_f32_e32 v4, v112, v4
	v_add_f32_e32 v5, v113, v5
	v_add_f32_e32 v6, v114, v6
	v_add_f32_e32 v7, v115, v7
	global_store_dwordx4 v244, v[4:7], s[26:27] offset:64
	v_mul_f32_e32 v158, v4, v4
	v_mul_f32_e32 v159, v5, v5
	v_mul_f32_e32 v250, v6, v6
	v_mul_f32_e32 v251, v7, v7
	v_add_f32_e32 v158, v158, v159
	v_add_f32_e32 v250, v250, v251
	v_add_f32_e32 v158, v158, v250
	v_add_f32_e32 v161, v161, v158
	v_mul_f32_e32 v158, v4, v212
	v_mul_f32_e32 v159, v5, v213
	v_mul_f32_e32 v250, v6, v214
	v_mul_f32_e32 v251, v7, v215
	v_cvt_pk_bf16_f32 v158, v158, v159
	v_cvt_pk_bf16_f32 v159, v250, v251
	s_nop 1
	v_permlane16_swap_b32_e32 v156, v158
	v_permlane16_swap_b32_e32 v157, v159
	global_store_dwordx4 v254, v[156:159], s[28:29]
	v_add_f32_e32 v8, v116, v8
	v_add_f32_e32 v9, v117, v9
	v_add_f32_e32 v10, v118, v10
	v_add_f32_e32 v11, v119, v11
	global_store_dwordx4 v244, v[8:11], s[26:27] offset:128
	v_mul_f32_e32 v158, v8, v8
	v_mul_f32_e32 v159, v9, v9
	v_mul_f32_e32 v250, v10, v10
	v_mul_f32_e32 v251, v11, v11
	v_add_f32_e32 v158, v158, v159
	v_add_f32_e32 v250, v250, v251
	v_add_f32_e32 v158, v158, v250
	v_add_f32_e32 v161, v161, v158
	v_mul_f32_e32 v156, v8, v216
	v_mul_f32_e32 v157, v9, v217
	v_mul_f32_e32 v158, v10, v218
	v_mul_f32_e32 v159, v11, v219
	v_cvt_pk_bf16_f32 v156, v156, v157
	v_cvt_pk_bf16_f32 v157, v158, v159
	v_add_f32_e32 v12, v124, v12
	v_add_f32_e32 v13, v125, v13
	v_add_f32_e32 v14, v126, v14
	v_add_f32_e32 v15, v127, v15
	global_store_dwordx4 v244, v[12:15], s[26:27] offset:192
	v_mul_f32_e32 v158, v12, v12
	v_mul_f32_e32 v159, v13, v13
	v_mul_f32_e32 v250, v14, v14
	v_mul_f32_e32 v251, v15, v15
	v_add_f32_e32 v158, v158, v159
	v_add_f32_e32 v250, v250, v251
	v_add_f32_e32 v158, v158, v250
	v_add_f32_e32 v161, v161, v158
	v_mul_f32_e32 v158, v12, v220
	v_mul_f32_e32 v159, v13, v221
	v_mul_f32_e32 v250, v14, v222
	v_mul_f32_e32 v251, v15, v223
	v_cvt_pk_bf16_f32 v158, v158, v159
	v_cvt_pk_bf16_f32 v159, v250, v251
	s_nop 1
	v_permlane16_swap_b32_e32 v156, v158
	v_permlane16_swap_b32_e32 v157, v159
	global_store_dwordx4 v254, v[156:159], s[28:29] offset:64
	ds_bpermute_b32 v158, v248, v161
	s_waitcnt lgkmcnt(0)
	v_add_f32_e32 v161, v161, v158
	ds_bpermute_b32 v158, v249, v161
	s_waitcnt lgkmcnt(0)
	v_add_f32_e32 v161, v161, v158
	global_store_dword v247, v161, s[30:31]
	s_waitcnt vmcnt(29)
	v_add_f32_e32 v16, v88, v16
	v_add_f32_e32 v17, v89, v17
	v_add_f32_e32 v18, v90, v18
	v_add_f32_e32 v19, v91, v19
	global_store_dwordx4 v244, v[16:19], s[26:27] offset:256
	v_mul_f32_e32 v158, v16, v16
	v_mul_f32_e32 v159, v17, v17
	v_mul_f32_e32 v250, v18, v18
	v_mul_f32_e32 v251, v19, v19
	v_add_f32_e32 v158, v158, v159
	v_add_f32_e32 v250, v250, v251
	v_add_f32_e32 v161, v158, v250
	v_mul_f32_e32 v156, v16, v224
	v_mul_f32_e32 v157, v17, v225
	v_mul_f32_e32 v158, v18, v226
	v_mul_f32_e32 v159, v19, v227
	v_cvt_pk_bf16_f32 v156, v156, v157
	v_cvt_pk_bf16_f32 v157, v158, v159
	v_add_f32_e32 v20, v92, v20
	v_add_f32_e32 v21, v93, v21
	v_add_f32_e32 v22, v94, v22
	v_add_f32_e32 v23, v95, v23
	global_store_dwordx4 v244, v[20:23], s[26:27] offset:320
	v_mul_f32_e32 v158, v20, v20
	v_mul_f32_e32 v159, v21, v21
	v_mul_f32_e32 v250, v22, v22
	v_mul_f32_e32 v251, v23, v23
	v_add_f32_e32 v158, v158, v159
	v_add_f32_e32 v250, v250, v251
	v_add_f32_e32 v158, v158, v250
	v_add_f32_e32 v161, v161, v158
	v_mul_f32_e32 v158, v20, v228
	v_mul_f32_e32 v159, v21, v229
	v_mul_f32_e32 v250, v22, v230
	v_mul_f32_e32 v251, v23, v231
	v_cvt_pk_bf16_f32 v158, v158, v159
	v_cvt_pk_bf16_f32 v159, v250, v251
	s_nop 1
	v_permlane16_swap_b32_e32 v156, v158
	v_permlane16_swap_b32_e32 v157, v159
	global_store_dwordx4 v254, v[156:159], s[28:29] offset:128
	v_add_f32_e32 v162, v96, v162
	v_add_f32_e32 v163, v97, v163
	v_add_f32_e32 v164, v98, v164
	v_add_f32_e32 v165, v99, v165
	global_store_dwordx4 v244, v[162:165], s[26:27] offset:384
	v_mul_f32_e32 v158, v162, v162
	v_mul_f32_e32 v159, v163, v163
	v_mul_f32_e32 v250, v164, v164
	v_mul_f32_e32 v251, v165, v165
	v_add_f32_e32 v158, v158, v159
	v_add_f32_e32 v250, v250, v251
	v_add_f32_e32 v158, v158, v250
	v_add_f32_e32 v161, v161, v158
	v_mul_f32_e32 v156, v162, v232
	v_mul_f32_e32 v157, v163, v233
	v_mul_f32_e32 v158, v164, v234
	v_mul_f32_e32 v159, v165, v235
	v_cvt_pk_bf16_f32 v156, v156, v157
	v_cvt_pk_bf16_f32 v157, v158, v159
	v_add_f32_e32 v166, v84, v166
	v_add_f32_e32 v167, v85, v167
	v_add_f32_e32 v168, v86, v168
	v_add_f32_e32 v169, v87, v169
	global_store_dwordx4 v244, v[166:169], s[26:27] offset:448
	v_mul_f32_e32 v158, v166, v166
	v_mul_f32_e32 v159, v167, v167
	v_mul_f32_e32 v250, v168, v168
	v_mul_f32_e32 v251, v169, v169
	v_add_f32_e32 v158, v158, v159
	v_add_f32_e32 v250, v250, v251
	v_add_f32_e32 v158, v158, v250
	v_add_f32_e32 v161, v161, v158
	v_mul_f32_e32 v158, v166, v236
	v_mul_f32_e32 v159, v167, v237
	v_mul_f32_e32 v250, v168, v238
	v_mul_f32_e32 v251, v169, v239
	v_cvt_pk_bf16_f32 v158, v158, v159
	v_cvt_pk_bf16_f32 v159, v250, v251
	s_nop 1
	v_permlane16_swap_b32_e32 v156, v158
	v_permlane16_swap_b32_e32 v157, v159
	global_store_dwordx4 v254, v[156:159], s[28:29] offset:192
	ds_bpermute_b32 v158, v248, v161
	s_waitcnt lgkmcnt(0)
	v_add_f32_e32 v161, v161, v158
	ds_bpermute_b32 v158, v249, v161
	s_waitcnt lgkmcnt(0)
	v_add_f32_e32 v161, v161, v158
	global_store_dword v247, v161, s[30:31] offset:4
	s_add_u32 s26, s26, 0x10000
	s_addc_u32 s27, s27, 0
	s_add_u32 s28, s28, 0x8000
	s_addc_u32 s29, s29, 0
	s_add_u32 s30, s30, 0x400
	s_addc_u32 s31, s31, 0
	s_waitcnt vmcnt(25)
	v_add_f32_e32 v170, v132, v170
	v_add_f32_e32 v171, v133, v171
	v_add_f32_e32 v172, v134, v172
	v_add_f32_e32 v173, v135, v173
	global_store_dwordx4 v244, v[170:173], s[26:27]
	v_mul_f32_e32 v158, v170, v170
	v_mul_f32_e32 v159, v171, v171
	v_mul_f32_e32 v250, v172, v172
	v_mul_f32_e32 v251, v173, v173
	v_add_f32_e32 v158, v158, v159
	v_add_f32_e32 v250, v250, v251
	v_add_f32_e32 v161, v158, v250
	v_mul_f32_e32 v156, v170, v208
	v_mul_f32_e32 v157, v171, v209
	v_mul_f32_e32 v158, v172, v210
	v_mul_f32_e32 v159, v173, v211
	v_cvt_pk_bf16_f32 v156, v156, v157
	v_cvt_pk_bf16_f32 v157, v158, v159
	v_add_f32_e32 v174, v136, v174
	v_add_f32_e32 v175, v137, v175
	v_add_f32_e32 v176, v138, v176
	v_add_f32_e32 v177, v139, v177
	global_store_dwordx4 v244, v[174:177], s[26:27] offset:64
	v_mul_f32_e32 v158, v174, v174
	v_mul_f32_e32 v159, v175, v175
	v_mul_f32_e32 v250, v176, v176
	v_mul_f32_e32 v251, v177, v177
	v_add_f32_e32 v158, v158, v159
	v_add_f32_e32 v250, v250, v251
	v_add_f32_e32 v158, v158, v250
	v_add_f32_e32 v161, v161, v158
	v_mul_f32_e32 v158, v174, v212
	v_mul_f32_e32 v159, v175, v213
	v_mul_f32_e32 v250, v176, v214
	v_mul_f32_e32 v251, v177, v215
	v_cvt_pk_bf16_f32 v158, v158, v159
	v_cvt_pk_bf16_f32 v159, v250, v251
	s_nop 1
	v_permlane16_swap_b32_e32 v156, v158
	v_permlane16_swap_b32_e32 v157, v159
	global_store_dwordx4 v254, v[156:159], s[28:29]
	v_add_f32_e32 v178, v140, v178
	v_add_f32_e32 v179, v141, v179
	v_add_f32_e32 v180, v142, v180
	v_add_f32_e32 v181, v143, v181
	global_store_dwordx4 v244, v[178:181], s[26:27] offset:128
	v_mul_f32_e32 v158, v178, v178
	v_mul_f32_e32 v159, v179, v179
	v_mul_f32_e32 v250, v180, v180
	v_mul_f32_e32 v251, v181, v181
	v_add_f32_e32 v158, v158, v159
	v_add_f32_e32 v250, v250, v251
	v_add_f32_e32 v158, v158, v250
	v_add_f32_e32 v161, v161, v158
	v_mul_f32_e32 v156, v178, v216
	v_mul_f32_e32 v157, v179, v217
	v_mul_f32_e32 v158, v180, v218
	v_mul_f32_e32 v159, v181, v219
	v_cvt_pk_bf16_f32 v156, v156, v157
	v_cvt_pk_bf16_f32 v157, v158, v159
	v_add_f32_e32 v182, v144, v182
	v_add_f32_e32 v183, v145, v183
	v_add_f32_e32 v184, v146, v184
	v_add_f32_e32 v185, v147, v185
	global_store_dwordx4 v244, v[182:185], s[26:27] offset:192
	v_mul_f32_e32 v158, v182, v182
	v_mul_f32_e32 v159, v183, v183
	v_mul_f32_e32 v250, v184, v184
	v_mul_f32_e32 v251, v185, v185
	v_add_f32_e32 v158, v158, v159
	v_add_f32_e32 v250, v250, v251
	v_add_f32_e32 v158, v158, v250
	v_add_f32_e32 v161, v161, v158
	v_mul_f32_e32 v158, v182, v220
	v_mul_f32_e32 v159, v183, v221
	v_mul_f32_e32 v250, v184, v222
	v_mul_f32_e32 v251, v185, v223
	v_cvt_pk_bf16_f32 v158, v158, v159
	v_cvt_pk_bf16_f32 v159, v250, v251
	s_nop 1
	v_permlane16_swap_b32_e32 v156, v158
	v_permlane16_swap_b32_e32 v157, v159
	global_store_dwordx4 v254, v[156:159], s[28:29] offset:64
	ds_bpermute_b32 v158, v248, v161
	s_waitcnt lgkmcnt(0)
	v_add_f32_e32 v161, v161, v158
	ds_bpermute_b32 v158, v249, v161
	s_waitcnt lgkmcnt(0)
	v_add_f32_e32 v161, v161, v158
	global_store_dword v247, v161, s[30:31]
	s_waitcnt vmcnt(21)
	v_add_f32_e32 v186, v76, v186
	v_add_f32_e32 v187, v77, v187
	v_add_f32_e32 v188, v78, v188
	v_add_f32_e32 v189, v79, v189
	global_store_dwordx4 v244, v[186:189], s[26:27] offset:256
	v_mul_f32_e32 v158, v186, v186
	v_mul_f32_e32 v159, v187, v187
	v_mul_f32_e32 v250, v188, v188
	v_mul_f32_e32 v251, v189, v189
	v_add_f32_e32 v158, v158, v159
	v_add_f32_e32 v250, v250, v251
	v_add_f32_e32 v161, v158, v250
	v_mul_f32_e32 v156, v186, v224
	v_mul_f32_e32 v157, v187, v225
	v_mul_f32_e32 v158, v188, v226
	v_mul_f32_e32 v159, v189, v227
	v_cvt_pk_bf16_f32 v156, v156, v157
	v_cvt_pk_bf16_f32 v157, v158, v159
	v_add_f32_e32 v190, v52, v190
	v_add_f32_e32 v191, v53, v191
	v_add_f32_e32 v192, v54, v192
	v_add_f32_e32 v193, v55, v193
	global_store_dwordx4 v244, v[190:193], s[26:27] offset:320
	v_mul_f32_e32 v158, v190, v190
	v_mul_f32_e32 v159, v191, v191
	v_mul_f32_e32 v250, v192, v192
	v_mul_f32_e32 v251, v193, v193
	v_add_f32_e32 v158, v158, v159
	v_add_f32_e32 v250, v250, v251
	v_add_f32_e32 v158, v158, v250
	v_add_f32_e32 v161, v161, v158
	v_mul_f32_e32 v158, v190, v228
	v_mul_f32_e32 v159, v191, v229
	v_mul_f32_e32 v250, v192, v230
	v_mul_f32_e32 v251, v193, v231
	v_cvt_pk_bf16_f32 v158, v158, v159
	v_cvt_pk_bf16_f32 v159, v250, v251
	s_nop 1
	v_permlane16_swap_b32_e32 v156, v158
	v_permlane16_swap_b32_e32 v157, v159
	global_store_dwordx4 v254, v[156:159], s[28:29] offset:128
	v_add_f32_e32 v194, v44, v194
	v_add_f32_e32 v195, v45, v195
	v_add_f32_e32 v196, v46, v196
	v_add_f32_e32 v197, v47, v197
	global_store_dwordx4 v244, v[194:197], s[26:27] offset:384
	v_mul_f32_e32 v158, v194, v194
	v_mul_f32_e32 v159, v195, v195
	v_mul_f32_e32 v250, v196, v196
	v_mul_f32_e32 v251, v197, v197
	v_add_f32_e32 v158, v158, v159
	v_add_f32_e32 v250, v250, v251
	v_add_f32_e32 v158, v158, v250
	v_add_f32_e32 v161, v161, v158
	v_mul_f32_e32 v156, v194, v232
	v_mul_f32_e32 v157, v195, v233
	v_mul_f32_e32 v158, v196, v234
	v_mul_f32_e32 v159, v197, v235
	v_cvt_pk_bf16_f32 v156, v156, v157
	v_cvt_pk_bf16_f32 v157, v158, v159
	v_add_f32_e32 v240, v148, v240
	v_add_f32_e32 v241, v149, v241
	v_add_f32_e32 v242, v150, v242
	v_add_f32_e32 v243, v151, v243
	global_store_dwordx4 v244, v[240:243], s[26:27] offset:448
	v_mul_f32_e32 v158, v240, v240
	v_mul_f32_e32 v159, v241, v241
	v_mul_f32_e32 v250, v242, v242
	v_mul_f32_e32 v251, v243, v243
	v_add_f32_e32 v158, v158, v159
	v_add_f32_e32 v250, v250, v251
	v_add_f32_e32 v158, v158, v250
	v_add_f32_e32 v161, v161, v158
	v_mul_f32_e32 v158, v240, v236
	v_mul_f32_e32 v159, v241, v237
	v_mul_f32_e32 v250, v242, v238
	v_mul_f32_e32 v251, v243, v239
	v_cvt_pk_bf16_f32 v158, v158, v159
	v_cvt_pk_bf16_f32 v159, v250, v251
	s_nop 1
	v_permlane16_swap_b32_e32 v156, v158
	v_permlane16_swap_b32_e32 v157, v159
	global_store_dwordx4 v254, v[156:159], s[28:29] offset:192
	ds_bpermute_b32 v158, v248, v161
	s_waitcnt lgkmcnt(0)
	v_add_f32_e32 v161, v161, v158
	ds_bpermute_b32 v158, v249, v161
	s_waitcnt lgkmcnt(0)
	v_add_f32_e32 v161, v161, v158
	global_store_dword v247, v161, s[30:31] offset:4
	s_add_u32 s26, s26, 0x10000
	s_addc_u32 s27, s27, 0
	s_add_u32 s28, s28, 0x8000
	s_addc_u32 s29, s29, 0
	s_add_u32 s30, s30, 0x400
	s_addc_u32 s31, s31, 0
	s_branch .LBB0_23

.LBB0_362:
	s_lshr_b32 s4, s20, 2
	s_and_b32 s4, s4, 24
	s_and_b32 s5, s20, 7
	s_or_b32 s4, s4, s5
	s_lshl_b32 s4, s4, 10
	v_mov_b32 v8, v198
	s_or_b32 s4, s4, s65
	v_ashrrev_i32_e32 v12, 2, v8
	v_add_u32_e32 v0, s4, v12
	s_waitcnt lgkmcnt(0)
	v_ashrrev_i32_e32 v1, 31, v0
	s_lshl_b32 s5, s20, 5
	v_lshlrev_b64 v[0:1], 6, v[0:1]
	v_lshlrev_b32_e32 v2, 4, v8
	s_and_b32 s5, s5, 0x300
	v_lshl_add_u64 v[0:1], s[92:93], 0, v[0:1]
	v_and_b32_e32 v152, 48, v2
	v_lshl_add_u64 v[14:15], v[0:1], 0, v[152:153]
	v_add_u32_e32 v0, s5, v12
	v_ashrrev_i32_e32 v1, 31, v0
	v_lshlrev_b64 v[0:1], 6, v[0:1]
	s_mov_b32 s12, 0x80000
	v_lshl_add_u64 v[0:1], s[6:7], 0, v[0:1]
	v_add_co_u32_e32 v54, vcc, s12, v14
	v_lshl_add_u64 v[0:1], v[0:1], 0, v[152:153]
	s_nop 0
	v_addc_co_u32_e32 v55, vcc, 0, v15, vcc
	s_lshl_b32 s13, s19, 13
	s_lshl_b32 s21, s20, 8
	s_and_b32 s22, s18, 7
	v_lshrrev_b32_e32 v6, 2, v8
	v_add_co_u32_e32 v2, vcc, s12, v0
	s_and_b32 s13, s13, 0x600000
	s_and_b32 s21, s21, 0x6000
	s_lshl_b32 s24, s22, 10
	v_and_b32_e32 v6, 12, v6
	s_movk_i32 s22, 0x1230
	v_addc_co_u32_e32 v3, vcc, 0, v1, vcc
	s_mov_b32 s12, 0x100000
	v_lshrrev_b32_e64 v10, v6, s22
	s_add_u32 s22, s15, s13
	v_add_co_u32_e32 v4, vcc, s12, v0
	s_addc_u32 s23, s16, 0
	s_or_b32 s13, s24, s21
	v_addc_co_u32_e32 v5, vcc, 0, v1, vcc
	s_mov_b32 s12, 0x180000
	v_and_b32_e32 v22, 3, v8
	v_ashrrev_i32_e32 v13, 31, v12
	v_xor_b32_e32 v8, v10, v8
	s_or_b32 s13, s13, s65
	v_add_co_u32_e32 v20, vcc, s12, v0
	v_lshlrev_b32_e32 v9, 6, v12
	v_lshlrev_b64 v[6:7], 13, v[12:13]
	v_lshlrev_b32_e32 v8, 4, v8
	v_add_u32_e32 v12, s13, v12
	v_addc_co_u32_e32 v21, vcc, 0, v1, vcc
	s_nop 0
	v_readfirstlane_b32 s26, v14
	v_readfirstlane_b32 s27, v15
	v_readfirstlane_b32 s28, v0
	v_readfirstlane_b32 s29, v1
	v_lshrrev_b32_e32 v250, 6, v198
	s_nop 0
	v_readfirstlane_b32 s24, v250
	s_lshl_b32 s24, s24, 10
	v_lshrrev_b32_e32 v250, 2, v200
	v_lshrrev_b32_e32 v251, 4, v200
	v_lshlrev_b32_e32 v251, 2, v251
	v_mov_b32_e32 v248, 0x1230
	v_lshrrev_b32_e32 v251, v251, v248
	v_xor_b32_e32 v251, v251, v200
	v_and_b32_e32 v251, 3, v251
	v_lshlrev_b32_e32 v251, 4, v251
	v_lshl_add_u32 v244, v250, 13, v251
	v_add_u32_e32 v245, 0x80000, v244
	v_add_u32_e32 v246, 0x100000, v244
	v_add_u32_e32 v247, 0x180000, v244
	v_lshl_add_u32 v156, v250, 6, v251
	v_add_u32_e32 v157, 0x1000, v156
	v_add_u32_e32 v158, 0x2000, v156
	v_add_u32_e32 v159, 0x3000, v156
	s_mov_b32 s25, 0
	s_add_u32 m0, s25, s24
	s_nop 0
	global_load_lds_dwordx4 v156, s[26:27]
	s_add_u32 m0, m0, 0x1000
	s_nop 0
	global_load_lds_dwordx4 v157, s[26:27]
	s_add_u32 m0, m0, 0x1000
	s_nop 0
	global_load_lds_dwordx4 v156, s[28:29]
	s_add_u32 m0, m0, 0x1000
	s_nop 0
	global_load_lds_dwordx4 v157, s[28:29]
	s_add_u32 m0, m0, 0x1000
	s_nop 0
	global_load_lds_dwordx4 v158, s[28:29]
	s_add_u32 m0, m0, 0x1000
	s_nop 0
	global_load_lds_dwordx4 v159, s[28:29]
	s_add_u32 s26, s26, 0x200000
	s_addc_u32 s27, s27, 0
	s_add_u32 s28, s28, 0x10000
	s_addc_u32 s29, s29, 0
	s_add_u32 s25, s25, 24576
	s_cmp_eq_u32 s25, 73728
	s_cselect_b32 s25, 0, s25
	s_add_u32 m0, s25, s24
	s_nop 0
	global_load_lds_dwordx4 v156, s[26:27]
	s_add_u32 m0, m0, 0x1000
	s_nop 0
	global_load_lds_dwordx4 v157, s[26:27]
	s_add_u32 m0, m0, 0x1000
	s_nop 0
	global_load_lds_dwordx4 v156, s[28:29]
	s_add_u32 m0, m0, 0x1000
	s_nop 0
	global_load_lds_dwordx4 v157, s[28:29]
	s_add_u32 m0, m0, 0x1000
	s_nop 0
	global_load_lds_dwordx4 v158, s[28:29]
	s_add_u32 m0, m0, 0x1000
	s_nop 0
	global_load_lds_dwordx4 v159, s[28:29]
	s_add_u32 s26, s26, 0x200000
	s_addc_u32 s27, s27, 0
	s_add_u32 s28, s28, 0x10000
	s_addc_u32 s29, s29, 0
	s_add_u32 s25, s25, 24576
	s_cmp_eq_u32 s25, 73728
	s_cselect_b32 s25, 0, s25
	s_add_u32 m0, s25, s24
	s_nop 0
	global_load_lds_dwordx4 v156, s[26:27]
	s_add_u32 m0, m0, 0x1000
	s_nop 0
	global_load_lds_dwordx4 v157, s[26:27]
	s_add_u32 m0, m0, 0x1000
	s_nop 0
	global_load_lds_dwordx4 v156, s[28:29]
	s_add_u32 m0, m0, 0x1000
	s_nop 0
	global_load_lds_dwordx4 v157, s[28:29]
	s_add_u32 m0, m0, 0x1000
	s_nop 0
	global_load_lds_dwordx4 v158, s[28:29]
	s_add_u32 m0, m0, 0x1000
	s_nop 0
	global_load_lds_dwordx4 v159, s[28:29]
	s_add_u32 s26, s26, 0x200000
	s_addc_u32 s27, s27, 0
	s_add_u32 s28, s28, 0x10000
	s_addc_u32 s29, s29, 0
	s_add_u32 s25, s25, 24576
	s_cmp_eq_u32 s25, 73728
	s_cselect_b32 s25, 0, s25
	v_mov_b32_e32 v24, 0
	v_mov_b32_e32 v25, v24
	v_mov_b32_e32 v26, v24
	v_mov_b32_e32 v27, v24
	v_mov_b32_e32 v28, v24
	v_mov_b32_e32 v29, v24
	v_mov_b32_e32 v54, v24
	v_mov_b32_e32 v55, v24
	v_mov_b32_e32 v56, v24
	v_mov_b32_e32 v57, v24
	v_mov_b32_e32 v58, v24
	v_mov_b32_e32 v59, v24
	v_mov_b32_e32 v64, v24
	v_mov_b32_e32 v65, v24
	v_mov_b32_e32 v66, v24
	v_mov_b32_e32 v67, v24
	v_mov_b32_e32 v68, v24
	v_mov_b32_e32 v69, v24
	v_mov_b32_e32 v70, v24
	v_mov_b32_e32 v71, v24
	v_mov_b32_e32 v60, v24
	v_mov_b32_e32 v61, v24
	v_mov_b32_e32 v62, v24
	v_mov_b32_e32 v63, v24
	v_mov_b32_e32 v100, v24
	v_mov_b32_e32 v30, v24
	v_mov_b32_e32 v31, v24
	v_mov_b32_e32 v32, v24
	v_mov_b32_e32 v33, v24
	v_mov_b32_e32 v34, v24
	v_mov_b32_e32 v35, v24
	v_mov_b32_e32 v36, v24
	v_mov_b32_e32 v37, v24
	v_mov_b32_e32 v38, v24
	v_mov_b32_e32 v39, v24
	v_mov_b32_e32 v52, v24
	v_mov_b32_e32 v53, v24
	v_mov_b32_e32 v40, v24
	v_mov_b32_e32 v41, v24
	v_mov_b32_e32 v42, v24
	v_mov_b32_e32 v43, v24
	v_mov_b32_e32 v44, v24
	v_mov_b32_e32 v45, v24
	v_mov_b32_e32 v46, v24
	v_mov_b32_e32 v47, v24
	v_mov_b32_e32 v48, v24
	v_mov_b32_e32 v49, v24
	v_mov_b32_e32 v50, v24
	v_mov_b32_e32 v51, v24
	v_mov_b32_e32 v101, v24
	v_mov_b32_e32 v102, v24
	v_mov_b32_e32 v103, v24
	v_mov_b32_e32 v104, v24
	v_mov_b32_e32 v105, v24
	v_mov_b32_e32 v106, v24
	v_mov_b32_e32 v107, v24
	v_mov_b32_e32 v120, v24
	v_mov_b32_e32 v121, v24
	v_mov_b32_e32 v122, v24
	v_mov_b32_e32 v123, v24
	v_mov_b32_e32 v128, v24
	v_mov_b32_e32 v129, v24
	v_mov_b32_e32 v130, v24
	v_mov_b32_e32 v131, v24
	v_mov_b32_e32 v108, v24
	v_mov_b32_e32 v109, v24
	v_mov_b32_e32 v110, v24
	v_mov_b32_e32 v111, v24
	v_mov_b32_e32 v112, v24
	v_mov_b32_e32 v113, v24
	v_mov_b32_e32 v114, v24
	v_mov_b32_e32 v115, v24
	v_mov_b32_e32 v116, v24
	v_mov_b32_e32 v117, v24
	v_mov_b32_e32 v118, v24
	v_mov_b32_e32 v119, v24
	v_mov_b32_e32 v124, v24
	v_mov_b32_e32 v125, v24
	v_mov_b32_e32 v126, v24
	v_mov_b32_e32 v127, v24
	v_mov_b32_e32 v80, v24
	v_mov_b32_e32 v81, v24
	v_mov_b32_e32 v82, v24
	v_mov_b32_e32 v83, v24
	v_mov_b32_e32 v84, v24
	v_mov_b32_e32 v85, v24
	v_mov_b32_e32 v86, v24
	v_mov_b32_e32 v87, v24
	v_mov_b32_e32 v96, v24
	v_mov_b32_e32 v97, v24
	v_mov_b32_e32 v98, v24
	v_mov_b32_e32 v99, v24
	v_mov_b32_e32 v72, v24
	v_mov_b32_e32 v73, v24
	v_mov_b32_e32 v74, v24
	v_mov_b32_e32 v75, v24
	v_mov_b32_e32 v132, v24
	v_mov_b32_e32 v133, v24
	v_mov_b32_e32 v134, v24
	v_mov_b32_e32 v135, v24
	v_mov_b32_e32 v136, v24
	v_mov_b32_e32 v137, v24
	v_mov_b32_e32 v138, v24
	v_mov_b32_e32 v139, v24
	v_mov_b32_e32 v140, v24
	v_mov_b32_e32 v141, v24
	v_mov_b32_e32 v142, v24
	v_mov_b32_e32 v143, v24
	v_mov_b32_e32 v144, v24
	v_mov_b32_e32 v145, v24
	v_mov_b32_e32 v146, v24
	v_mov_b32_e32 v147, v24
	v_mov_b32_e32 v92, v24
	v_mov_b32_e32 v93, v24
	v_mov_b32_e32 v94, v24
	v_mov_b32_e32 v95, v24
	v_mov_b32_e32 v88, v24
	v_mov_b32_e32 v89, v24
	v_mov_b32_e32 v90, v24
	v_mov_b32_e32 v91, v24
	v_mov_b32_e32 v76, v24
	v_mov_b32_e32 v77, v24
	v_mov_b32_e32 v78, v24
	v_mov_b32_e32 v79, v24
	v_mov_b32_e32 v148, v24
	v_mov_b32_e32 v149, v24
	v_mov_b32_e32 v150, v24
	v_mov_b32_e32 v151, v24
	s_waitcnt vmcnt(12)
	s_barrier
	s_mov_b32 s30, 0
	v_add_u32_e32 v248, s30, v155
	v_add_u32_e32 v249, s30, v160
	ds_read_b128 v[186:189], v248
	ds_read_b128 v[212:215], v249 offset:8192
	ds_read_b128 v[190:193], v248 offset:1024
	ds_read_b128 v[216:219], v249 offset:9216
	ds_read_b128 v[194:197], v248 offset:2048
	ds_read_b128 v[220:223], v249 offset:10240
	ds_read_b128 v[208:211], v248 offset:3072
	ds_read_b128 v[224:227], v249 offset:11264
	ds_read_b128 v[228:231], v249 offset:12288
	ds_read_b128 v[232:235], v249 offset:13312
	ds_read_b128 v[236:239], v249 offset:14336
	ds_read_b128 v[240:243], v249 offset:15360
	s_add_u32 s30, s30, 24576
	s_cmp_eq_u32 s30, 73728
	s_cselect_b32 s30, 0, s30
	s_waitcnt vmcnt(6)
	s_waitcnt lgkmcnt(0)
	s_barrier
	s_mov_b32 s31, 62
.Lgm2_loop:
	v_add_u32_e32 v248, s30, v155
	v_add_u32_e32 v249, s30, v160
	v_mfma_f32_16x16x32_bf16 v[128:131], v[212:215], v[186:189], v[128:131]
	ds_read_b128 v[0:3], v248
	v_mfma_f32_16x16x32_bf16 v[68:71], v[212:215], v[190:193], v[68:71]
	ds_read_b128 v[16:19], v249 offset:8192
	v_mfma_f32_16x16x32_bf16 v[108:111], v[212:215], v[194:197], v[108:111]
	ds_read_b128 v[4:7], v248 offset:1024
	v_mfma_f32_16x16x32_bf16 v[132:135], v[212:215], v[208:211], v[132:135]
	ds_read_b128 v[20:23], v249 offset:9216
	v_mfma_f32_16x16x32_bf16 v[120:123], v[216:219], v[186:189], v[120:123]
	ds_read_b128 v[8:11], v248 offset:2048
	v_mfma_f32_16x16x32_bf16 v[64:67], v[216:219], v[190:193], v[64:67]
	ds_read_b128 v[162:165], v249 offset:10240
	v_mfma_f32_16x16x32_bf16 v[112:115], v[216:219], v[194:197], v[112:115]
	ds_read_b128 v[12:15], v248 offset:3072
	v_mfma_f32_16x16x32_bf16 v[136:139], v[216:219], v[208:211], v[136:139]
	ds_read_b128 v[166:169], v249 offset:11264
	v_mfma_f32_16x16x32_bf16 v[104:107], v[220:223], v[186:189], v[104:107]
	ds_read_b128 v[170:173], v249 offset:12288
	v_mfma_f32_16x16x32_bf16 v[56:59], v[220:223], v[190:193], v[56:59]
	ds_read_b128 v[174:177], v249 offset:13312
	v_mfma_f32_16x16x32_bf16 v[116:119], v[220:223], v[194:197], v[116:119]
	ds_read_b128 v[178:181], v249 offset:14336
	v_mfma_f32_16x16x32_bf16 v[140:143], v[220:223], v[208:211], v[140:143]
	ds_read_b128 v[182:185], v249 offset:15360
	s_add_u32 m0, s25, s24
	v_mfma_f32_16x16x32_bf16 v[100:103], v[224:227], v[186:189], v[100:103]
	global_load_lds_dwordx4 v156, s[26:27]
	v_mfma_f32_16x16x32_bf16 v[52:55], v[224:227], v[190:193], v[52:55]
	v_mfma_f32_16x16x32_bf16 v[124:127], v[224:227], v[194:197], v[124:127]
	s_add_u32 m0, m0, 0x1000
	v_mfma_f32_16x16x32_bf16 v[144:147], v[224:227], v[208:211], v[144:147]
	global_load_lds_dwordx4 v157, s[26:27]
	v_mfma_f32_16x16x32_bf16 v[60:63], v[228:231], v[186:189], v[60:63]
	v_mfma_f32_16x16x32_bf16 v[36:39], v[228:231], v[190:193], v[36:39]
	s_add_u32 m0, m0, 0x1000
	v_mfma_f32_16x16x32_bf16 v[80:83], v[228:231], v[194:197], v[80:83]
	global_load_lds_dwordx4 v156, s[28:29]
	v_mfma_f32_16x16x32_bf16 v[92:95], v[228:231], v[208:211], v[92:95]
	v_mfma_f32_16x16x32_bf16 v[48:51], v[232:235], v[186:189], v[48:51]
	s_add_u32 m0, m0, 0x1000
	v_mfma_f32_16x16x32_bf16 v[32:35], v[232:235], v[190:193], v[32:35]
	global_load_lds_dwordx4 v157, s[28:29]
	v_mfma_f32_16x16x32_bf16 v[84:87], v[232:235], v[194:197], v[84:87]
	v_mfma_f32_16x16x32_bf16 v[88:91], v[232:235], v[208:211], v[88:91]
	s_add_u32 m0, m0, 0x1000
	v_mfma_f32_16x16x32_bf16 v[44:47], v[236:239], v[186:189], v[44:47]
	global_load_lds_dwordx4 v158, s[28:29]
	v_mfma_f32_16x16x32_bf16 v[28:31], v[236:239], v[190:193], v[28:31]
	v_mfma_f32_16x16x32_bf16 v[96:99], v[236:239], v[194:197], v[96:99]
	s_add_u32 m0, m0, 0x1000
	v_mfma_f32_16x16x32_bf16 v[76:79], v[236:239], v[208:211], v[76:79]
	global_load_lds_dwordx4 v159, s[28:29]
	v_mfma_f32_16x16x32_bf16 v[40:43], v[240:243], v[186:189], v[40:43]
	v_mfma_f32_16x16x32_bf16 v[24:27], v[240:243], v[190:193], v[24:27]
	v_mfma_f32_16x16x32_bf16 v[72:75], v[240:243], v[194:197], v[72:75]
	v_mfma_f32_16x16x32_bf16 v[148:151], v[240:243], v[208:211], v[148:151]
	s_add_u32 s26, s26, 0x200000
	s_addc_u32 s27, s27, 0
	s_add_u32 s28, s28, 0x10000
	s_addc_u32 s29, s29, 0
	s_add_u32 s25, s25, 24576
	s_cmp_eq_u32 s25, 73728
	s_cselect_b32 s25, 0, s25
	s_add_u32 s30, s30, 24576
	s_cmp_eq_u32 s30, 73728
	s_cselect_b32 s30, 0, s30
	s_waitcnt vmcnt(6)
	s_waitcnt lgkmcnt(0)
	s_barrier
	v_add_u32_e32 v248, s30, v155
	v_add_u32_e32 v249, s30, v160
	v_mfma_f32_16x16x32_bf16 v[128:131], v[16:19], v[0:3], v[128:131]
	ds_read_b128 v[186:189], v248
	v_mfma_f32_16x16x32_bf16 v[68:71], v[16:19], v[4:7], v[68:71]
	ds_read_b128 v[212:215], v249 offset:8192
	v_mfma_f32_16x16x32_bf16 v[108:111], v[16:19], v[8:11], v[108:111]
	ds_read_b128 v[190:193], v248 offset:1024
	v_mfma_f32_16x16x32_bf16 v[132:135], v[16:19], v[12:15], v[132:135]
	ds_read_b128 v[216:219], v249 offset:9216
	v_mfma_f32_16x16x32_bf16 v[120:123], v[20:23], v[0:3], v[120:123]
	ds_read_b128 v[194:197], v248 offset:2048
	v_mfma_f32_16x16x32_bf16 v[64:67], v[20:23], v[4:7], v[64:67]
	ds_read_b128 v[220:223], v249 offset:10240
	v_mfma_f32_16x16x32_bf16 v[112:115], v[20:23], v[8:11], v[112:115]
	ds_read_b128 v[208:211], v248 offset:3072
	v_mfma_f32_16x16x32_bf16 v[136:139], v[20:23], v[12:15], v[136:139]
	ds_read_b128 v[224:227], v249 offset:11264
	v_mfma_f32_16x16x32_bf16 v[104:107], v[162:165], v[0:3], v[104:107]
	ds_read_b128 v[228:231], v249 offset:12288
	v_mfma_f32_16x16x32_bf16 v[56:59], v[162:165], v[4:7], v[56:59]
	ds_read_b128 v[232:235], v249 offset:13312
	v_mfma_f32_16x16x32_bf16 v[116:119], v[162:165], v[8:11], v[116:119]
	ds_read_b128 v[236:239], v249 offset:14336
	v_mfma_f32_16x16x32_bf16 v[140:143], v[162:165], v[12:15], v[140:143]
	ds_read_b128 v[240:243], v249 offset:15360
	s_add_u32 m0, s25, s24
	v_mfma_f32_16x16x32_bf16 v[100:103], v[166:169], v[0:3], v[100:103]
	global_load_lds_dwordx4 v156, s[26:27]
	v_mfma_f32_16x16x32_bf16 v[52:55], v[166:169], v[4:7], v[52:55]
	v_mfma_f32_16x16x32_bf16 v[124:127], v[166:169], v[8:11], v[124:127]
	s_add_u32 m0, m0, 0x1000
	v_mfma_f32_16x16x32_bf16 v[144:147], v[166:169], v[12:15], v[144:147]
	global_load_lds_dwordx4 v157, s[26:27]
	v_mfma_f32_16x16x32_bf16 v[60:63], v[170:173], v[0:3], v[60:63]
	v_mfma_f32_16x16x32_bf16 v[36:39], v[170:173], v[4:7], v[36:39]
	s_add_u32 m0, m0, 0x1000
	v_mfma_f32_16x16x32_bf16 v[80:83], v[170:173], v[8:11], v[80:83]
	global_load_lds_dwordx4 v156, s[28:29]
	v_mfma_f32_16x16x32_bf16 v[92:95], v[170:173], v[12:15], v[92:95]
	v_mfma_f32_16x16x32_bf16 v[48:51], v[174:177], v[0:3], v[48:51]
	s_add_u32 m0, m0, 0x1000
	v_mfma_f32_16x16x32_bf16 v[32:35], v[174:177], v[4:7], v[32:35]
	global_load_lds_dwordx4 v157, s[28:29]
	v_mfma_f32_16x16x32_bf16 v[84:87], v[174:177], v[8:11], v[84:87]
	v_mfma_f32_16x16x32_bf16 v[88:91], v[174:177], v[12:15], v[88:91]
	s_add_u32 m0, m0, 0x1000
	v_mfma_f32_16x16x32_bf16 v[44:47], v[178:181], v[0:3], v[44:47]
	global_load_lds_dwordx4 v158, s[28:29]
	v_mfma_f32_16x16x32_bf16 v[28:31], v[178:181], v[4:7], v[28:31]
	v_mfma_f32_16x16x32_bf16 v[96:99], v[178:181], v[8:11], v[96:99]
	s_add_u32 m0, m0, 0x1000
	v_mfma_f32_16x16x32_bf16 v[76:79], v[178:181], v[12:15], v[76:79]
	global_load_lds_dwordx4 v159, s[28:29]
	v_mfma_f32_16x16x32_bf16 v[40:43], v[182:185], v[0:3], v[40:43]
	v_mfma_f32_16x16x32_bf16 v[24:27], v[182:185], v[4:7], v[24:27]
	v_mfma_f32_16x16x32_bf16 v[72:75], v[182:185], v[8:11], v[72:75]
	v_mfma_f32_16x16x32_bf16 v[148:151], v[182:185], v[12:15], v[148:151]
	s_add_u32 s26, s26, 0x200000
	s_addc_u32 s27, s27, 0
	s_add_u32 s28, s28, 0x10000
	s_addc_u32 s29, s29, 0
	s_add_u32 s25, s25, 24576
	s_cmp_eq_u32 s25, 73728
	s_cselect_b32 s25, 0, s25
	s_add_u32 s30, s30, 24576
	s_cmp_eq_u32 s30, 73728
	s_cselect_b32 s30, 0, s30
	s_waitcnt vmcnt(6)
	s_waitcnt lgkmcnt(0)
	s_barrier
	s_sub_u32 s31, s31, 1
	s_cmp_lg_u32 s31, 0
	s_cbranch_scc1 .Lgm2_loop
	v_add_u32_e32 v248, s30, v155
	v_add_u32_e32 v249, s30, v160
	v_mfma_f32_16x16x32_bf16 v[128:131], v[212:215], v[186:189], v[128:131]
	ds_read_b128 v[0:3], v248
	v_mfma_f32_16x16x32_bf16 v[68:71], v[212:215], v[190:193], v[68:71]
	ds_read_b128 v[16:19], v249 offset:8192
	v_mfma_f32_16x16x32_bf16 v[108:111], v[212:215], v[194:197], v[108:111]
	ds_read_b128 v[4:7], v248 offset:1024
	v_mfma_f32_16x16x32_bf16 v[132:135], v[212:215], v[208:211], v[132:135]
	ds_read_b128 v[20:23], v249 offset:9216
	v_mfma_f32_16x16x32_bf16 v[120:123], v[216:219], v[186:189], v[120:123]
	ds_read_b128 v[8:11], v248 offset:2048
	v_mfma_f32_16x16x32_bf16 v[64:67], v[216:219], v[190:193], v[64:67]
	ds_read_b128 v[162:165], v249 offset:10240
	v_mfma_f32_16x16x32_bf16 v[112:115], v[216:219], v[194:197], v[112:115]
	ds_read_b128 v[12:15], v248 offset:3072
	v_mfma_f32_16x16x32_bf16 v[136:139], v[216:219], v[208:211], v[136:139]
	ds_read_b128 v[166:169], v249 offset:11264
	v_mfma_f32_16x16x32_bf16 v[104:107], v[220:223], v[186:189], v[104:107]
	ds_read_b128 v[170:173], v249 offset:12288
	v_mfma_f32_16x16x32_bf16 v[56:59], v[220:223], v[190:193], v[56:59]
	ds_read_b128 v[174:177], v249 offset:13312
	v_mfma_f32_16x16x32_bf16 v[116:119], v[220:223], v[194:197], v[116:119]
	ds_read_b128 v[178:181], v249 offset:14336
	v_mfma_f32_16x16x32_bf16 v[140:143], v[220:223], v[208:211], v[140:143]
	ds_read_b128 v[182:185], v249 offset:15360
	s_add_u32 m0, s25, s24
	v_mfma_f32_16x16x32_bf16 v[100:103], v[224:227], v[186:189], v[100:103]
	global_load_lds_dwordx4 v156, s[26:27]
	v_mfma_f32_16x16x32_bf16 v[52:55], v[224:227], v[190:193], v[52:55]
	v_mfma_f32_16x16x32_bf16 v[124:127], v[224:227], v[194:197], v[124:127]
	s_add_u32 m0, m0, 0x1000
	v_mfma_f32_16x16x32_bf16 v[144:147], v[224:227], v[208:211], v[144:147]
	global_load_lds_dwordx4 v157, s[26:27]
	v_mfma_f32_16x16x32_bf16 v[60:63], v[228:231], v[186:189], v[60:63]
	v_mfma_f32_16x16x32_bf16 v[36:39], v[228:231], v[190:193], v[36:39]
	s_add_u32 m0, m0, 0x1000
	v_mfma_f32_16x16x32_bf16 v[80:83], v[228:231], v[194:197], v[80:83]
	global_load_lds_dwordx4 v156, s[28:29]
	v_mfma_f32_16x16x32_bf16 v[92:95], v[228:231], v[208:211], v[92:95]
	v_mfma_f32_16x16x32_bf16 v[48:51], v[232:235], v[186:189], v[48:51]
	s_add_u32 m0, m0, 0x1000
	v_mfma_f32_16x16x32_bf16 v[32:35], v[232:235], v[190:193], v[32:35]
	global_load_lds_dwordx4 v157, s[28:29]
	v_mfma_f32_16x16x32_bf16 v[84:87], v[232:235], v[194:197], v[84:87]
	v_mfma_f32_16x16x32_bf16 v[88:91], v[232:235], v[208:211], v[88:91]
	s_add_u32 m0, m0, 0x1000
	v_mfma_f32_16x16x32_bf16 v[44:47], v[236:239], v[186:189], v[44:47]
	global_load_lds_dwordx4 v158, s[28:29]
	v_mfma_f32_16x16x32_bf16 v[28:31], v[236:239], v[190:193], v[28:31]
	v_mfma_f32_16x16x32_bf16 v[96:99], v[236:239], v[194:197], v[96:99]
	s_add_u32 m0, m0, 0x1000
	v_mfma_f32_16x16x32_bf16 v[76:79], v[236:239], v[208:211], v[76:79]
	global_load_lds_dwordx4 v159, s[28:29]
	v_mfma_f32_16x16x32_bf16 v[40:43], v[240:243], v[186:189], v[40:43]
	v_mfma_f32_16x16x32_bf16 v[24:27], v[240:243], v[190:193], v[24:27]
	v_mfma_f32_16x16x32_bf16 v[72:75], v[240:243], v[194:197], v[72:75]
	v_mfma_f32_16x16x32_bf16 v[148:151], v[240:243], v[208:211], v[148:151]
	s_add_u32 s26, s26, 0x200000
	s_addc_u32 s27, s27, 0
	s_add_u32 s28, s28, 0x10000
	s_addc_u32 s29, s29, 0
	s_add_u32 s25, s25, 24576
	s_cmp_eq_u32 s25, 73728
	s_cselect_b32 s25, 0, s25
	s_add_u32 s30, s30, 24576
	s_cmp_eq_u32 s30, 73728
	s_cselect_b32 s30, 0, s30
	s_waitcnt vmcnt(6)
	s_waitcnt lgkmcnt(0)
	s_barrier
	v_add_u32_e32 v248, s30, v155
	v_add_u32_e32 v249, s30, v160
	v_mfma_f32_16x16x32_bf16 v[128:131], v[16:19], v[0:3], v[128:131]
	ds_read_b128 v[186:189], v248
	v_mfma_f32_16x16x32_bf16 v[68:71], v[16:19], v[4:7], v[68:71]
	ds_read_b128 v[212:215], v249 offset:8192
	v_mfma_f32_16x16x32_bf16 v[108:111], v[16:19], v[8:11], v[108:111]
	ds_read_b128 v[190:193], v248 offset:1024
	v_mfma_f32_16x16x32_bf16 v[132:135], v[16:19], v[12:15], v[132:135]
	ds_read_b128 v[216:219], v249 offset:9216
	v_mfma_f32_16x16x32_bf16 v[120:123], v[20:23], v[0:3], v[120:123]
	ds_read_b128 v[194:197], v248 offset:2048
	v_mfma_f32_16x16x32_bf16 v[64:67], v[20:23], v[4:7], v[64:67]
	ds_read_b128 v[220:223], v249 offset:10240
	v_mfma_f32_16x16x32_bf16 v[112:115], v[20:23], v[8:11], v[112:115]
	ds_read_b128 v[208:211], v248 offset:3072
	v_mfma_f32_16x16x32_bf16 v[136:139], v[20:23], v[12:15], v[136:139]
	ds_read_b128 v[224:227], v249 offset:11264
	v_mfma_f32_16x16x32_bf16 v[104:107], v[162:165], v[0:3], v[104:107]
	ds_read_b128 v[228:231], v249 offset:12288
	v_mfma_f32_16x16x32_bf16 v[56:59], v[162:165], v[4:7], v[56:59]
	ds_read_b128 v[232:235], v249 offset:13312
	v_mfma_f32_16x16x32_bf16 v[116:119], v[162:165], v[8:11], v[116:119]
	ds_read_b128 v[236:239], v249 offset:14336
	v_mfma_f32_16x16x32_bf16 v[140:143], v[162:165], v[12:15], v[140:143]
	ds_read_b128 v[240:243], v249 offset:15360
	v_mfma_f32_16x16x32_bf16 v[100:103], v[166:169], v[0:3], v[100:103]
	v_mfma_f32_16x16x32_bf16 v[52:55], v[166:169], v[4:7], v[52:55]
	v_mfma_f32_16x16x32_bf16 v[124:127], v[166:169], v[8:11], v[124:127]
	v_mfma_f32_16x16x32_bf16 v[144:147], v[166:169], v[12:15], v[144:147]
	v_mfma_f32_16x16x32_bf16 v[60:63], v[170:173], v[0:3], v[60:63]
	v_mfma_f32_16x16x32_bf16 v[36:39], v[170:173], v[4:7], v[36:39]
	v_mfma_f32_16x16x32_bf16 v[80:83], v[170:173], v[8:11], v[80:83]
	v_mfma_f32_16x16x32_bf16 v[92:95], v[170:173], v[12:15], v[92:95]
	v_mfma_f32_16x16x32_bf16 v[48:51], v[174:177], v[0:3], v[48:51]
	v_mfma_f32_16x16x32_bf16 v[32:35], v[174:177], v[4:7], v[32:35]
	v_mfma_f32_16x16x32_bf16 v[84:87], v[174:177], v[8:11], v[84:87]
	v_mfma_f32_16x16x32_bf16 v[88:91], v[174:177], v[12:15], v[88:91]
	v_mfma_f32_16x16x32_bf16 v[44:47], v[178:181], v[0:3], v[44:47]
	v_mfma_f32_16x16x32_bf16 v[28:31], v[178:181], v[4:7], v[28:31]
	v_mfma_f32_16x16x32_bf16 v[96:99], v[178:181], v[8:11], v[96:99]
	v_mfma_f32_16x16x32_bf16 v[76:79], v[178:181], v[12:15], v[76:79]
	v_mfma_f32_16x16x32_bf16 v[40:43], v[182:185], v[0:3], v[40:43]
	v_mfma_f32_16x16x32_bf16 v[24:27], v[182:185], v[4:7], v[24:27]
	v_mfma_f32_16x16x32_bf16 v[72:75], v[182:185], v[8:11], v[72:75]
	v_mfma_f32_16x16x32_bf16 v[148:151], v[182:185], v[12:15], v[148:151]
	s_add_u32 s30, s30, 24576
	s_cmp_eq_u32 s30, 73728
	s_cselect_b32 s30, 0, s30
	s_waitcnt vmcnt(0)
	s_waitcnt lgkmcnt(0)
	s_barrier
	v_add_u32_e32 v248, s30, v155
	v_add_u32_e32 v249, s30, v160
	v_mfma_f32_16x16x32_bf16 v[128:131], v[212:215], v[186:189], v[128:131]
	ds_read_b128 v[0:3], v248
	v_mfma_f32_16x16x32_bf16 v[68:71], v[212:215], v[190:193], v[68:71]
	ds_read_b128 v[16:19], v249 offset:8192
	v_mfma_f32_16x16x32_bf16 v[108:111], v[212:215], v[194:197], v[108:111]
	ds_read_b128 v[4:7], v248 offset:1024
	v_mfma_f32_16x16x32_bf16 v[132:135], v[212:215], v[208:211], v[132:135]
	ds_read_b128 v[20:23], v249 offset:9216
	v_mfma_f32_16x16x32_bf16 v[120:123], v[216:219], v[186:189], v[120:123]
	ds_read_b128 v[8:11], v248 offset:2048
	v_mfma_f32_16x16x32_bf16 v[64:67], v[216:219], v[190:193], v[64:67]
	ds_read_b128 v[162:165], v249 offset:10240
	v_mfma_f32_16x16x32_bf16 v[112:115], v[216:219], v[194:197], v[112:115]
	ds_read_b128 v[12:15], v248 offset:3072
	v_mfma_f32_16x16x32_bf16 v[136:139], v[216:219], v[208:211], v[136:139]
	ds_read_b128 v[166:169], v249 offset:11264
	v_mfma_f32_16x16x32_bf16 v[104:107], v[220:223], v[186:189], v[104:107]
	ds_read_b128 v[170:173], v249 offset:12288
	v_mfma_f32_16x16x32_bf16 v[56:59], v[220:223], v[190:193], v[56:59]
	ds_read_b128 v[174:177], v249 offset:13312
	v_mfma_f32_16x16x32_bf16 v[116:119], v[220:223], v[194:197], v[116:119]
	ds_read_b128 v[178:181], v249 offset:14336
	v_mfma_f32_16x16x32_bf16 v[140:143], v[220:223], v[208:211], v[140:143]
	ds_read_b128 v[182:185], v249 offset:15360
	v_mfma_f32_16x16x32_bf16 v[100:103], v[224:227], v[186:189], v[100:103]
	v_mfma_f32_16x16x32_bf16 v[52:55], v[224:227], v[190:193], v[52:55]
	v_mfma_f32_16x16x32_bf16 v[124:127], v[224:227], v[194:197], v[124:127]
	v_mfma_f32_16x16x32_bf16 v[144:147], v[224:227], v[208:211], v[144:147]
	v_mfma_f32_16x16x32_bf16 v[60:63], v[228:231], v[186:189], v[60:63]
	v_mfma_f32_16x16x32_bf16 v[36:39], v[228:231], v[190:193], v[36:39]
	v_mfma_f32_16x16x32_bf16 v[80:83], v[228:231], v[194:197], v[80:83]
	v_mfma_f32_16x16x32_bf16 v[92:95], v[228:231], v[208:211], v[92:95]
	v_mfma_f32_16x16x32_bf16 v[48:51], v[232:235], v[186:189], v[48:51]
	v_mfma_f32_16x16x32_bf16 v[32:35], v[232:235], v[190:193], v[32:35]
	v_mfma_f32_16x16x32_bf16 v[84:87], v[232:235], v[194:197], v[84:87]
	v_mfma_f32_16x16x32_bf16 v[88:91], v[232:235], v[208:211], v[88:91]
	v_mfma_f32_16x16x32_bf16 v[44:47], v[236:239], v[186:189], v[44:47]
	v_mfma_f32_16x16x32_bf16 v[28:31], v[236:239], v[190:193], v[28:31]
	v_mfma_f32_16x16x32_bf16 v[96:99], v[236:239], v[194:197], v[96:99]
	v_mfma_f32_16x16x32_bf16 v[76:79], v[236:239], v[208:211], v[76:79]
	v_mfma_f32_16x16x32_bf16 v[40:43], v[240:243], v[186:189], v[40:43]
	v_mfma_f32_16x16x32_bf16 v[24:27], v[240:243], v[190:193], v[24:27]
	v_mfma_f32_16x16x32_bf16 v[72:75], v[240:243], v[194:197], v[72:75]
	v_mfma_f32_16x16x32_bf16 v[148:151], v[240:243], v[208:211], v[148:151]
	s_add_u32 s30, s30, 24576
	s_cmp_eq_u32 s30, 73728
	s_cselect_b32 s30, 0, s30
	s_waitcnt lgkmcnt(0)
	s_barrier
	v_mfma_f32_16x16x32_bf16 v[128:131], v[16:19], v[0:3], v[128:131]
	v_mfma_f32_16x16x32_bf16 v[68:71], v[16:19], v[4:7], v[68:71]
	v_mfma_f32_16x16x32_bf16 v[108:111], v[16:19], v[8:11], v[108:111]
	v_mfma_f32_16x16x32_bf16 v[132:135], v[16:19], v[12:15], v[132:135]
	v_mfma_f32_16x16x32_bf16 v[120:123], v[20:23], v[0:3], v[120:123]
	v_mfma_f32_16x16x32_bf16 v[64:67], v[20:23], v[4:7], v[64:67]
	v_mfma_f32_16x16x32_bf16 v[112:115], v[20:23], v[8:11], v[112:115]
	v_mfma_f32_16x16x32_bf16 v[136:139], v[20:23], v[12:15], v[136:139]
	v_mfma_f32_16x16x32_bf16 v[104:107], v[162:165], v[0:3], v[104:107]
	v_mfma_f32_16x16x32_bf16 v[56:59], v[162:165], v[4:7], v[56:59]
	v_mfma_f32_16x16x32_bf16 v[116:119], v[162:165], v[8:11], v[116:119]
	v_mfma_f32_16x16x32_bf16 v[140:143], v[162:165], v[12:15], v[140:143]
	v_mfma_f32_16x16x32_bf16 v[100:103], v[166:169], v[0:3], v[100:103]
	v_mfma_f32_16x16x32_bf16 v[52:55], v[166:169], v[4:7], v[52:55]
	v_mfma_f32_16x16x32_bf16 v[124:127], v[166:169], v[8:11], v[124:127]
	v_mfma_f32_16x16x32_bf16 v[144:147], v[166:169], v[12:15], v[144:147]
	v_mfma_f32_16x16x32_bf16 v[60:63], v[170:173], v[0:3], v[60:63]
	v_mfma_f32_16x16x32_bf16 v[36:39], v[170:173], v[4:7], v[36:39]
	v_mfma_f32_16x16x32_bf16 v[80:83], v[170:173], v[8:11], v[80:83]
	v_mfma_f32_16x16x32_bf16 v[92:95], v[170:173], v[12:15], v[92:95]
	v_mfma_f32_16x16x32_bf16 v[48:51], v[174:177], v[0:3], v[48:51]
	v_mfma_f32_16x16x32_bf16 v[32:35], v[174:177], v[4:7], v[32:35]
	v_mfma_f32_16x16x32_bf16 v[84:87], v[174:177], v[8:11], v[84:87]
	v_mfma_f32_16x16x32_bf16 v[88:91], v[174:177], v[12:15], v[88:91]
	v_mfma_f32_16x16x32_bf16 v[44:47], v[178:181], v[0:3], v[44:47]
	v_mfma_f32_16x16x32_bf16 v[28:31], v[178:181], v[4:7], v[28:31]
	v_mfma_f32_16x16x32_bf16 v[96:99], v[178:181], v[8:11], v[96:99]
	v_mfma_f32_16x16x32_bf16 v[76:79], v[178:181], v[12:15], v[76:79]
	v_mfma_f32_16x16x32_bf16 v[40:43], v[182:185], v[0:3], v[40:43]
	v_mfma_f32_16x16x32_bf16 v[24:27], v[182:185], v[4:7], v[24:27]
	v_mfma_f32_16x16x32_bf16 v[72:75], v[182:185], v[8:11], v[72:75]
	v_mfma_f32_16x16x32_bf16 v[148:151], v[182:185], v[12:15], v[148:151]
	v_mov_b32 v250, v198
	s_nop 0
	v_and_b32_e32 v251, 15, v250
	v_bfe_u32 v156, v250, 4, 2
	v_bfe_u32 v157, v250, 6, 1
	v_bfe_u32 v158, v250, 7, 1
	v_lshl_add_u32 v158, v158, 6, s4
	v_add_u32_e32 v158, v158, v251
	v_lshl_add_u32 v157, v157, 7, s5
	v_lshl_add_u32 v159, v156, 2, v157
	v_lshlrev_b32_e32 v246, 2, v159
	v_lshl_add_u32 v244, v158, 12, v246
	v_lshlrev_b32_e32 v161, 1, v159
	v_lshl_add_u32 v245, v158, 11, v161
	v_and_b32_e32 v254, 1, v156
	v_mul_u32_u24_e32 v254, 24, v254
	v_add_u32_e32 v254, v254, v245
	v_lshrrev_b32_e32 v161, 6, v157
	v_lshlrev_b32_e32 v161, 2, v161
	v_lshl_add_u32 v247, v158, 6, v161
	v_xor_b32_e32 v248, 16, v200
	v_lshlrev_b32_e32 v248, 2, v248
	v_xor_b32_e32 v249, 32, v200
	v_lshlrev_b32_e32 v249, 2, v249
	s_mov_b32 s24, s78
	s_mov_b32 s25, s79
	s_mov_b32 s26, s78
	s_mov_b32 s27, s79
	s_mov_b32 s28, s96
	s_mov_b32 s29, s97
	s_mov_b32 s30, s94
	s_mov_b32 s31, s95
	s_cmp_lg_u64 s[8:9], 0
	s_cbranch_scc0 .Lgm2_noemit
	global_load_dwordx4 v[208:211], v246, s[10:11]
	global_load_dwordx4 v[212:215], v246, s[10:11] offset:64
	global_load_dwordx4 v[216:219], v246, s[10:11] offset:128
	global_load_dwordx4 v[220:223], v246, s[10:11] offset:192
	global_load_dwordx4 v[224:227], v246, s[10:11] offset:256
	global_load_dwordx4 v[228:231], v246, s[10:11] offset:320
	global_load_dwordx4 v[232:235], v246, s[10:11] offset:384
	global_load_dwordx4 v[236:239], v246, s[10:11] offset:448
	global_load_dwordx4 v[0:3], v244, s[24:25]
	global_load_dwordx4 v[4:7], v244, s[24:25] offset:64
	global_load_dwordx4 v[8:11], v244, s[24:25] offset:128
	global_load_dwordx4 v[12:15], v244, s[24:25] offset:192
	global_load_dwordx4 v[16:19], v244, s[24:25] offset:256
	global_load_dwordx4 v[20:23], v244, s[24:25] offset:320
	global_load_dwordx4 v[162:165], v244, s[24:25] offset:384
	global_load_dwordx4 v[166:169], v244, s[24:25] offset:448
	s_add_u32 s24, s24, 0x10000
	s_addc_u32 s25, s25, 0
	global_load_dwordx4 v[170:173], v244, s[24:25]
	global_load_dwordx4 v[174:177], v244, s[24:25] offset:64
	global_load_dwordx4 v[178:181], v244, s[24:25] offset:128
	global_load_dwordx4 v[182:185], v244, s[24:25] offset:192
	global_load_dwordx4 v[186:189], v244, s[24:25] offset:256
	global_load_dwordx4 v[190:193], v244, s[24:25] offset:320
	global_load_dwordx4 v[194:197], v244, s[24:25] offset:384
	global_load_dwordx4 v[240:243], v244, s[24:25] offset:448
	s_add_u32 s24, s24, 0x10000
	s_addc_u32 s25, s25, 0
	s_waitcnt vmcnt(12)
	v_add_f32_e32 v0, v128, v0
	v_add_f32_e32 v1, v129, v1
	v_add_f32_e32 v2, v130, v2
	v_add_f32_e32 v3, v131, v3
	global_store_dwordx4 v244, v[0:3], s[26:27]
	v_mul_f32_e32 v158, v0, v0
	v_mul_f32_e32 v159, v1, v1
	v_mul_f32_e32 v250, v2, v2
	v_mul_f32_e32 v251, v3, v3
	v_add_f32_e32 v158, v158, v159
	v_add_f32_e32 v250, v250, v251
	v_add_f32_e32 v161, v158, v250
	v_mul_f32_e32 v156, v0, v208
	v_mul_f32_e32 v157, v1, v209
	v_mul_f32_e32 v158, v2, v210
	v_mul_f32_e32 v159, v3, v211
	v_cvt_pk_bf16_f32 v156, v156, v157
	v_cvt_pk_bf16_f32 v157, v158, v159
	v_add_f32_e32 v4, v120, v4
	v_add_f32_e32 v5, v121, v5
	v_add_f32_e32 v6, v122, v6
	v_add_f32_e32 v7, v123, v7
	global_store_dwordx4 v244, v[4:7], s[26:27] offset:64
	v_mul_f32_e32 v158, v4, v4
	v_mul_f32_e32 v159, v5, v5
	v_mul_f32_e32 v250, v6, v6
	v_mul_f32_e32 v251, v7, v7
	v_add_f32_e32 v158, v158, v159
	v_add_f32_e32 v250, v250, v251
	v_add_f32_e32 v158, v158, v250
	v_add_f32_e32 v161, v161, v158
	v_mul_f32_e32 v158, v4, v212
	v_mul_f32_e32 v159, v5, v213
	v_mul_f32_e32 v250, v6, v214
	v_mul_f32_e32 v251, v7, v215
	v_cvt_pk_bf16_f32 v158, v158, v159
	v_cvt_pk_bf16_f32 v159, v250, v251
	s_nop 1
	v_permlane16_swap_b32_e32 v156, v158
	v_permlane16_swap_b32_e32 v157, v159
	global_store_dwordx4 v254, v[156:159], s[28:29]
	v_add_f32_e32 v8, v104, v8
	v_add_f32_e32 v9, v105, v9
	v_add_f32_e32 v10, v106, v10
	v_add_f32_e32 v11, v107, v11
	global_store_dwordx4 v244, v[8:11], s[26:27] offset:128
	v_mul_f32_e32 v158, v8, v8
	v_mul_f32_e32 v159, v9, v9
	v_mul_f32_e32 v250, v10, v10
	v_mul_f32_e32 v251, v11, v11
	v_add_f32_e32 v158, v158, v159
	v_add_f32_e32 v250, v250, v251
	v_add_f32_e32 v158, v158, v250
	v_add_f32_e32 v161, v161, v158
	v_mul_f32_e32 v156, v8, v216
	v_mul_f32_e32 v157, v9, v217
	v_mul_f32_e32 v158, v10, v218
	v_mul_f32_e32 v159, v11, v219
	v_cvt_pk_bf16_f32 v156, v156, v157
	v_cvt_pk_bf16_f32 v157, v158, v159
	v_add_f32_e32 v12, v100, v12
	v_add_f32_e32 v13, v101, v13
	v_add_f32_e32 v14, v102, v14
	v_add_f32_e32 v15, v103, v15
	global_store_dwordx4 v244, v[12:15], s[26:27] offset:192
	v_mul_f32_e32 v158, v12, v12
	v_mul_f32_e32 v159, v13, v13
	v_mul_f32_e32 v250, v14, v14
	v_mul_f32_e32 v251, v15, v15
	v_add_f32_e32 v158, v158, v159
	v_add_f32_e32 v250, v250, v251
	v_add_f32_e32 v158, v158, v250
	v_add_f32_e32 v161, v161, v158
	v_mul_f32_e32 v158, v12, v220
	v_mul_f32_e32 v159, v13, v221
	v_mul_f32_e32 v250, v14, v222
	v_mul_f32_e32 v251, v15, v223
	v_cvt_pk_bf16_f32 v158, v158, v159
	v_cvt_pk_bf16_f32 v159, v250, v251
	s_nop 1
	v_permlane16_swap_b32_e32 v156, v158
	v_permlane16_swap_b32_e32 v157, v159
	global_store_dwordx4 v254, v[156:159], s[28:29] offset:64
	ds_bpermute_b32 v158, v248, v161
	s_waitcnt lgkmcnt(0)
	v_add_f32_e32 v161, v161, v158
	ds_bpermute_b32 v158, v249, v161
	s_waitcnt lgkmcnt(0)
	v_add_f32_e32 v161, v161, v158
	global_store_dword v247, v161, s[30:31]
	global_load_dwordx4 v[0:3], v244, s[24:25]
	global_load_dwordx4 v[4:7], v244, s[24:25] offset:64
	global_load_dwordx4 v[8:11], v244, s[24:25] offset:128
	global_load_dwordx4 v[12:15], v244, s[24:25] offset:192
	s_waitcnt vmcnt(19)
	v_add_f32_e32 v16, v60, v16
	v_add_f32_e32 v17, v61, v17
	v_add_f32_e32 v18, v62, v18
	v_add_f32_e32 v19, v63, v19
	global_store_dwordx4 v244, v[16:19], s[26:27] offset:256
	v_mul_f32_e32 v158, v16, v16
	v_mul_f32_e32 v159, v17, v17
	v_mul_f32_e32 v250, v18, v18
	v_mul_f32_e32 v251, v19, v19
	v_add_f32_e32 v158, v158, v159
	v_add_f32_e32 v250, v250, v251
	v_add_f32_e32 v161, v158, v250
	v_mul_f32_e32 v156, v16, v224
	v_mul_f32_e32 v157, v17, v225
	v_mul_f32_e32 v158, v18, v226
	v_mul_f32_e32 v159, v19, v227
	v_cvt_pk_bf16_f32 v156, v156, v157
	v_cvt_pk_bf16_f32 v157, v158, v159
	v_add_f32_e32 v20, v48, v20
	v_add_f32_e32 v21, v49, v21
	v_add_f32_e32 v22, v50, v22
	v_add_f32_e32 v23, v51, v23
	global_store_dwordx4 v244, v[20:23], s[26:27] offset:320
	v_mul_f32_e32 v158, v20, v20
	v_mul_f32_e32 v159, v21, v21
	v_mul_f32_e32 v250, v22, v22
	v_mul_f32_e32 v251, v23, v23
	v_add_f32_e32 v158, v158, v159
	v_add_f32_e32 v250, v250, v251
	v_add_f32_e32 v158, v158, v250
	v_add_f32_e32 v161, v161, v158
	v_mul_f32_e32 v158, v20, v228
	v_mul_f32_e32 v159, v21, v229
	v_mul_f32_e32 v250, v22, v230
	v_mul_f32_e32 v251, v23, v231
	v_cvt_pk_bf16_f32 v158, v158, v159
	v_cvt_pk_bf16_f32 v159, v250, v251
	s_nop 1
	v_permlane16_swap_b32_e32 v156, v158
	v_permlane16_swap_b32_e32 v157, v159
	global_store_dwordx4 v254, v[156:159], s[28:29] offset:128
	v_add_f32_e32 v162, v44, v162
	v_add_f32_e32 v163, v45, v163
	v_add_f32_e32 v164, v46, v164
	v_add_f32_e32 v165, v47, v165
	global_store_dwordx4 v244, v[162:165], s[26:27] offset:384
	v_mul_f32_e32 v158, v162, v162
	v_mul_f32_e32 v159, v163, v163
	v_mul_f32_e32 v250, v164, v164
	v_mul_f32_e32 v251, v165, v165
	v_add_f32_e32 v158, v158, v159
	v_add_f32_e32 v250, v250, v251
	v_add_f32_e32 v158, v158, v250
	v_add_f32_e32 v161, v161, v158
	v_mul_f32_e32 v156, v162, v232
	v_mul_f32_e32 v157, v163, v233
	v_mul_f32_e32 v158, v164, v234
	v_mul_f32_e32 v159, v165, v235
	v_cvt_pk_bf16_f32 v156, v156, v157
	v_cvt_pk_bf16_f32 v157, v158, v159
	v_add_f32_e32 v166, v40, v166
	v_add_f32_e32 v167, v41, v167
	v_add_f32_e32 v168, v42, v168
	v_add_f32_e32 v169, v43, v169
	global_store_dwordx4 v244, v[166:169], s[26:27] offset:448
	v_mul_f32_e32 v158, v166, v166
	v_mul_f32_e32 v159, v167, v167
	v_mul_f32_e32 v250, v168, v168
	v_mul_f32_e32 v251, v169, v169
	v_add_f32_e32 v158, v158, v159
	v_add_f32_e32 v250, v250, v251
	v_add_f32_e32 v158, v158, v250
	v_add_f32_e32 v161, v161, v158
	v_mul_f32_e32 v158, v166, v236
	v_mul_f32_e32 v159, v167, v237
	v_mul_f32_e32 v250, v168, v238
	v_mul_f32_e32 v251, v169, v239
	v_cvt_pk_bf16_f32 v158, v158, v159
	v_cvt_pk_bf16_f32 v159, v250, v251
	s_nop 1
	v_permlane16_swap_b32_e32 v156, v158
	v_permlane16_swap_b32_e32 v157, v159
	global_store_dwordx4 v254, v[156:159], s[28:29] offset:192
	ds_bpermute_b32 v158, v248, v161
	s_waitcnt lgkmcnt(0)
	v_add_f32_e32 v161, v161, v158
	ds_bpermute_b32 v158, v249, v161
	s_waitcnt lgkmcnt(0)
	v_add_f32_e32 v161, v161, v158
	global_store_dword v247, v161, s[30:31] offset:4
	s_add_u32 s26, s26, 0x10000
	s_addc_u32 s27, s27, 0
	s_add_u32 s28, s28, 0x8000
	s_addc_u32 s29, s29, 0
	s_add_u32 s30, s30, 0x400
	s_addc_u32 s31, s31, 0
	global_load_dwordx4 v[16:19], v244, s[24:25] offset:256
	global_load_dwordx4 v[20:23], v244, s[24:25] offset:320
	global_load_dwordx4 v[162:165], v244, s[24:25] offset:384
	global_load_dwordx4 v[166:169], v244, s[24:25] offset:448
	s_add_u32 s24, s24, 0x10000
	s_addc_u32 s25, s25, 0
	s_waitcnt vmcnt(26)
	v_add_f32_e32 v170, v68, v170
	v_add_f32_e32 v171, v69, v171
	v_add_f32_e32 v172, v70, v172
	v_add_f32_e32 v173, v71, v173
	global_store_dwordx4 v244, v[170:173], s[26:27]
	v_mul_f32_e32 v158, v170, v170
	v_mul_f32_e32 v159, v171, v171
	v_mul_f32_e32 v250, v172, v172
	v_mul_f32_e32 v251, v173, v173
	v_add_f32_e32 v158, v158, v159
	v_add_f32_e32 v250, v250, v251
	v_add_f32_e32 v161, v158, v250
	v_mul_f32_e32 v156, v170, v208
	v_mul_f32_e32 v157, v171, v209
	v_mul_f32_e32 v158, v172, v210
	v_mul_f32_e32 v159, v173, v211
	v_cvt_pk_bf16_f32 v156, v156, v157
	v_cvt_pk_bf16_f32 v157, v158, v159
	v_add_f32_e32 v174, v64, v174
	v_add_f32_e32 v175, v65, v175
	v_add_f32_e32 v176, v66, v176
	v_add_f32_e32 v177, v67, v177
	global_store_dwordx4 v244, v[174:177], s[26:27] offset:64
	v_mul_f32_e32 v158, v174, v174
	v_mul_f32_e32 v159, v175, v175
	v_mul_f32_e32 v250, v176, v176
	v_mul_f32_e32 v251, v177, v177
	v_add_f32_e32 v158, v158, v159
	v_add_f32_e32 v250, v250, v251
	v_add_f32_e32 v158, v158, v250
	v_add_f32_e32 v161, v161, v158
	v_mul_f32_e32 v158, v174, v212
	v_mul_f32_e32 v159, v175, v213
	v_mul_f32_e32 v250, v176, v214
	v_mul_f32_e32 v251, v177, v215
	v_cvt_pk_bf16_f32 v158, v158, v159
	v_cvt_pk_bf16_f32 v159, v250, v251
	s_nop 1
	v_permlane16_swap_b32_e32 v156, v158
	v_permlane16_swap_b32_e32 v157, v159
	global_store_dwordx4 v254, v[156:159], s[28:29]
	v_add_f32_e32 v178, v56, v178
	v_add_f32_e32 v179, v57, v179
	v_add_f32_e32 v180, v58, v180
	v_add_f32_e32 v181, v59, v181
	global_store_dwordx4 v244, v[178:181], s[26:27] offset:128
	v_mul_f32_e32 v158, v178, v178
	v_mul_f32_e32 v159, v179, v179
	v_mul_f32_e32 v250, v180, v180
	v_mul_f32_e32 v251, v181, v181
	v_add_f32_e32 v158, v158, v159
	v_add_f32_e32 v250, v250, v251
	v_add_f32_e32 v158, v158, v250
	v_add_f32_e32 v161, v161, v158
	v_mul_f32_e32 v156, v178, v216
	v_mul_f32_e32 v157, v179, v217
	v_mul_f32_e32 v158, v180, v218
	v_mul_f32_e32 v159, v181, v219
	v_cvt_pk_bf16_f32 v156, v156, v157
	v_cvt_pk_bf16_f32 v157, v158, v159
	v_add_f32_e32 v182, v52, v182
	v_add_f32_e32 v183, v53, v183
	v_add_f32_e32 v184, v54, v184
	v_add_f32_e32 v185, v55, v185
	global_store_dwordx4 v244, v[182:185], s[26:27] offset:192
	v_mul_f32_e32 v158, v182, v182
	v_mul_f32_e32 v159, v183, v183
	v_mul_f32_e32 v250, v184, v184
	v_mul_f32_e32 v251, v185, v185
	v_add_f32_e32 v158, v158, v159
	v_add_f32_e32 v250, v250, v251
	v_add_f32_e32 v158, v158, v250
	v_add_f32_e32 v161, v161, v158
	v_mul_f32_e32 v158, v182, v220
	v_mul_f32_e32 v159, v183, v221
	v_mul_f32_e32 v250, v184, v222
	v_mul_f32_e32 v251, v185, v223
	v_cvt_pk_bf16_f32 v158, v158, v159
	v_cvt_pk_bf16_f32 v159, v250, v251
	s_nop 1
	v_permlane16_swap_b32_e32 v156, v158
	v_permlane16_swap_b32_e32 v157, v159
	global_store_dwordx4 v254, v[156:159], s[28:29] offset:64
	ds_bpermute_b32 v158, v248, v161
	s_waitcnt lgkmcnt(0)
	v_add_f32_e32 v161, v161, v158
	ds_bpermute_b32 v158, v249, v161
	s_waitcnt lgkmcnt(0)
	v_add_f32_e32 v161, v161, v158
	global_store_dword v247, v161, s[30:31]
	global_load_dwordx4 v[170:173], v244, s[24:25]
	global_load_dwordx4 v[174:177], v244, s[24:25] offset:64
	global_load_dwordx4 v[178:181], v244, s[24:25] offset:128
	global_load_dwordx4 v[182:185], v244, s[24:25] offset:192
	s_waitcnt vmcnt(33)
	v_add_f32_e32 v186, v36, v186
	v_add_f32_e32 v187, v37, v187
	v_add_f32_e32 v188, v38, v188
	v_add_f32_e32 v189, v39, v189
	global_store_dwordx4 v244, v[186:189], s[26:27] offset:256
	v_mul_f32_e32 v158, v186, v186
	v_mul_f32_e32 v159, v187, v187
	v_mul_f32_e32 v250, v188, v188
	v_mul_f32_e32 v251, v189, v189
	v_add_f32_e32 v158, v158, v159
	v_add_f32_e32 v250, v250, v251
	v_add_f32_e32 v161, v158, v250
	v_mul_f32_e32 v156, v186, v224
	v_mul_f32_e32 v157, v187, v225
	v_mul_f32_e32 v158, v188, v226
	v_mul_f32_e32 v159, v189, v227
	v_cvt_pk_bf16_f32 v156, v156, v157
	v_cvt_pk_bf16_f32 v157, v158, v159
	v_add_f32_e32 v190, v32, v190
	v_add_f32_e32 v191, v33, v191
	v_add_f32_e32 v192, v34, v192
	v_add_f32_e32 v193, v35, v193
	global_store_dwordx4 v244, v[190:193], s[26:27] offset:320
	v_mul_f32_e32 v158, v190, v190
	v_mul_f32_e32 v159, v191, v191
	v_mul_f32_e32 v250, v192, v192
	v_mul_f32_e32 v251, v193, v193
	v_add_f32_e32 v158, v158, v159
	v_add_f32_e32 v250, v250, v251
	v_add_f32_e32 v158, v158, v250
	v_add_f32_e32 v161, v161, v158
	v_mul_f32_e32 v158, v190, v228
	v_mul_f32_e32 v159, v191, v229
	v_mul_f32_e32 v250, v192, v230
	v_mul_f32_e32 v251, v193, v231
	v_cvt_pk_bf16_f32 v158, v158, v159
	v_cvt_pk_bf16_f32 v159, v250, v251
	s_nop 1
	v_permlane16_swap_b32_e32 v156, v158
	v_permlane16_swap_b32_e32 v157, v159
	global_store_dwordx4 v254, v[156:159], s[28:29] offset:128
	v_add_f32_e32 v194, v28, v194
	v_add_f32_e32 v195, v29, v195
	v_add_f32_e32 v196, v30, v196
	v_add_f32_e32 v197, v31, v197
	global_store_dwordx4 v244, v[194:197], s[26:27] offset:384
	v_mul_f32_e32 v158, v194, v194
	v_mul_f32_e32 v159, v195, v195
	v_mul_f32_e32 v250, v196, v196
	v_mul_f32_e32 v251, v197, v197
	v_add_f32_e32 v158, v158, v159
	v_add_f32_e32 v250, v250, v251
	v_add_f32_e32 v158, v158, v250
	v_add_f32_e32 v161, v161, v158
	v_mul_f32_e32 v156, v194, v232
	v_mul_f32_e32 v157, v195, v233
	v_mul_f32_e32 v158, v196, v234
	v_mul_f32_e32 v159, v197, v235
	v_cvt_pk_bf16_f32 v156, v156, v157
	v_cvt_pk_bf16_f32 v157, v158, v159
	v_add_f32_e32 v240, v24, v240
	v_add_f32_e32 v241, v25, v241
	v_add_f32_e32 v242, v26, v242
	v_add_f32_e32 v243, v27, v243
	global_store_dwordx4 v244, v[240:243], s[26:27] offset:448
	v_mul_f32_e32 v158, v240, v240
	v_mul_f32_e32 v159, v241, v241
	v_mul_f32_e32 v250, v242, v242
	v_mul_f32_e32 v251, v243, v243
	v_add_f32_e32 v158, v158, v159
	v_add_f32_e32 v250, v250, v251
	v_add_f32_e32 v158, v158, v250
	v_add_f32_e32 v161, v161, v158
	v_mul_f32_e32 v158, v240, v236
	v_mul_f32_e32 v159, v241, v237
	v_mul_f32_e32 v250, v242, v238
	v_mul_f32_e32 v251, v243, v239
	v_cvt_pk_bf16_f32 v158, v158, v159
	v_cvt_pk_bf16_f32 v159, v250, v251
	s_nop 1
	v_permlane16_swap_b32_e32 v156, v158
	v_permlane16_swap_b32_e32 v157, v159
	global_store_dwordx4 v254, v[156:159], s[28:29] offset:192
	ds_bpermute_b32 v158, v248, v161
	s_waitcnt lgkmcnt(0)
	v_add_f32_e32 v161, v161, v158
	ds_bpermute_b32 v158, v249, v161
	s_waitcnt lgkmcnt(0)
	v_add_f32_e32 v161, v161, v158
	global_store_dword v247, v161, s[30:31] offset:4
	s_add_u32 s26, s26, 0x10000
	s_addc_u32 s27, s27, 0
	s_add_u32 s28, s28, 0x8000
	s_addc_u32 s29, s29, 0
	s_add_u32 s30, s30, 0x400
	s_addc_u32 s31, s31, 0
	global_load_dwordx4 v[186:189], v244, s[24:25] offset:256
	global_load_dwordx4 v[190:193], v244, s[24:25] offset:320
	global_load_dwordx4 v[194:197], v244, s[24:25] offset:384
	global_load_dwordx4 v[240:243], v244, s[24:25] offset:448
	s_add_u32 s24, s24, 0x10000
	s_addc_u32 s25, s25, 0
	s_waitcnt vmcnt(33)
	v_add_f32_e32 v0, v108, v0
	v_add_f32_e32 v1, v109, v1
	v_add_f32_e32 v2, v110, v2
	v_add_f32_e32 v3, v111, v3
	global_store_dwordx4 v244, v[0:3], s[26:27]
	v_mul_f32_e32 v158, v0, v0
	v_mul_f32_e32 v159, v1, v1
	v_mul_f32_e32 v250, v2, v2
	v_mul_f32_e32 v251, v3, v3
	v_add_f32_e32 v158, v158, v159
	v_add_f32_e32 v250, v250, v251
	v_add_f32_e32 v161, v158, v250
	v_mul_f32_e32 v156, v0, v208
	v_mul_f32_e32 v157, v1, v209
	v_mul_f32_e32 v158, v2, v210
	v_mul_f32_e32 v159, v3, v211
	v_cvt_pk_bf16_f32 v156, v156, v157
	v_cvt_pk_bf16_f32 v157, v158, v159
	v_add_f32_e32 v4, v112, v4
	v_add_f32_e32 v5, v113, v5
	v_add_f32_e32 v6, v114, v6
	v_add_f32_e32 v7, v115, v7
	global_store_dwordx4 v244, v[4:7], s[26:27] offset:64
	v_mul_f32_e32 v158, v4, v4
	v_mul_f32_e32 v159, v5, v5
	v_mul_f32_e32 v250, v6, v6
	v_mul_f32_e32 v251, v7, v7
	v_add_f32_e32 v158, v158, v159
	v_add_f32_e32 v250, v250, v251
	v_add_f32_e32 v158, v158, v250
	v_add_f32_e32 v161, v161, v158
	v_mul_f32_e32 v158, v4, v212
	v_mul_f32_e32 v159, v5, v213
	v_mul_f32_e32 v250, v6, v214
	v_mul_f32_e32 v251, v7, v215
	v_cvt_pk_bf16_f32 v158, v158, v159
	v_cvt_pk_bf16_f32 v159, v250, v251
	s_nop 1
	v_permlane16_swap_b32_e32 v156, v158
	v_permlane16_swap_b32_e32 v157, v159
	global_store_dwordx4 v254, v[156:159], s[28:29]
	v_add_f32_e32 v8, v116, v8
	v_add_f32_e32 v9, v117, v9
	v_add_f32_e32 v10, v118, v10
	v_add_f32_e32 v11, v119, v11
	global_store_dwordx4 v244, v[8:11], s[26:27] offset:128
	v_mul_f32_e32 v158, v8, v8
	v_mul_f32_e32 v159, v9, v9
	v_mul_f32_e32 v250, v10, v10
	v_mul_f32_e32 v251, v11, v11
	v_add_f32_e32 v158, v158, v159
	v_add_f32_e32 v250, v250, v251
	v_add_f32_e32 v158, v158, v250
	v_add_f32_e32 v161, v161, v158
	v_mul_f32_e32 v156, v8, v216
	v_mul_f32_e32 v157, v9, v217
	v_mul_f32_e32 v158, v10, v218
	v_mul_f32_e32 v159, v11, v219
	v_cvt_pk_bf16_f32 v156, v156, v157
	v_cvt_pk_bf16_f32 v157, v158, v159
	v_add_f32_e32 v12, v124, v12
	v_add_f32_e32 v13, v125, v13
	v_add_f32_e32 v14, v126, v14
	v_add_f32_e32 v15, v127, v15
	global_store_dwordx4 v244, v[12:15], s[26:27] offset:192
	v_mul_f32_e32 v158, v12, v12
	v_mul_f32_e32 v159, v13, v13
	v_mul_f32_e32 v250, v14, v14
	v_mul_f32_e32 v251, v15, v15
	v_add_f32_e32 v158, v158, v159
	v_add_f32_e32 v250, v250, v251
	v_add_f32_e32 v158, v158, v250
	v_add_f32_e32 v161, v161, v158
	v_mul_f32_e32 v158, v12, v220
	v_mul_f32_e32 v159, v13, v221
	v_mul_f32_e32 v250, v14, v222
	v_mul_f32_e32 v251, v15, v223
	v_cvt_pk_bf16_f32 v158, v158, v159
	v_cvt_pk_bf16_f32 v159, v250, v251
	s_nop 1
	v_permlane16_swap_b32_e32 v156, v158
	v_permlane16_swap_b32_e32 v157, v159
	global_store_dwordx4 v254, v[156:159], s[28:29] offset:64
	ds_bpermute_b32 v158, v248, v161
	s_waitcnt lgkmcnt(0)
	v_add_f32_e32 v161, v161, v158
	ds_bpermute_b32 v158, v249, v161
	s_waitcnt lgkmcnt(0)
	v_add_f32_e32 v161, v161, v158
	global_store_dword v247, v161, s[30:31]
	s_waitcnt vmcnt(29)
	v_add_f32_e32 v16, v80, v16
	v_add_f32_e32 v17, v81, v17
	v_add_f32_e32 v18, v82, v18
	v_add_f32_e32 v19, v83, v19
	global_store_dwordx4 v244, v[16:19], s[26:27] offset:256
	v_mul_f32_e32 v158, v16, v16
	v_mul_f32_e32 v159, v17, v17
	v_mul_f32_e32 v250, v18, v18
	v_mul_f32_e32 v251, v19, v19
	v_add_f32_e32 v158, v158, v159
	v_add_f32_e32 v250, v250, v251
	v_add_f32_e32 v161, v158, v250
	v_mul_f32_e32 v156, v16, v224
	v_mul_f32_e32 v157, v17, v225
	v_mul_f32_e32 v158, v18, v226
	v_mul_f32_e32 v159, v19, v227
	v_cvt_pk_bf16_f32 v156, v156, v157
	v_cvt_pk_bf16_f32 v157, v158, v159
	v_add_f32_e32 v20, v84, v20
	v_add_f32_e32 v21, v85, v21
	v_add_f32_e32 v22, v86, v22
	v_add_f32_e32 v23, v87, v23
	global_store_dwordx4 v244, v[20:23], s[26:27] offset:320
	v_mul_f32_e32 v158, v20, v20
	v_mul_f32_e32 v159, v21, v21
	v_mul_f32_e32 v250, v22, v22
	v_mul_f32_e32 v251, v23, v23
	v_add_f32_e32 v158, v158, v159
	v_add_f32_e32 v250, v250, v251
	v_add_f32_e32 v158, v158, v250
	v_add_f32_e32 v161, v161, v158
	v_mul_f32_e32 v158, v20, v228
	v_mul_f32_e32 v159, v21, v229
	v_mul_f32_e32 v250, v22, v230
	v_mul_f32_e32 v251, v23, v231
	v_cvt_pk_bf16_f32 v158, v158, v159
	v_cvt_pk_bf16_f32 v159, v250, v251
	s_nop 1
	v_permlane16_swap_b32_e32 v156, v158
	v_permlane16_swap_b32_e32 v157, v159
	global_store_dwordx4 v254, v[156:159], s[28:29] offset:128
	v_add_f32_e32 v162, v96, v162
	v_add_f32_e32 v163, v97, v163
	v_add_f32_e32 v164, v98, v164
	v_add_f32_e32 v165, v99, v165
	global_store_dwordx4 v244, v[162:165], s[26:27] offset:384
	v_mul_f32_e32 v158, v162, v162
	v_mul_f32_e32 v159, v163, v163
	v_mul_f32_e32 v250, v164, v164
	v_mul_f32_e32 v251, v165, v165
	v_add_f32_e32 v158, v158, v159
	v_add_f32_e32 v250, v250, v251
	v_add_f32_e32 v158, v158, v250
	v_add_f32_e32 v161, v161, v158
	v_mul_f32_e32 v156, v162, v232
	v_mul_f32_e32 v157, v163, v233
	v_mul_f32_e32 v158, v164, v234
	v_mul_f32_e32 v159, v165, v235
	v_cvt_pk_bf16_f32 v156, v156, v157
	v_cvt_pk_bf16_f32 v157, v158, v159
	v_add_f32_e32 v166, v72, v166
	v_add_f32_e32 v167, v73, v167
	v_add_f32_e32 v168, v74, v168
	v_add_f32_e32 v169, v75, v169
	global_store_dwordx4 v244, v[166:169], s[26:27] offset:448
	v_mul_f32_e32 v158, v166, v166
	v_mul_f32_e32 v159, v167, v167
	v_mul_f32_e32 v250, v168, v168
	v_mul_f32_e32 v251, v169, v169
	v_add_f32_e32 v158, v158, v159
	v_add_f32_e32 v250, v250, v251
	v_add_f32_e32 v158, v158, v250
	v_add_f32_e32 v161, v161, v158
	v_mul_f32_e32 v158, v166, v236
	v_mul_f32_e32 v159, v167, v237
	v_mul_f32_e32 v250, v168, v238
	v_mul_f32_e32 v251, v169, v239
	v_cvt_pk_bf16_f32 v158, v158, v159
	v_cvt_pk_bf16_f32 v159, v250, v251
	s_nop 1
	v_permlane16_swap_b32_e32 v156, v158
	v_permlane16_swap_b32_e32 v157, v159
	global_store_dwordx4 v254, v[156:159], s[28:29] offset:192
	ds_bpermute_b32 v158, v248, v161
	s_waitcnt lgkmcnt(0)
	v_add_f32_e32 v161, v161, v158
	ds_bpermute_b32 v158, v249, v161
	s_waitcnt lgkmcnt(0)
	v_add_f32_e32 v161, v161, v158
	global_store_dword v247, v161, s[30:31] offset:4
	s_add_u32 s26, s26, 0x10000
	s_addc_u32 s27, s27, 0
	s_add_u32 s28, s28, 0x8000
	s_addc_u32 s29, s29, 0
	s_add_u32 s30, s30, 0x400
	s_addc_u32 s31, s31, 0
	s_waitcnt vmcnt(25)
	v_add_f32_e32 v170, v132, v170
	v_add_f32_e32 v171, v133, v171
	v_add_f32_e32 v172, v134, v172
	v_add_f32_e32 v173, v135, v173
	global_store_dwordx4 v244, v[170:173], s[26:27]
	v_mul_f32_e32 v158, v170, v170
	v_mul_f32_e32 v159, v171, v171
	v_mul_f32_e32 v250, v172, v172
	v_mul_f32_e32 v251, v173, v173
	v_add_f32_e32 v158, v158, v159
	v_add_f32_e32 v250, v250, v251
	v_add_f32_e32 v161, v158, v250
	v_mul_f32_e32 v156, v170, v208
	v_mul_f32_e32 v157, v171, v209
	v_mul_f32_e32 v158, v172, v210
	v_mul_f32_e32 v159, v173, v211
	v_cvt_pk_bf16_f32 v156, v156, v157
	v_cvt_pk_bf16_f32 v157, v158, v159
	v_add_f32_e32 v174, v136, v174
	v_add_f32_e32 v175, v137, v175
	v_add_f32_e32 v176, v138, v176
	v_add_f32_e32 v177, v139, v177
	global_store_dwordx4 v244, v[174:177], s[26:27] offset:64
	v_mul_f32_e32 v158, v174, v174
	v_mul_f32_e32 v159, v175, v175
	v_mul_f32_e32 v250, v176, v176
	v_mul_f32_e32 v251, v177, v177
	v_add_f32_e32 v158, v158, v159
	v_add_f32_e32 v250, v250, v251
	v_add_f32_e32 v158, v158, v250
	v_add_f32_e32 v161, v161, v158
	v_mul_f32_e32 v158, v174, v212
	v_mul_f32_e32 v159, v175, v213
	v_mul_f32_e32 v250, v176, v214
	v_mul_f32_e32 v251, v177, v215
	v_cvt_pk_bf16_f32 v158, v158, v159
	v_cvt_pk_bf16_f32 v159, v250, v251
	s_nop 1
	v_permlane16_swap_b32_e32 v156, v158
	v_permlane16_swap_b32_e32 v157, v159
	global_store_dwordx4 v254, v[156:159], s[28:29]
	v_add_f32_e32 v178, v140, v178
	v_add_f32_e32 v179, v141, v179
	v_add_f32_e32 v180, v142, v180
	v_add_f32_e32 v181, v143, v181
	global_store_dwordx4 v244, v[178:181], s[26:27] offset:128
	v_mul_f32_e32 v158, v178, v178
	v_mul_f32_e32 v159, v179, v179
	v_mul_f32_e32 v250, v180, v180
	v_mul_f32_e32 v251, v181, v181
	v_add_f32_e32 v158, v158, v159
	v_add_f32_e32 v250, v250, v251
	v_add_f32_e32 v158, v158, v250
	v_add_f32_e32 v161, v161, v158
	v_mul_f32_e32 v156, v178, v216
	v_mul_f32_e32 v157, v179, v217
	v_mul_f32_e32 v158, v180, v218
	v_mul_f32_e32 v159, v181, v219
	v_cvt_pk_bf16_f32 v156, v156, v157
	v_cvt_pk_bf16_f32 v157, v158, v159
	v_add_f32_e32 v182, v144, v182
	v_add_f32_e32 v183, v145, v183
	v_add_f32_e32 v184, v146, v184
	v_add_f32_e32 v185, v147, v185
	global_store_dwordx4 v244, v[182:185], s[26:27] offset:192
	v_mul_f32_e32 v158, v182, v182
	v_mul_f32_e32 v159, v183, v183
	v_mul_f32_e32 v250, v184, v184
	v_mul_f32_e32 v251, v185, v185
	v_add_f32_e32 v158, v158, v159
	v_add_f32_e32 v250, v250, v251
	v_add_f32_e32 v158, v158, v250
	v_add_f32_e32 v161, v161, v158
	v_mul_f32_e32 v158, v182, v220
	v_mul_f32_e32 v159, v183, v221
	v_mul_f32_e32 v250, v184, v222
	v_mul_f32_e32 v251, v185, v223
	v_cvt_pk_bf16_f32 v158, v158, v159
	v_cvt_pk_bf16_f32 v159, v250, v251
	s_nop 1
	v_permlane16_swap_b32_e32 v156, v158
	v_permlane16_swap_b32_e32 v157, v159
	global_store_dwordx4 v254, v[156:159], s[28:29] offset:64
	ds_bpermute_b32 v158, v248, v161
	s_waitcnt lgkmcnt(0)
	v_add_f32_e32 v161, v161, v158
	ds_bpermute_b32 v158, v249, v161
	s_waitcnt lgkmcnt(0)
	v_add_f32_e32 v161, v161, v158
	global_store_dword v247, v161, s[30:31]
	s_waitcnt vmcnt(21)
	v_add_f32_e32 v186, v92, v186
	v_add_f32_e32 v187, v93, v187
	v_add_f32_e32 v188, v94, v188
	v_add_f32_e32 v189, v95, v189
	global_store_dwordx4 v244, v[186:189], s[26:27] offset:256
	v_mul_f32_e32 v158, v186, v186
	v_mul_f32_e32 v159, v187, v187
	v_mul_f32_e32 v250, v188, v188
	v_mul_f32_e32 v251, v189, v189
	v_add_f32_e32 v158, v158, v159
	v_add_f32_e32 v250, v250, v251
	v_add_f32_e32 v161, v158, v250
	v_mul_f32_e32 v156, v186, v224
	v_mul_f32_e32 v157, v187, v225
	v_mul_f32_e32 v158, v188, v226
	v_mul_f32_e32 v159, v189, v227
	v_cvt_pk_bf16_f32 v156, v156, v157
	v_cvt_pk_bf16_f32 v157, v158, v159
	v_add_f32_e32 v190, v88, v190
	v_add_f32_e32 v191, v89, v191
	v_add_f32_e32 v192, v90, v192
	v_add_f32_e32 v193, v91, v193
	global_store_dwordx4 v244, v[190:193], s[26:27] offset:320
	v_mul_f32_e32 v158, v190, v190
	v_mul_f32_e32 v159, v191, v191
	v_mul_f32_e32 v250, v192, v192
	v_mul_f32_e32 v251, v193, v193
	v_add_f32_e32 v158, v158, v159
	v_add_f32_e32 v250, v250, v251
	v_add_f32_e32 v158, v158, v250
	v_add_f32_e32 v161, v161, v158
	v_mul_f32_e32 v158, v190, v228
	v_mul_f32_e32 v159, v191, v229
	v_mul_f32_e32 v250, v192, v230
	v_mul_f32_e32 v251, v193, v231
	v_cvt_pk_bf16_f32 v158, v158, v159
	v_cvt_pk_bf16_f32 v159, v250, v251
	s_nop 1
	v_permlane16_swap_b32_e32 v156, v158
	v_permlane16_swap_b32_e32 v157, v159
	global_store_dwordx4 v254, v[156:159], s[28:29] offset:128
	v_add_f32_e32 v194, v76, v194
	v_add_f32_e32 v195, v77, v195
	v_add_f32_e32 v196, v78, v196
	v_add_f32_e32 v197, v79, v197
	global_store_dwordx4 v244, v[194:197], s[26:27] offset:384
	v_mul_f32_e32 v158, v194, v194
	v_mul_f32_e32 v159, v195, v195
	v_mul_f32_e32 v250, v196, v196
	v_mul_f32_e32 v251, v197, v197
	v_add_f32_e32 v158, v158, v159
	v_add_f32_e32 v250, v250, v251
	v_add_f32_e32 v158, v158, v250
	v_add_f32_e32 v161, v161, v158
	v_mul_f32_e32 v156, v194, v232
	v_mul_f32_e32 v157, v195, v233
	v_mul_f32_e32 v158, v196, v234
	v_mul_f32_e32 v159, v197, v235
	v_cvt_pk_bf16_f32 v156, v156, v157
	v_cvt_pk_bf16_f32 v157, v158, v159
	v_add_f32_e32 v240, v148, v240
	v_add_f32_e32 v241, v149, v241
	v_add_f32_e32 v242, v150, v242
	v_add_f32_e32 v243, v151, v243
	global_store_dwordx4 v244, v[240:243], s[26:27] offset:448
	v_mul_f32_e32 v158, v240, v240
	v_mul_f32_e32 v159, v241, v241
	v_mul_f32_e32 v250, v242, v242
	v_mul_f32_e32 v251, v243, v243
	v_add_f32_e32 v158, v158, v159
	v_add_f32_e32 v250, v250, v251
	v_add_f32_e32 v158, v158, v250
	v_add_f32_e32 v161, v161, v158
	v_mul_f32_e32 v158, v240, v236
	v_mul_f32_e32 v159, v241, v237
	v_mul_f32_e32 v250, v242, v238
	v_mul_f32_e32 v251, v243, v239
	v_cvt_pk_bf16_f32 v158, v158, v159
	v_cvt_pk_bf16_f32 v159, v250, v251
	s_nop 1
	v_permlane16_swap_b32_e32 v156, v158
	v_permlane16_swap_b32_e32 v157, v159
	global_store_dwordx4 v254, v[156:159], s[28:29] offset:192
	ds_bpermute_b32 v158, v248, v161
	s_waitcnt lgkmcnt(0)
	v_add_f32_e32 v161, v161, v158
	ds_bpermute_b32 v158, v249, v161
	s_waitcnt lgkmcnt(0)
	v_add_f32_e32 v161, v161, v158
	global_store_dword v247, v161, s[30:31] offset:4
	s_add_u32 s26, s26, 0x10000
	s_addc_u32 s27, s27, 0
	s_add_u32 s28, s28, 0x8000
	s_addc_u32 s29, s29, 0
	s_add_u32 s30, s30, 0x400
	s_addc_u32 s31, s31, 0
	s_branch .LBB0_360

.Lproj_cd:
	s_or_b32 s4, s16, s67
	v_mov_b32 v10, v198
	v_ashrrev_i32_e32 v0, 2, v10
	s_lshl_b32 s4, s4, 7
	v_add_u32_e32 v2, s4, v0
	v_ashrrev_i32_e32 v3, 31, v2
	v_lshlrev_b64 v[2:3], 11, v[2:3]
	v_lshlrev_b32_e32 v1, 4, v10
	v_add_u32_e32 v4, s17, v0
	v_lshl_add_u64 v[2:3], s[96:97], 0, v[2:3]
	v_and_b32_e32 v152, 48, v1
	v_ashrrev_i32_e32 v5, 31, v4
	v_lshl_add_u64 v[2:3], v[2:3], 0, v[152:153]
	v_lshlrev_b64 v[4:5], 6, v[4:5]
	v_lshl_add_u64 v[156:157], s[8:9], 0, v[4:5]
	v_add_co_u32_e32 v6, vcc, s62, v2
	v_lshl_add_u64 v[4:5], v[156:157], 0, v[152:153]
	s_nop 0
	v_addc_co_u32_e32 v7, vcc, 0, v3, vcc
	v_add_co_u32_e32 v8, vcc, s62, v4
	s_and_b32 s7, s42, 56
	v_lshrrev_b32_e32 v1, 2, v10
	s_or_b32 s6, s67, s6
	v_addc_co_u32_e32 v9, vcc, 0, v5, vcc
	v_and_b32_e32 v12, 12, v1
	s_movk_i32 s20, 0x1230
	s_or_b32 s84, s6, s7
	v_add_co_u32_e32 v60, vcc, s33, v4
	v_lshrrev_b32_e64 v12, v12, s20
	s_lshl_b64 s[6:7], s[84:85], 18
	v_addc_co_u32_e32 v61, vcc, 0, v5, vcc
	v_and_b32_e32 v11, 3, v10
	v_ashrrev_i32_e32 v1, 31, v0
	v_xor_b32_e32 v10, v12, v10
	s_add_u32 s6, s82, s6
	v_add_co_u32_e32 v62, vcc, s72, v4
	v_lshlrev_b32_e32 v13, 6, v0
	v_lshlrev_b64 v[0:1], 11, v[0:1]
	v_lshlrev_b32_e32 v10, 4, v10
	s_addc_u32 s7, s83, s7
	v_addc_co_u32_e32 v63, vcc, 0, v5, vcc
	s_nop 0
	v_readfirstlane_b32 s26, v2
	v_readfirstlane_b32 s27, v3
	v_readfirstlane_b32 s28, v4
	v_readfirstlane_b32 s29, v5
	v_lshrrev_b32_e32 v250, 6, v198
	s_nop 0
	v_readfirstlane_b32 s24, v250
	s_lshl_b32 s24, s24, 10
	v_lshrrev_b32_e32 v250, 2, v200
	v_lshrrev_b32_e32 v251, 4, v200
	v_lshlrev_b32_e32 v251, 2, v251
	v_mov_b32_e32 v248, 0x1230
	v_lshrrev_b32_e32 v251, v251, v248
	v_xor_b32_e32 v251, v251, v200
	v_and_b32_e32 v251, 3, v251
	v_lshlrev_b32_e32 v251, 4, v251
	v_lshl_add_u32 v244, v250, 11, v251
	v_add_u32_e32 v245, 0x20000, v244
	v_add_u32_e32 v246, 0x40000, v244
	v_add_u32_e32 v247, 0x60000, v244
	v_lshl_add_u32 v156, v250, 6, v251
	v_add_u32_e32 v157, 0x1000, v156
	v_add_u32_e32 v158, 0x2000, v156
	v_add_u32_e32 v159, 0x3000, v156
	s_mov_b32 s25, 0
	s_add_u32 m0, s25, s24
	s_nop 0
	global_load_lds_dwordx4 v244, s[26:27]
	s_add_u32 m0, m0, 0x1000
	s_nop 0
	global_load_lds_dwordx4 v245, s[26:27]
	s_add_u32 m0, m0, 0x1000
	s_nop 0
	global_load_lds_dwordx4 v156, s[28:29]
	s_add_u32 m0, m0, 0x1000
	s_nop 0
	global_load_lds_dwordx4 v157, s[28:29]
	s_add_u32 m0, m0, 0x1000
	s_nop 0
	global_load_lds_dwordx4 v158, s[28:29]
	s_add_u32 m0, m0, 0x1000
	s_nop 0
	global_load_lds_dwordx4 v159, s[28:29]
	s_add_u32 s26, s26, 0x40
	s_addc_u32 s27, s27, 0
	s_add_u32 s28, s28, 0x34000
	s_addc_u32 s29, s29, 0
	s_add_u32 s25, s25, 24576
	s_cmp_eq_u32 s25, 73728
	s_cselect_b32 s25, 0, s25
	s_add_u32 m0, s25, s24
	s_nop 0
	global_load_lds_dwordx4 v244, s[26:27]
	s_add_u32 m0, m0, 0x1000
	s_nop 0
	global_load_lds_dwordx4 v245, s[26:27]
	s_add_u32 m0, m0, 0x1000
	s_nop 0
	global_load_lds_dwordx4 v156, s[28:29]
	s_add_u32 m0, m0, 0x1000
	s_nop 0
	global_load_lds_dwordx4 v157, s[28:29]
	s_add_u32 m0, m0, 0x1000
	s_nop 0
	global_load_lds_dwordx4 v158, s[28:29]
	s_add_u32 m0, m0, 0x1000
	s_nop 0
	global_load_lds_dwordx4 v159, s[28:29]
	s_add_u32 s26, s26, 0x40
	s_addc_u32 s27, s27, 0
	s_add_u32 s28, s28, 0x34000
	s_addc_u32 s29, s29, 0
	s_add_u32 s25, s25, 24576
	s_cmp_eq_u32 s25, 73728
	s_cselect_b32 s25, 0, s25
	s_add_u32 m0, s25, s24
	s_nop 0
	global_load_lds_dwordx4 v244, s[26:27]
	s_add_u32 m0, m0, 0x1000
	s_nop 0
	global_load_lds_dwordx4 v245, s[26:27]
	s_add_u32 m0, m0, 0x1000
	s_nop 0
	global_load_lds_dwordx4 v156, s[28:29]
	s_add_u32 m0, m0, 0x1000
	s_nop 0
	global_load_lds_dwordx4 v157, s[28:29]
	s_add_u32 m0, m0, 0x1000
	s_nop 0
	global_load_lds_dwordx4 v158, s[28:29]
	s_add_u32 m0, m0, 0x1000
	s_nop 0
	global_load_lds_dwordx4 v159, s[28:29]
	s_add_u32 s26, s26, 0x40
	s_addc_u32 s27, s27, 0
	s_add_u32 s28, s28, 0x34000
	s_addc_u32 s29, s29, 0
	s_add_u32 s25, s25, 24576
	s_cmp_eq_u32 s25, 73728
	s_cselect_b32 s25, 0, s25
	v_mov_b32_e32 v24, 0
	v_mov_b32_e32 v25, v24
	v_mov_b32_e32 v26, v24
	v_mov_b32_e32 v27, v24
	v_mov_b32_e32 v28, v24
	v_mov_b32_e32 v29, v24
	v_mov_b32_e32 v30, v24
	v_mov_b32_e32 v31, v24
	v_mov_b32_e32 v32, v24
	v_mov_b32_e32 v33, v24
	v_mov_b32_e32 v34, v24
	v_mov_b32_e32 v35, v24
	v_mov_b32_e32 v64, v24
	v_mov_b32_e32 v65, v24
	v_mov_b32_e32 v66, v24
	v_mov_b32_e32 v67, v24
	v_mov_b32_e32 v68, v24
	v_mov_b32_e32 v69, v24
	v_mov_b32_e32 v70, v24
	v_mov_b32_e32 v71, v24
	v_mov_b32_e32 v60, v24
	v_mov_b32_e32 v61, v24
	v_mov_b32_e32 v62, v24
	v_mov_b32_e32 v63, v24
	v_mov_b32_e32 v100, v24
	v_mov_b32_e32 v101, v24
	v_mov_b32_e32 v102, v24
	v_mov_b32_e32 v103, v24
	v_mov_b32_e32 v104, v24
	v_mov_b32_e32 v105, v24
	v_mov_b32_e32 v106, v24
	v_mov_b32_e32 v107, v24
	v_mov_b32_e32 v120, v24
	v_mov_b32_e32 v121, v24
	v_mov_b32_e32 v122, v24
	v_mov_b32_e32 v36, v24
	v_mov_b32_e32 v37, v24
	v_mov_b32_e32 v38, v24
	v_mov_b32_e32 v39, v24
	v_mov_b32_e32 v52, v24
	v_mov_b32_e32 v53, v24
	v_mov_b32_e32 v54, v24
	v_mov_b32_e32 v55, v24
	v_mov_b32_e32 v56, v24
	v_mov_b32_e32 v57, v24
	v_mov_b32_e32 v58, v24
	v_mov_b32_e32 v59, v24
	v_mov_b32_e32 v40, v24
	v_mov_b32_e32 v41, v24
	v_mov_b32_e32 v42, v24
	v_mov_b32_e32 v43, v24
	v_mov_b32_e32 v44, v24
	v_mov_b32_e32 v45, v24
	v_mov_b32_e32 v46, v24
	v_mov_b32_e32 v47, v24
	v_mov_b32_e32 v48, v24
	v_mov_b32_e32 v49, v24
	v_mov_b32_e32 v50, v24
	v_mov_b32_e32 v51, v24
	v_mov_b32_e32 v123, v24
	v_mov_b32_e32 v128, v24
	v_mov_b32_e32 v129, v24
	v_mov_b32_e32 v130, v24
	v_mov_b32_e32 v131, v24
	v_mov_b32_e32 v108, v24
	v_mov_b32_e32 v109, v24
	v_mov_b32_e32 v110, v24
	v_mov_b32_e32 v111, v24
	v_mov_b32_e32 v112, v24
	v_mov_b32_e32 v113, v24
	v_mov_b32_e32 v114, v24
	v_mov_b32_e32 v115, v24
	v_mov_b32_e32 v116, v24
	v_mov_b32_e32 v117, v24
	v_mov_b32_e32 v118, v24
	v_mov_b32_e32 v119, v24
	v_mov_b32_e32 v124, v24
	v_mov_b32_e32 v125, v24
	v_mov_b32_e32 v126, v24
	v_mov_b32_e32 v127, v24
	v_mov_b32_e32 v80, v24
	v_mov_b32_e32 v81, v24
	v_mov_b32_e32 v82, v24
	v_mov_b32_e32 v83, v24
	v_mov_b32_e32 v88, v24
	v_mov_b32_e32 v89, v24
	v_mov_b32_e32 v90, v24
	v_mov_b32_e32 v91, v24
	v_mov_b32_e32 v92, v24
	v_mov_b32_e32 v93, v24
	v_mov_b32_e32 v94, v24
	v_mov_b32_e32 v95, v24
	v_mov_b32_e32 v76, v24
	v_mov_b32_e32 v77, v24
	v_mov_b32_e32 v78, v24
	v_mov_b32_e32 v79, v24
	v_mov_b32_e32 v132, v24
	v_mov_b32_e32 v133, v24
	v_mov_b32_e32 v134, v24
	v_mov_b32_e32 v135, v24
	v_mov_b32_e32 v136, v24
	v_mov_b32_e32 v137, v24
	v_mov_b32_e32 v138, v24
	v_mov_b32_e32 v139, v24
	v_mov_b32_e32 v140, v24
	v_mov_b32_e32 v141, v24
	v_mov_b32_e32 v142, v24
	v_mov_b32_e32 v143, v24
	v_mov_b32_e32 v144, v24
	v_mov_b32_e32 v145, v24
	v_mov_b32_e32 v146, v24
	v_mov_b32_e32 v147, v24
	v_mov_b32_e32 v96, v24
	v_mov_b32_e32 v97, v24
	v_mov_b32_e32 v98, v24
	v_mov_b32_e32 v99, v24
	v_mov_b32_e32 v84, v24
	v_mov_b32_e32 v85, v24
	v_mov_b32_e32 v86, v24
	v_mov_b32_e32 v87, v24
	v_mov_b32_e32 v72, v24
	v_mov_b32_e32 v73, v24
	v_mov_b32_e32 v74, v24
	v_mov_b32_e32 v75, v24
	v_mov_b32_e32 v148, v24
	v_mov_b32_e32 v149, v24
	v_mov_b32_e32 v150, v24
	v_mov_b32_e32 v151, v24
	s_waitcnt vmcnt(12)
	s_barrier
	s_mov_b32 s30, 0
	v_add_u32_e32 v248, s30, v155
	v_add_u32_e32 v249, s30, v160
	ds_read_b128 v[186:189], v248
	ds_read_b128 v[212:215], v249 offset:8192
	ds_read_b128 v[190:193], v248 offset:1024
	ds_read_b128 v[216:219], v249 offset:9216
	ds_read_b128 v[194:197], v248 offset:2048
	ds_read_b128 v[220:223], v249 offset:10240
	ds_read_b128 v[208:211], v248 offset:3072
	ds_read_b128 v[224:227], v249 offset:11264
	ds_read_b128 v[228:231], v249 offset:12288
	ds_read_b128 v[232:235], v249 offset:13312
	ds_read_b128 v[236:239], v249 offset:14336
	ds_read_b128 v[240:243], v249 offset:15360
	s_add_u32 s30, s30, 24576
	s_cmp_eq_u32 s30, 73728
	s_cselect_b32 s30, 0, s30
	s_waitcnt vmcnt(6)
	s_waitcnt lgkmcnt(0)
	s_barrier
	s_mov_b32 s31, 14
	s_cmpk_lt_u32 s43, 0x180
	s_cbranch_scc0 .Lgm3_cheap
.Lgm3_loop:
	v_add_u32_e32 v248, s30, v155
	v_add_u32_e32 v249, s30, v160
	v_mfma_f32_16x16x32_bf16 v[128:131], v[212:215], v[186:189], v[128:131]
	ds_read_b128 v[0:3], v248
	v_mfma_f32_16x16x32_bf16 v[68:71], v[212:215], v[190:193], v[68:71]
	ds_read_b128 v[16:19], v249 offset:8192
	v_mfma_f32_16x16x32_bf16 v[108:111], v[212:215], v[194:197], v[108:111]
	ds_read_b128 v[4:7], v248 offset:1024
	v_mfma_f32_16x16x32_bf16 v[132:135], v[212:215], v[208:211], v[132:135]
	ds_read_b128 v[20:23], v249 offset:9216
	v_mfma_f32_16x16x32_bf16 v[120:123], v[216:219], v[186:189], v[120:123]
	ds_read_b128 v[8:11], v248 offset:2048
	v_mfma_f32_16x16x32_bf16 v[64:67], v[216:219], v[190:193], v[64:67]
	ds_read_b128 v[162:165], v249 offset:10240
	v_mfma_f32_16x16x32_bf16 v[112:115], v[216:219], v[194:197], v[112:115]
	ds_read_b128 v[12:15], v248 offset:3072
	v_mfma_f32_16x16x32_bf16 v[136:139], v[216:219], v[208:211], v[136:139]
	ds_read_b128 v[166:169], v249 offset:11264
	v_mfma_f32_16x16x32_bf16 v[104:107], v[220:223], v[186:189], v[104:107]
	ds_read_b128 v[170:173], v249 offset:12288
	v_mfma_f32_16x16x32_bf16 v[56:59], v[220:223], v[190:193], v[56:59]
	ds_read_b128 v[174:177], v249 offset:13312
	v_mfma_f32_16x16x32_bf16 v[116:119], v[220:223], v[194:197], v[116:119]
	ds_read_b128 v[178:181], v249 offset:14336
	v_mfma_f32_16x16x32_bf16 v[140:143], v[220:223], v[208:211], v[140:143]
	ds_read_b128 v[182:185], v249 offset:15360
	s_add_u32 m0, s25, s24
	v_mfma_f32_16x16x32_bf16 v[100:103], v[224:227], v[186:189], v[100:103]
	global_load_lds_dwordx4 v244, s[26:27]
	v_mfma_f32_16x16x32_bf16 v[52:55], v[224:227], v[190:193], v[52:55]
	v_mfma_f32_16x16x32_bf16 v[124:127], v[224:227], v[194:197], v[124:127]
	s_add_u32 m0, m0, 0x1000
	v_mfma_f32_16x16x32_bf16 v[144:147], v[224:227], v[208:211], v[144:147]
	global_load_lds_dwordx4 v245, s[26:27]
	v_mfma_f32_16x16x32_bf16 v[60:63], v[228:231], v[186:189], v[60:63]
	v_mfma_f32_16x16x32_bf16 v[36:39], v[228:231], v[190:193], v[36:39]
	s_add_u32 m0, m0, 0x1000
	v_mfma_f32_16x16x32_bf16 v[80:83], v[228:231], v[194:197], v[80:83]
	global_load_lds_dwordx4 v156, s[28:29]
	v_mfma_f32_16x16x32_bf16 v[96:99], v[228:231], v[208:211], v[96:99]
	v_mfma_f32_16x16x32_bf16 v[48:51], v[232:235], v[186:189], v[48:51]
	s_add_u32 m0, m0, 0x1000
	v_mfma_f32_16x16x32_bf16 v[32:35], v[232:235], v[190:193], v[32:35]
	global_load_lds_dwordx4 v157, s[28:29]
	v_mfma_f32_16x16x32_bf16 v[88:91], v[232:235], v[194:197], v[88:91]
	v_mfma_f32_16x16x32_bf16 v[84:87], v[232:235], v[208:211], v[84:87]
	s_add_u32 m0, m0, 0x1000
	v_mfma_f32_16x16x32_bf16 v[44:47], v[236:239], v[186:189], v[44:47]
	global_load_lds_dwordx4 v158, s[28:29]
	v_mfma_f32_16x16x32_bf16 v[28:31], v[236:239], v[190:193], v[28:31]
	v_mfma_f32_16x16x32_bf16 v[92:95], v[236:239], v[194:197], v[92:95]
	s_add_u32 m0, m0, 0x1000
	v_mfma_f32_16x16x32_bf16 v[72:75], v[236:239], v[208:211], v[72:75]
	global_load_lds_dwordx4 v159, s[28:29]
	v_mfma_f32_16x16x32_bf16 v[40:43], v[240:243], v[186:189], v[40:43]
	v_mfma_f32_16x16x32_bf16 v[24:27], v[240:243], v[190:193], v[24:27]
	v_mfma_f32_16x16x32_bf16 v[76:79], v[240:243], v[194:197], v[76:79]
	v_mfma_f32_16x16x32_bf16 v[148:151], v[240:243], v[208:211], v[148:151]
	s_add_u32 s26, s26, 0x40
	s_addc_u32 s27, s27, 0
	s_add_u32 s28, s28, 0x34000
	s_addc_u32 s29, s29, 0
	s_add_u32 s25, s25, 24576
	s_cmp_eq_u32 s25, 73728
	s_cselect_b32 s25, 0, s25
	s_add_u32 s30, s30, 24576
	s_cmp_eq_u32 s30, 73728
	s_cselect_b32 s30, 0, s30
	s_waitcnt vmcnt(6)
	s_waitcnt lgkmcnt(0)
	s_barrier
	v_add_u32_e32 v248, s30, v155
	v_add_u32_e32 v249, s30, v160
	v_mfma_f32_16x16x32_bf16 v[128:131], v[16:19], v[0:3], v[128:131]
	ds_read_b128 v[186:189], v248
	v_mfma_f32_16x16x32_bf16 v[68:71], v[16:19], v[4:7], v[68:71]
	ds_read_b128 v[212:215], v249 offset:8192
	v_mfma_f32_16x16x32_bf16 v[108:111], v[16:19], v[8:11], v[108:111]
	ds_read_b128 v[190:193], v248 offset:1024
	v_mfma_f32_16x16x32_bf16 v[132:135], v[16:19], v[12:15], v[132:135]
	ds_read_b128 v[216:219], v249 offset:9216
	v_mfma_f32_16x16x32_bf16 v[120:123], v[20:23], v[0:3], v[120:123]
	ds_read_b128 v[194:197], v248 offset:2048
	v_mfma_f32_16x16x32_bf16 v[64:67], v[20:23], v[4:7], v[64:67]
	ds_read_b128 v[220:223], v249 offset:10240
	v_mfma_f32_16x16x32_bf16 v[112:115], v[20:23], v[8:11], v[112:115]
	ds_read_b128 v[208:211], v248 offset:3072
	v_mfma_f32_16x16x32_bf16 v[136:139], v[20:23], v[12:15], v[136:139]
	ds_read_b128 v[224:227], v249 offset:11264
	v_mfma_f32_16x16x32_bf16 v[104:107], v[162:165], v[0:3], v[104:107]
	ds_read_b128 v[228:231], v249 offset:12288
	v_mfma_f32_16x16x32_bf16 v[56:59], v[162:165], v[4:7], v[56:59]
	ds_read_b128 v[232:235], v249 offset:13312
	v_mfma_f32_16x16x32_bf16 v[116:119], v[162:165], v[8:11], v[116:119]
	ds_read_b128 v[236:239], v249 offset:14336
	v_mfma_f32_16x16x32_bf16 v[140:143], v[162:165], v[12:15], v[140:143]
	ds_read_b128 v[240:243], v249 offset:15360
	s_add_u32 m0, s25, s24
	v_mfma_f32_16x16x32_bf16 v[100:103], v[166:169], v[0:3], v[100:103]
	global_load_lds_dwordx4 v244, s[26:27]
	v_mfma_f32_16x16x32_bf16 v[52:55], v[166:169], v[4:7], v[52:55]
	v_mfma_f32_16x16x32_bf16 v[124:127], v[166:169], v[8:11], v[124:127]
	s_add_u32 m0, m0, 0x1000
	v_mfma_f32_16x16x32_bf16 v[144:147], v[166:169], v[12:15], v[144:147]
	global_load_lds_dwordx4 v245, s[26:27]
	v_mfma_f32_16x16x32_bf16 v[60:63], v[170:173], v[0:3], v[60:63]
	v_mfma_f32_16x16x32_bf16 v[36:39], v[170:173], v[4:7], v[36:39]
	s_add_u32 m0, m0, 0x1000
	v_mfma_f32_16x16x32_bf16 v[80:83], v[170:173], v[8:11], v[80:83]
	global_load_lds_dwordx4 v156, s[28:29]
	v_mfma_f32_16x16x32_bf16 v[96:99], v[170:173], v[12:15], v[96:99]
	v_mfma_f32_16x16x32_bf16 v[48:51], v[174:177], v[0:3], v[48:51]
	s_add_u32 m0, m0, 0x1000
	v_mfma_f32_16x16x32_bf16 v[32:35], v[174:177], v[4:7], v[32:35]
	global_load_lds_dwordx4 v157, s[28:29]
	v_mfma_f32_16x16x32_bf16 v[88:91], v[174:177], v[8:11], v[88:91]
	v_mfma_f32_16x16x32_bf16 v[84:87], v[174:177], v[12:15], v[84:87]
	s_add_u32 m0, m0, 0x1000
	v_mfma_f32_16x16x32_bf16 v[44:47], v[178:181], v[0:3], v[44:47]
	global_load_lds_dwordx4 v158, s[28:29]
	v_mfma_f32_16x16x32_bf16 v[28:31], v[178:181], v[4:7], v[28:31]
	v_mfma_f32_16x16x32_bf16 v[92:95], v[178:181], v[8:11], v[92:95]
	s_add_u32 m0, m0, 0x1000
	v_mfma_f32_16x16x32_bf16 v[72:75], v[178:181], v[12:15], v[72:75]
	global_load_lds_dwordx4 v159, s[28:29]
	v_mfma_f32_16x16x32_bf16 v[40:43], v[182:185], v[0:3], v[40:43]
	v_mfma_f32_16x16x32_bf16 v[24:27], v[182:185], v[4:7], v[24:27]
	v_mfma_f32_16x16x32_bf16 v[76:79], v[182:185], v[8:11], v[76:79]
	v_mfma_f32_16x16x32_bf16 v[148:151], v[182:185], v[12:15], v[148:151]
	s_add_u32 s26, s26, 0x40
	s_addc_u32 s27, s27, 0
	s_add_u32 s28, s28, 0x34000
	s_addc_u32 s29, s29, 0
	s_add_u32 s25, s25, 24576
	s_cmp_eq_u32 s25, 73728
	s_cselect_b32 s25, 0, s25
	s_add_u32 s30, s30, 24576
	s_cmp_eq_u32 s30, 73728
	s_cselect_b32 s30, 0, s30
	s_waitcnt vmcnt(6)
	s_waitcnt lgkmcnt(0)
	s_barrier
	s_sub_u32 s31, s31, 1
	s_cmp_lg_u32 s31, 0
	s_cbranch_scc1 .Lgm3_loop
	v_add_u32_e32 v248, s30, v155
	v_add_u32_e32 v249, s30, v160
	v_mfma_f32_16x16x32_bf16 v[128:131], v[212:215], v[186:189], v[128:131]
	ds_read_b128 v[0:3], v248
	v_mfma_f32_16x16x32_bf16 v[68:71], v[212:215], v[190:193], v[68:71]
	ds_read_b128 v[16:19], v249 offset:8192
	v_mfma_f32_16x16x32_bf16 v[108:111], v[212:215], v[194:197], v[108:111]
	ds_read_b128 v[4:7], v248 offset:1024
	v_mfma_f32_16x16x32_bf16 v[132:135], v[212:215], v[208:211], v[132:135]
	ds_read_b128 v[20:23], v249 offset:9216
	v_mfma_f32_16x16x32_bf16 v[120:123], v[216:219], v[186:189], v[120:123]
	ds_read_b128 v[8:11], v248 offset:2048
	v_mfma_f32_16x16x32_bf16 v[64:67], v[216:219], v[190:193], v[64:67]
	ds_read_b128 v[162:165], v249 offset:10240
	v_mfma_f32_16x16x32_bf16 v[112:115], v[216:219], v[194:197], v[112:115]
	ds_read_b128 v[12:15], v248 offset:3072
	v_mfma_f32_16x16x32_bf16 v[136:139], v[216:219], v[208:211], v[136:139]
	ds_read_b128 v[166:169], v249 offset:11264
	v_mfma_f32_16x16x32_bf16 v[104:107], v[220:223], v[186:189], v[104:107]
	ds_read_b128 v[170:173], v249 offset:12288
	v_mfma_f32_16x16x32_bf16 v[56:59], v[220:223], v[190:193], v[56:59]
	ds_read_b128 v[174:177], v249 offset:13312
	v_mfma_f32_16x16x32_bf16 v[116:119], v[220:223], v[194:197], v[116:119]
	ds_read_b128 v[178:181], v249 offset:14336
	v_mfma_f32_16x16x32_bf16 v[140:143], v[220:223], v[208:211], v[140:143]
	ds_read_b128 v[182:185], v249 offset:15360
	s_add_u32 m0, s25, s24
	v_mfma_f32_16x16x32_bf16 v[100:103], v[224:227], v[186:189], v[100:103]
	global_load_lds_dwordx4 v244, s[26:27]
	v_mfma_f32_16x16x32_bf16 v[52:55], v[224:227], v[190:193], v[52:55]
	v_mfma_f32_16x16x32_bf16 v[124:127], v[224:227], v[194:197], v[124:127]
	s_add_u32 m0, m0, 0x1000
	v_mfma_f32_16x16x32_bf16 v[144:147], v[224:227], v[208:211], v[144:147]
	global_load_lds_dwordx4 v245, s[26:27]
	v_mfma_f32_16x16x32_bf16 v[60:63], v[228:231], v[186:189], v[60:63]
	v_mfma_f32_16x16x32_bf16 v[36:39], v[228:231], v[190:193], v[36:39]
	s_add_u32 m0, m0, 0x1000
	v_mfma_f32_16x16x32_bf16 v[80:83], v[228:231], v[194:197], v[80:83]
	global_load_lds_dwordx4 v156, s[28:29]
	v_mfma_f32_16x16x32_bf16 v[96:99], v[228:231], v[208:211], v[96:99]
	v_mfma_f32_16x16x32_bf16 v[48:51], v[232:235], v[186:189], v[48:51]
	s_add_u32 m0, m0, 0x1000
	v_mfma_f32_16x16x32_bf16 v[32:35], v[232:235], v[190:193], v[32:35]
	global_load_lds_dwordx4 v157, s[28:29]
	v_mfma_f32_16x16x32_bf16 v[88:91], v[232:235], v[194:197], v[88:91]
	v_mfma_f32_16x16x32_bf16 v[84:87], v[232:235], v[208:211], v[84:87]
	s_add_u32 m0, m0, 0x1000
	v_mfma_f32_16x16x32_bf16 v[44:47], v[236:239], v[186:189], v[44:47]
	global_load_lds_dwordx4 v158, s[28:29]
	v_mfma_f32_16x16x32_bf16 v[28:31], v[236:239], v[190:193], v[28:31]
	v_mfma_f32_16x16x32_bf16 v[92:95], v[236:239], v[194:197], v[92:95]
	s_add_u32 m0, m0, 0x1000
	v_mfma_f32_16x16x32_bf16 v[72:75], v[236:239], v[208:211], v[72:75]
	global_load_lds_dwordx4 v159, s[28:29]
	v_mfma_f32_16x16x32_bf16 v[40:43], v[240:243], v[186:189], v[40:43]
	v_mfma_f32_16x16x32_bf16 v[24:27], v[240:243], v[190:193], v[24:27]
	v_mfma_f32_16x16x32_bf16 v[76:79], v[240:243], v[194:197], v[76:79]
	v_mfma_f32_16x16x32_bf16 v[148:151], v[240:243], v[208:211], v[148:151]
	s_add_u32 s26, s26, 0x40
	s_addc_u32 s27, s27, 0
	s_add_u32 s28, s28, 0x34000
	s_addc_u32 s29, s29, 0
	s_add_u32 s25, s25, 24576
	s_cmp_eq_u32 s25, 73728
	s_cselect_b32 s25, 0, s25
	s_add_u32 s30, s30, 24576
	s_cmp_eq_u32 s30, 73728
	s_cselect_b32 s30, 0, s30
	s_waitcnt vmcnt(6)
	s_waitcnt lgkmcnt(0)
	s_barrier
	v_mfma_f32_16x16x32_bf16 v[128:131], v[16:19], v[0:3], v[128:131]
	v_mfma_f32_16x16x32_bf16 v[68:71], v[16:19], v[4:7], v[68:71]
	v_mfma_f32_16x16x32_bf16 v[108:111], v[16:19], v[8:11], v[108:111]
	v_mfma_f32_16x16x32_bf16 v[132:135], v[16:19], v[12:15], v[132:135]
	v_mfma_f32_16x16x32_bf16 v[120:123], v[20:23], v[0:3], v[120:123]
	v_mfma_f32_16x16x32_bf16 v[64:67], v[20:23], v[4:7], v[64:67]
	v_mfma_f32_16x16x32_bf16 v[112:115], v[20:23], v[8:11], v[112:115]
	v_mfma_f32_16x16x32_bf16 v[136:139], v[20:23], v[12:15], v[136:139]
	v_mfma_f32_16x16x32_bf16 v[104:107], v[162:165], v[0:3], v[104:107]
	v_mfma_f32_16x16x32_bf16 v[56:59], v[162:165], v[4:7], v[56:59]
	v_mfma_f32_16x16x32_bf16 v[116:119], v[162:165], v[8:11], v[116:119]
	v_mfma_f32_16x16x32_bf16 v[140:143], v[162:165], v[12:15], v[140:143]
	v_mfma_f32_16x16x32_bf16 v[100:103], v[166:169], v[0:3], v[100:103]
	v_mfma_f32_16x16x32_bf16 v[52:55], v[166:169], v[4:7], v[52:55]
	v_mfma_f32_16x16x32_bf16 v[124:127], v[166:169], v[8:11], v[124:127]
	v_mfma_f32_16x16x32_bf16 v[144:147], v[166:169], v[12:15], v[144:147]
	v_mfma_f32_16x16x32_bf16 v[60:63], v[170:173], v[0:3], v[60:63]
	v_mfma_f32_16x16x32_bf16 v[36:39], v[170:173], v[4:7], v[36:39]
	v_mfma_f32_16x16x32_bf16 v[80:83], v[170:173], v[8:11], v[80:83]
	v_mfma_f32_16x16x32_bf16 v[96:99], v[170:173], v[12:15], v[96:99]
	v_mfma_f32_16x16x32_bf16 v[48:51], v[174:177], v[0:3], v[48:51]
	v_mfma_f32_16x16x32_bf16 v[32:35], v[174:177], v[4:7], v[32:35]
	v_mfma_f32_16x16x32_bf16 v[88:91], v[174:177], v[8:11], v[88:91]
	v_mfma_f32_16x16x32_bf16 v[84:87], v[174:177], v[12:15], v[84:87]
	v_mfma_f32_16x16x32_bf16 v[44:47], v[178:181], v[0:3], v[44:47]
	v_mfma_f32_16x16x32_bf16 v[28:31], v[178:181], v[4:7], v[28:31]
	v_mfma_f32_16x16x32_bf16 v[92:95], v[178:181], v[8:11], v[92:95]
	v_mfma_f32_16x16x32_bf16 v[72:75], v[178:181], v[12:15], v[72:75]
	v_mfma_f32_16x16x32_bf16 v[40:43], v[182:185], v[0:3], v[40:43]
	v_mfma_f32_16x16x32_bf16 v[24:27], v[182:185], v[4:7], v[24:27]
	v_mfma_f32_16x16x32_bf16 v[76:79], v[182:185], v[8:11], v[76:79]
	v_mfma_f32_16x16x32_bf16 v[148:151], v[182:185], v[12:15], v[148:151]
	s_waitcnt vmcnt(0)
	s_waitcnt lgkmcnt(0)
	s_barrier
	s_branch .Lgm3_tail
.Lgm3_cheap:
	v_add_u32_e32 v248, s30, v155
	v_add_u32_e32 v249, s30, v160
	v_mfma_f32_16x16x32_bf16 v[128:131], v[212:215], v[186:189], v[128:131]
	ds_read_b128 v[0:3], v248
	v_mfma_f32_16x16x32_bf16 v[68:71], v[212:215], v[190:193], v[68:71]
	ds_read_b128 v[16:19], v249 offset:8192
	v_mfma_f32_16x16x32_bf16 v[108:111], v[212:215], v[194:197], v[108:111]
	ds_read_b128 v[4:7], v248 offset:1024
	v_mfma_f32_16x16x32_bf16 v[132:135], v[212:215], v[208:211], v[132:135]
	ds_read_b128 v[20:23], v249 offset:9216
	v_mfma_f32_16x16x32_bf16 v[120:123], v[216:219], v[186:189], v[120:123]
	ds_read_b128 v[8:11], v248 offset:2048
	s_add_u32 m0, s25, s24
	v_mfma_f32_16x16x32_bf16 v[64:67], v[216:219], v[190:193], v[64:67]
	ds_read_b128 v[12:15], v248 offset:3072
	global_load_lds_dwordx4 v244, s[26:27]
	s_add_u32 m0, m0, 0x1000
	v_mfma_f32_16x16x32_bf16 v[112:115], v[216:219], v[194:197], v[112:115]
	global_load_lds_dwordx4 v245, s[26:27]
	s_add_u32 m0, m0, 0x1000
	v_mfma_f32_16x16x32_bf16 v[136:139], v[216:219], v[208:211], v[136:139]
	global_load_lds_dwordx4 v156, s[28:29]
	s_add_u32 s26, s26, 0x40
	s_addc_u32 s27, s27, 0
	s_add_u32 s28, s28, 0x34000
	s_addc_u32 s29, s29, 0
	s_add_u32 s25, s25, 24576
	s_cmp_eq_u32 s25, 73728
	s_cselect_b32 s25, 0, s25
	s_add_u32 s30, s30, 24576
	s_cmp_eq_u32 s30, 73728
	s_cselect_b32 s30, 0, s30
	s_waitcnt vmcnt(3)
	s_waitcnt lgkmcnt(0)
	s_barrier
	v_add_u32_e32 v248, s30, v155
	v_add_u32_e32 v249, s30, v160
	v_mfma_f32_16x16x32_bf16 v[128:131], v[16:19], v[0:3], v[128:131]
	ds_read_b128 v[186:189], v248
	v_mfma_f32_16x16x32_bf16 v[68:71], v[16:19], v[4:7], v[68:71]
	ds_read_b128 v[212:215], v249 offset:8192
	v_mfma_f32_16x16x32_bf16 v[108:111], v[16:19], v[8:11], v[108:111]
	ds_read_b128 v[190:193], v248 offset:1024
	v_mfma_f32_16x16x32_bf16 v[132:135], v[16:19], v[12:15], v[132:135]
	ds_read_b128 v[216:219], v249 offset:9216
	v_mfma_f32_16x16x32_bf16 v[120:123], v[20:23], v[0:3], v[120:123]
	ds_read_b128 v[194:197], v248 offset:2048
	s_add_u32 m0, s25, s24
	v_mfma_f32_16x16x32_bf16 v[64:67], v[20:23], v[4:7], v[64:67]
	ds_read_b128 v[208:211], v248 offset:3072
	global_load_lds_dwordx4 v244, s[26:27]
	s_add_u32 m0, m0, 0x1000
	v_mfma_f32_16x16x32_bf16 v[112:115], v[20:23], v[8:11], v[112:115]
	global_load_lds_dwordx4 v245, s[26:27]
	s_add_u32 m0, m0, 0x1000
	v_mfma_f32_16x16x32_bf16 v[136:139], v[20:23], v[12:15], v[136:139]
	global_load_lds_dwordx4 v156, s[28:29]
	s_add_u32 s26, s26, 0x40
	s_addc_u32 s27, s27, 0
	s_add_u32 s28, s28, 0x34000
	s_addc_u32 s29, s29, 0
	s_add_u32 s25, s25, 24576
	s_cmp_eq_u32 s25, 73728
	s_cselect_b32 s25, 0, s25
	s_add_u32 s30, s30, 24576
	s_cmp_eq_u32 s30, 73728
	s_cselect_b32 s30, 0, s30
	s_waitcnt vmcnt(3)
	s_waitcnt lgkmcnt(0)
	s_barrier
	s_sub_u32 s31, s31, 1
	s_cmp_lg_u32 s31, 0
	s_cbranch_scc1 .Lgm3_cheap
	v_add_u32_e32 v248, s30, v155
	v_add_u32_e32 v249, s30, v160
	v_mfma_f32_16x16x32_bf16 v[128:131], v[212:215], v[186:189], v[128:131]
	ds_read_b128 v[0:3], v248
	v_mfma_f32_16x16x32_bf16 v[68:71], v[212:215], v[190:193], v[68:71]
	ds_read_b128 v[16:19], v249 offset:8192
	v_mfma_f32_16x16x32_bf16 v[108:111], v[212:215], v[194:197], v[108:111]
	ds_read_b128 v[4:7], v248 offset:1024
	v_mfma_f32_16x16x32_bf16 v[132:135], v[212:215], v[208:211], v[132:135]
	ds_read_b128 v[20:23], v249 offset:9216
	v_mfma_f32_16x16x32_bf16 v[120:123], v[216:219], v[186:189], v[120:123]
	ds_read_b128 v[8:11], v248 offset:2048
	s_add_u32 m0, s25, s24
	v_mfma_f32_16x16x32_bf16 v[64:67], v[216:219], v[190:193], v[64:67]
	ds_read_b128 v[12:15], v248 offset:3072
	global_load_lds_dwordx4 v244, s[26:27]
	s_add_u32 m0, m0, 0x1000
	v_mfma_f32_16x16x32_bf16 v[112:115], v[216:219], v[194:197], v[112:115]
	global_load_lds_dwordx4 v245, s[26:27]
	s_add_u32 m0, m0, 0x1000
	v_mfma_f32_16x16x32_bf16 v[136:139], v[216:219], v[208:211], v[136:139]
	global_load_lds_dwordx4 v156, s[28:29]
	s_add_u32 s26, s26, 0x40
	s_addc_u32 s27, s27, 0
	s_add_u32 s28, s28, 0x34000
	s_addc_u32 s29, s29, 0
	s_add_u32 s25, s25, 24576
	s_cmp_eq_u32 s25, 73728
	s_cselect_b32 s25, 0, s25
	s_add_u32 s30, s30, 24576
	s_cmp_eq_u32 s30, 73728
	s_cselect_b32 s30, 0, s30
	s_waitcnt vmcnt(3)
	s_waitcnt lgkmcnt(0)
	s_barrier
	v_mfma_f32_16x16x32_bf16 v[128:131], v[16:19], v[0:3], v[128:131]
	v_mfma_f32_16x16x32_bf16 v[68:71], v[16:19], v[4:7], v[68:71]
	v_mfma_f32_16x16x32_bf16 v[108:111], v[16:19], v[8:11], v[108:111]
	v_mfma_f32_16x16x32_bf16 v[132:135], v[16:19], v[12:15], v[132:135]
	v_mfma_f32_16x16x32_bf16 v[120:123], v[20:23], v[0:3], v[120:123]
	v_mfma_f32_16x16x32_bf16 v[64:67], v[20:23], v[4:7], v[64:67]
	v_mfma_f32_16x16x32_bf16 v[112:115], v[20:23], v[8:11], v[112:115]
	v_mfma_f32_16x16x32_bf16 v[136:139], v[20:23], v[12:15], v[136:139]
	s_waitcnt vmcnt(0)
	s_waitcnt lgkmcnt(0)
	s_barrier
